# code placement: every 32-MFMA run of the K-loops starts 8-byte aligned (s_nop padding ahead of the load segment's closing wait)
# speedup vs baseline: 1.0109x; 1.0036x over previous
; #define PG8_STAGE(bufoff, gbase, voff) do { _Pragma("unroll") for (int _i = 0; _i < 2; ++_i) \
;         __builtin_amdgcn_global_load_lds((const unsigned*)((const char*)(gbase) + (voff)[_i]), (LAS unsigned*)(lds + (bufoff) + ldsw + _i * 8192), 16, 0, 0); } while (0)
; #define PG8_LDA(dst, b, h) do { _Pragma("unroll") for (int m = 0; m < 4; ++m) _Pragma("unroll") for (int k = 0; k < 2; ++k) dst[m][k] = *(const LAS bf16x8*)(lds + PG8_SA(b, h) + aoff + m * 2048 + k * 1024); } while (0)
; #define PG8_LDB(dst, b, h) do { _Pragma("unroll") for (int n = 0; n < 2; ++n) _Pragma("unroll") for (int k = 0; k < 2; ++k) dst[n][k] = *(const LAS bf16x8*)(lds + PG8_SB(b, h) + boff + n * 2048 + k * 1024); } while (0)
; #define PG8_WAIT_V(n) asm volatile("s_waitcnt vmcnt(" #n ")" ::: "memory")
; #define PG8_WAIT_L(n) asm volatile("s_waitcnt lgkmcnt(" #n ")" ::: "memory")
; #define PG8_BAR __builtin_amdgcn_s_barrier()
; #define PG8_SCHED __builtin_amdgcn_sched_barrier(0)
; template <class Epi>
; __device__ __forceinline__ void gemm_phase(LAS unsigned char* lds, const Gemm g, const StaticOrder& S, const Epi& E, const int tid) {
;     ...
;         for (int t = 0; t < ntt; t += 2) {
;             const bool last = (t == ntt - 2);
;             const bool s1 = Epi::TWO && (t >= nt), s2 = Epi::TWO && (t + 2 >= nt);
;             const char* a1 = (s1 ? cA2 + (size_t)(t - nt + 1) * kstep : cA + (size_t)(t + 1) * kstep);
;             const char* a2 = last ? nA : (s2 ? cA2 + (size_t)(t + 2 - nt) * kstep : cA + (size_t)(t + 2) * kstep);
;             const char* b2 = last ? nB : (s2 ? cB2 + (size_t)(t + 2 - nt) * kstep : cB + (size_t)(t + 2) * kstep);
;             const char* a3 = a2 + kstep; const char* b3 = b2 + kstep;
;             if constexpr (Epi::TWO) { if (t == nt) E.mid(acc, cur, wr, wc, fr, fq); }
;             if constexpr (SP2) {
;             PG8_LDB(B0, 0, 0); PG8_LDB(B1, 0, 1); PG8_SCHED; PG8_LDA(At, 0, 0); PG8_STAGE(PG8_SA(1, 1), a1 + hstep, voffA);
;             PG8_WAIT_V(8); PG8_WAIT_L(0); PG8_BAR; PG8_MMA(0, 0, At, B0); PG8_MMA(0, 1, At, B1); PG8_BAR; PG8_SCHED;
;             PG8_LDA(At, 0, 1); PG8_STAGE(PG8_SB(0, 0), b2, voffB); PG8_STAGE(PG8_SB(0, 1), b2 + bhs, voffB); PG8_STAGE(PG8_SA(0, 0), a2, voffA);
;             PG8_WAIT_V(8); PG8_WAIT_L(0); PG8_BAR; PG8_MMA(1, 0, At, B0); PG8_MMA(1, 1, At, B1); PG8_BAR; PG8_SCHED;
.LBB0_126:
	s_add_u32 s30, s28, 0xffe00080
	s_addc_u32 s31, s29, -1
	s_add_i32 s52, 0, 0x10000
	s_cmpk_eq_i32 s51, 0x7c
	s_cselect_b32 s35, s17, s31
	s_cselect_b32 s34, s27, s30
	s_cselect_b32 s31, s15, s50
	s_cselect_b32 s30, s33, s49
	s_add_i32 s54, 0, 0x14000
	v_add_u32_e32 v30, s52, v193
	v_add_u32_e32 v54, s54, v193
	ds_read_b128 v[18:21], v30
	ds_read_b128 v[22:25], v30 offset:1024
	ds_read_b128 v[26:29], v30 offset:2048
	ds_read_b128 v[30:33], v30 offset:3072
	ds_read_b128 v[42:45], v54
	ds_read_b128 v[46:49], v54 offset:1024
	ds_read_b128 v[50:53], v54 offset:2048
	ds_read_b128 v[54:57], v54 offset:3072
	v_lshl_add_u64 v[172:173], s[28:29], 0, v[180:181]
	s_add_i32 m0, s37, 0xc000
	ds_read_b128 v[182:185], v199
	global_load_lds_dwordx4 v[172:173], off
	ds_read_b128 v[186:189], v199 offset:1024
	ds_read_b128 v[212:215], v199 offset:2048
	v_lshl_add_u64 v[172:173], s[28:29], 0, v[178:179]
	s_add_i32 m0, s37, 0xe000
	s_nop 0
	global_load_lds_dwordx4 v[172:173], off
	ds_read_b128 v[216:219], v199 offset:3072
	ds_read_b128 v[220:223], v199 offset:4096
	ds_read_b128 v[224:227], v199 offset:5120
	ds_read_b128 v[228:231], v199 offset:6144
	ds_read_b128 v[232:235], v199 offset:7168
	s_nop 0
	s_waitcnt vmcnt(8)
	s_waitcnt lgkmcnt(0)
	s_barrier
	s_setprio 1
	s_waitcnt lgkmcnt(0)
	v_mfma_f32_16x16x32_bf16 v[158:161], v[18:21], v[182:185], v[158:161]
	v_mfma_f32_16x16x32_bf16 v[154:157], v[26:29], v[182:185], v[154:157]
	v_mfma_f32_16x16x32_bf16 v[142:145], v[18:21], v[212:215], v[142:145]
	v_mfma_f32_16x16x32_bf16 v[138:141], v[26:29], v[212:215], v[138:141]
	v_mfma_f32_16x16x32_bf16 v[126:129], v[18:21], v[220:223], v[126:129]
	v_mfma_f32_16x16x32_bf16 v[122:125], v[26:29], v[220:223], v[122:125]
	v_mfma_f32_16x16x32_bf16 v[110:113], v[18:21], v[228:231], v[110:113]
	v_mfma_f32_16x16x32_bf16 v[106:109], v[26:29], v[228:231], v[106:109]
	v_mfma_f32_16x16x32_bf16 v[158:161], v[22:25], v[186:189], v[158:161]
	v_mfma_f32_16x16x32_bf16 v[154:157], v[30:33], v[186:189], v[154:157]
	v_mfma_f32_16x16x32_bf16 v[142:145], v[22:25], v[216:219], v[142:145]
	v_mfma_f32_16x16x32_bf16 v[138:141], v[30:33], v[216:219], v[138:141]
	v_mfma_f32_16x16x32_bf16 v[126:129], v[22:25], v[224:227], v[126:129]
	v_mfma_f32_16x16x32_bf16 v[122:125], v[30:33], v[224:227], v[122:125]
	v_mfma_f32_16x16x32_bf16 v[110:113], v[22:25], v[232:235], v[110:113]
	v_mfma_f32_16x16x32_bf16 v[106:109], v[30:33], v[232:235], v[106:109]
	s_setprio 0
	s_setprio 1
	v_mfma_f32_16x16x32_bf16 v[150:153], v[42:45], v[182:185], v[150:153]
	v_mfma_f32_16x16x32_bf16 v[146:149], v[50:53], v[182:185], v[146:149]
	v_mfma_f32_16x16x32_bf16 v[134:137], v[42:45], v[212:215], v[134:137]
	v_mfma_f32_16x16x32_bf16 v[130:133], v[50:53], v[212:215], v[130:133]
	v_mfma_f32_16x16x32_bf16 v[118:121], v[42:45], v[220:223], v[118:121]
	v_mfma_f32_16x16x32_bf16 v[114:117], v[50:53], v[220:223], v[114:117]
	v_mfma_f32_16x16x32_bf16 v[102:105], v[42:45], v[228:231], v[102:105]
	v_mfma_f32_16x16x32_bf16 v[98:101], v[50:53], v[228:231], v[98:101]
	v_mfma_f32_16x16x32_bf16 v[150:153], v[46:49], v[186:189], v[150:153]
	v_mfma_f32_16x16x32_bf16 v[146:149], v[54:57], v[186:189], v[146:149]
	v_mfma_f32_16x16x32_bf16 v[134:137], v[46:49], v[216:219], v[134:137]
	v_mfma_f32_16x16x32_bf16 v[130:133], v[54:57], v[216:219], v[130:133]
	v_mfma_f32_16x16x32_bf16 v[118:121], v[46:49], v[224:227], v[118:121]
	v_mfma_f32_16x16x32_bf16 v[114:117], v[54:57], v[224:227], v[114:117]
	v_mfma_f32_16x16x32_bf16 v[102:105], v[46:49], v[232:235], v[102:105]
	v_mfma_f32_16x16x32_bf16 v[98:101], v[54:57], v[232:235], v[98:101]
	s_setprio 0
	s_barrier
	s_add_i32 s52, s52, s36
	v_lshl_add_u64 v[172:173], s[30:31], 0, v[0:1]
	s_mov_b32 m0, s52
	ds_read_b128 v[182:185], v199 offset:16384
	global_load_lds_dwordx4 v[172:173], off
	ds_read_b128 v[186:189], v199 offset:17408
	ds_read_b128 v[212:215], v199 offset:18432
	s_add_i32 m0, s52, 0x2000
	s_add_u32 s52, s30, 0x20000
	v_lshl_add_u64 v[174:175], s[30:31], 0, v[166:167]
	s_addc_u32 s53, s31, 0
	s_add_i32 s54, s54, s36
	global_load_lds_dwordx4 v[174:175], off
	ds_read_b128 v[216:219], v199 offset:19456
	ds_read_b128 v[220:223], v199 offset:20480
	v_lshl_add_u64 v[176:177], s[52:53], 0, v[0:1]
	s_mov_b32 m0, s54
	v_lshl_add_u64 v[200:201], s[34:35], 0, v[164:165]
	global_load_lds_dwordx4 v[176:177], off
	ds_read_b128 v[224:227], v199 offset:21504
	ds_read_b128 v[228:231], v199 offset:22528
	v_lshl_add_u64 v[176:177], s[52:53], 0, v[166:167]
	s_add_i32 m0, s54, 0x2000
	s_nop 0
	global_load_lds_dwordx4 v[176:177], off
	ds_read_b128 v[232:235], v199 offset:23552
	v_lshl_add_u64 v[176:177], s[34:35], 0, v[162:163]
	s_mov_b32 m0, s37
	s_nop 0
	global_load_lds_dwordx4 v[176:177], off
	s_mov_b32 m0, s38
	s_nop 0
	global_load_lds_dwordx4 v[200:201], off
	s_nop 0
	s_waitcnt vmcnt(8)
	s_waitcnt lgkmcnt(0)
	s_barrier
; #define PG8_STAGE(bufoff, gbase, voff) do { _Pragma("unroll") for (int _i = 0; _i < 2; ++_i) \
;         __builtin_amdgcn_global_load_lds((const unsigned*)((const char*)(gbase) + (voff)[_i]), (LAS unsigned*)(lds + (bufoff) + ldsw + _i * 8192), 16, 0, 0); } while (0)
; #define PG8_LDA(dst, b, h) do { _Pragma("unroll") for (int m = 0; m < 4; ++m) _Pragma("unroll") for (int k = 0; k < 2; ++k) dst[m][k] = *(const LAS bf16x8*)(lds + PG8_SA(b, h) + aoff + m * 2048 + k * 1024); } while (0)
; #define PG8_LDB(dst, b, h) do { _Pragma("unroll") for (int n = 0; n < 2; ++n) _Pragma("unroll") for (int k = 0; k < 2; ++k) dst[n][k] = *(const LAS bf16x8*)(lds + PG8_SB(b, h) + boff + n * 2048 + k * 1024); } while (0)
; #define PG8_MMA(ai, bj, At, Bt) do { __builtin_amdgcn_s_setprio(1); _Pragma("unroll") for (int m = 0; m < 4; ++m) _Pragma("unroll") for (int n = 0; n < 2; ++n) _Pragma("unroll") for (int k = 0; k < 2; ++k) \
;         acc[ai][bj][m][n] = __builtin_amdgcn_mfma_f32_16x16x32_bf16(Bt[n][k], At[m][k], acc[ai][bj][m][n], 0, 0, 0); __builtin_amdgcn_s_setprio(0); } while (0)
; #define PG8_WAIT_V(n) asm volatile("s_waitcnt vmcnt(" #n ")" ::: "memory")
; #define PG8_WAIT_L(n) asm volatile("s_waitcnt lgkmcnt(" #n ")" ::: "memory")
; #define PG8_BAR __builtin_amdgcn_s_barrier()
; #define PG8_SCHED __builtin_amdgcn_sched_barrier(0)
; template <class Epi>
; __device__ __forceinline__ void gemm_phase(LAS unsigned char* lds, const Gemm g, const StaticOrder& S, const Epi& E, const int tid) {
;     ...
;             PG8_LDA(At, 0, 1); PG8_STAGE(PG8_SB(0, 0), b2, voffB); PG8_STAGE(PG8_SB(0, 1), b2 + bhs, voffB); PG8_STAGE(PG8_SA(0, 0), a2, voffA);
;             PG8_WAIT_V(8); PG8_WAIT_L(0); PG8_BAR; PG8_MMA(1, 0, At, B0); PG8_MMA(1, 1, At, B1); PG8_BAR; PG8_SCHED;
;             PG8_LDB(B0, 1, 0); PG8_LDB(B1, 1, 1); PG8_SCHED; PG8_LDA(At, 1, 0); PG8_STAGE(PG8_SA(0, 1), a2 + hstep, voffA);
;             PG8_WAIT_V(8); PG8_WAIT_L(0); PG8_BAR; PG8_MMA(0, 0, At, B0); PG8_MMA(0, 1, At, B1); PG8_BAR; PG8_SCHED;
	s_setprio 1
	s_waitcnt lgkmcnt(0)
	v_mfma_f32_16x16x32_bf16 v[94:97], v[18:21], v[182:185], v[94:97]
	v_mfma_f32_16x16x32_bf16 v[90:93], v[26:29], v[182:185], v[90:93]
	v_mfma_f32_16x16x32_bf16 v[78:81], v[18:21], v[212:215], v[78:81]
	v_mfma_f32_16x16x32_bf16 v[74:77], v[26:29], v[212:215], v[74:77]
	v_mfma_f32_16x16x32_bf16 v[62:65], v[18:21], v[220:223], v[62:65]
	v_mfma_f32_16x16x32_bf16 v[58:61], v[26:29], v[220:223], v[58:61]
	v_mfma_f32_16x16x32_bf16 v[14:17], v[18:21], v[228:231], v[14:17]
	v_mfma_f32_16x16x32_bf16 v[10:13], v[26:29], v[228:231], v[10:13]
	v_mfma_f32_16x16x32_bf16 v[94:97], v[22:25], v[186:189], v[94:97]
	v_mfma_f32_16x16x32_bf16 v[90:93], v[30:33], v[186:189], v[90:93]
	v_mfma_f32_16x16x32_bf16 v[78:81], v[22:25], v[216:219], v[78:81]
	v_mfma_f32_16x16x32_bf16 v[74:77], v[30:33], v[216:219], v[74:77]
	v_mfma_f32_16x16x32_bf16 v[62:65], v[22:25], v[224:227], v[62:65]
	v_mfma_f32_16x16x32_bf16 v[58:61], v[30:33], v[224:227], v[58:61]
	v_mfma_f32_16x16x32_bf16 v[14:17], v[22:25], v[232:235], v[14:17]
	v_mfma_f32_16x16x32_bf16 v[10:13], v[30:33], v[232:235], v[10:13]
	s_setprio 0
	s_setprio 1
	v_mfma_f32_16x16x32_bf16 v[38:41], v[42:45], v[220:223], v[38:41]
	v_mfma_f32_16x16x32_bf16 v[34:37], v[50:53], v[220:223], v[34:37]
	v_mfma_f32_16x16x32_bf16 v[6:9], v[42:45], v[228:231], v[6:9]
	v_mfma_f32_16x16x32_bf16 v[2:5], v[50:53], v[228:231], v[2:5]
	v_mfma_f32_16x16x32_bf16 v[18:21], v[42:45], v[182:185], v[86:89]
	v_mfma_f32_16x16x32_bf16 v[22:25], v[50:53], v[182:185], v[82:85]
	v_mfma_f32_16x16x32_bf16 v[26:29], v[42:45], v[212:215], v[70:73]
	v_mfma_f32_16x16x32_bf16 v[30:33], v[50:53], v[212:215], v[66:69]
	v_mfma_f32_16x16x32_bf16 v[38:41], v[46:49], v[224:227], v[38:41]
	v_mfma_f32_16x16x32_bf16 v[34:37], v[54:57], v[224:227], v[34:37]
	v_mfma_f32_16x16x32_bf16 v[6:9], v[46:49], v[232:235], v[6:9]
	v_mfma_f32_16x16x32_bf16 v[2:5], v[54:57], v[232:235], v[2:5]
	v_mfma_f32_16x16x32_bf16 v[18:21], v[46:49], v[186:189], v[18:21]
	v_mfma_f32_16x16x32_bf16 v[22:25], v[54:57], v[186:189], v[22:25]
	v_mfma_f32_16x16x32_bf16 v[26:29], v[46:49], v[216:219], v[26:29]
	v_mfma_f32_16x16x32_bf16 v[30:33], v[54:57], v[216:219], v[30:33]
	s_setprio 0
	s_barrier
	s_add_i32 s52, 0, 0x18000
	s_add_i32 s53, 0, 0x1c000
	v_add_u32_e32 v54, s52, v193
	v_add_u32_e32 v66, s53, v193
	ds_read_b128 v[42:45], v54
	ds_read_b128 v[46:49], v54 offset:1024
	ds_read_b128 v[50:53], v54 offset:2048
	ds_read_b128 v[54:57], v54 offset:3072
	ds_read_b128 v[182:185], v66
	ds_read_b128 v[186:189], v66 offset:1024
	ds_read_b128 v[212:215], v66 offset:2048
	ds_read_b128 v[216:219], v66 offset:3072
	s_add_u32 s34, s34, 0x200000
	s_addc_u32 s35, s35, 0
	s_mov_b32 m0, s39
	v_lshl_add_u64 v[236:237], s[34:35], 0, v[162:163]
	ds_read_b128 v[66:69], v199 offset:32768
	global_load_lds_dwordx4 v[236:237], off
	ds_read_b128 v[70:73], v199 offset:33792
	ds_read_b128 v[82:85], v199 offset:34816
	v_lshl_add_u64 v[236:237], s[34:35], 0, v[164:165]
	s_mov_b32 m0, s44
	s_nop 0
	global_load_lds_dwordx4 v[236:237], off
	ds_read_b128 v[86:89], v199 offset:35840
	ds_read_b128 v[220:223], v199 offset:36864
	ds_read_b128 v[224:227], v199 offset:37888
	ds_read_b128 v[228:231], v199 offset:38912
	ds_read_b128 v[232:235], v199 offset:39936
	s_nop 0
	s_waitcnt vmcnt(8)
	s_waitcnt lgkmcnt(0)
	s_barrier
	s_setprio 1
	s_waitcnt lgkmcnt(0)
	v_mfma_f32_16x16x32_bf16 v[158:161], v[42:45], v[66:69], v[158:161]
	v_mfma_f32_16x16x32_bf16 v[154:157], v[50:53], v[66:69], v[154:157]
	v_mfma_f32_16x16x32_bf16 v[142:145], v[42:45], v[82:85], v[142:145]
	v_mfma_f32_16x16x32_bf16 v[138:141], v[50:53], v[82:85], v[138:141]
	v_mfma_f32_16x16x32_bf16 v[126:129], v[42:45], v[220:223], v[126:129]
	v_mfma_f32_16x16x32_bf16 v[122:125], v[50:53], v[220:223], v[122:125]
	v_mfma_f32_16x16x32_bf16 v[110:113], v[42:45], v[228:231], v[110:113]
	v_mfma_f32_16x16x32_bf16 v[106:109], v[50:53], v[228:231], v[106:109]
	v_mfma_f32_16x16x32_bf16 v[158:161], v[46:49], v[70:73], v[158:161]
	v_mfma_f32_16x16x32_bf16 v[154:157], v[54:57], v[70:73], v[154:157]
	v_mfma_f32_16x16x32_bf16 v[142:145], v[46:49], v[86:89], v[142:145]
	v_mfma_f32_16x16x32_bf16 v[138:141], v[54:57], v[86:89], v[138:141]
	v_mfma_f32_16x16x32_bf16 v[126:129], v[46:49], v[224:227], v[126:129]
	v_mfma_f32_16x16x32_bf16 v[122:125], v[54:57], v[224:227], v[122:125]
	v_mfma_f32_16x16x32_bf16 v[110:113], v[46:49], v[232:235], v[110:113]
	v_mfma_f32_16x16x32_bf16 v[106:109], v[54:57], v[232:235], v[106:109]
	s_setprio 0
	s_setprio 1
	v_mfma_f32_16x16x32_bf16 v[150:153], v[182:185], v[66:69], v[150:153]
	v_mfma_f32_16x16x32_bf16 v[66:69], v[212:215], v[66:69], v[146:149]
	v_mfma_f32_16x16x32_bf16 v[146:149], v[216:219], v[70:73], v[66:69]
	v_mfma_f32_16x16x32_bf16 v[66:69], v[182:185], v[82:85], v[134:137]
	v_mfma_f32_16x16x32_bf16 v[134:137], v[186:189], v[86:89], v[66:69]
	v_mfma_f32_16x16x32_bf16 v[66:69], v[212:215], v[82:85], v[130:133]
	v_mfma_f32_16x16x32_bf16 v[130:133], v[216:219], v[86:89], v[66:69]
	v_mfma_f32_16x16x32_bf16 v[66:69], v[182:185], v[220:223], v[118:121]
	v_mfma_f32_16x16x32_bf16 v[118:121], v[186:189], v[224:227], v[66:69]
	v_mfma_f32_16x16x32_bf16 v[66:69], v[212:215], v[220:223], v[114:117]
	v_mfma_f32_16x16x32_bf16 v[114:117], v[216:219], v[224:227], v[66:69]
	v_mfma_f32_16x16x32_bf16 v[66:69], v[182:185], v[228:231], v[102:105]
	v_mfma_f32_16x16x32_bf16 v[102:105], v[186:189], v[232:235], v[66:69]
	v_mfma_f32_16x16x32_bf16 v[66:69], v[212:215], v[228:231], v[98:101]
	v_mfma_f32_16x16x32_bf16 v[150:153], v[186:189], v[70:73], v[150:153]
	v_mfma_f32_16x16x32_bf16 v[98:101], v[216:219], v[232:235], v[66:69]
	s_setprio 0
	s_barrier
; #define PG8_STAGE(bufoff, gbase, voff) do { _Pragma("unroll") for (int _i = 0; _i < 2; ++_i) \
;         __builtin_amdgcn_global_load_lds((const unsigned*)((const char*)(gbase) + (voff)[_i]), (LAS unsigned*)(lds + (bufoff) + ldsw + _i * 8192), 16, 0, 0); } while (0)
; #define PG8_LDA(dst, b, h) do { _Pragma("unroll") for (int m = 0; m < 4; ++m) _Pragma("unroll") for (int k = 0; k < 2; ++k) dst[m][k] = *(const LAS bf16x8*)(lds + PG8_SA(b, h) + aoff + m * 2048 + k * 1024); } while (0)
; #define PG8_MMA(ai, bj, At, Bt) do { __builtin_amdgcn_s_setprio(1); _Pragma("unroll") for (int m = 0; m < 4; ++m) _Pragma("unroll") for (int n = 0; n < 2; ++n) _Pragma("unroll") for (int k = 0; k < 2; ++k) \
;         acc[ai][bj][m][n] = __builtin_amdgcn_mfma_f32_16x16x32_bf16(Bt[n][k], At[m][k], acc[ai][bj][m][n], 0, 0, 0); __builtin_amdgcn_s_setprio(0); } while (0)
; #define PG8_WAIT_V(n) asm volatile("s_waitcnt vmcnt(" #n ")" ::: "memory")
; #define PG8_WAIT_L(n) asm volatile("s_waitcnt lgkmcnt(" #n ")" ::: "memory")
; #define PG8_BAR __builtin_amdgcn_s_barrier()
; #define PG8_SCHED __builtin_amdgcn_sched_barrier(0)
; template <class Epi>
; __device__ __forceinline__ void gemm_phase(LAS unsigned char* lds, const Gemm g, const StaticOrder& S, const Epi& E, const int tid) {
;     ...
;             PG8_WAIT_V(8); PG8_WAIT_L(0); PG8_BAR; PG8_MMA(0, 0, At, B0); PG8_MMA(0, 1, At, B1); PG8_BAR; PG8_SCHED;
;             PG8_LDA(At, 1, 1); PG8_STAGE(PG8_SB(1, 0), b3, voffB); PG8_STAGE(PG8_SB(1, 1), b3 + bhs, voffB); PG8_STAGE(PG8_SA(1, 0), a3, voffA);
;             PG8_WAIT_V(8); PG8_WAIT_L(0); PG8_BAR; PG8_MMA(1, 0, At, B0); PG8_MMA(1, 1, At, B1); PG8_BAR; PG8_SCHED;
	s_add_i32 s34, s52, s36
	v_lshl_add_u64 v[82:83], v[172:173], 0, s[70:71]
	s_mov_b32 m0, s34
	s_nop 0
	ds_read_b128 v[66:69], v199 offset:49152
	global_load_lds_dwordx4 v[82:83], off
	ds_read_b128 v[70:73], v199 offset:50176
	ds_read_b128 v[220:223], v199 offset:51200
	s_add_i32 m0, s34, 0x2000
	s_add_u32 s30, s30, 0x20080
	v_lshl_add_u64 v[82:83], v[174:175], 0, s[70:71]
	s_addc_u32 s31, s31, 0
	s_add_i32 s34, s53, s36
	global_load_lds_dwordx4 v[82:83], off
	ds_read_b128 v[224:227], v199 offset:52224
	ds_read_b128 v[228:231], v199 offset:53248
	v_lshl_add_u64 v[82:83], s[30:31], 0, v[0:1]
	s_mov_b32 m0, s34
	s_nop 0
	global_load_lds_dwordx4 v[82:83], off
	ds_read_b128 v[232:235], v199 offset:54272
	ds_read_b128 v[236:239], v199 offset:55296
	v_lshl_add_u64 v[82:83], s[30:31], 0, v[166:167]
	s_add_i32 m0, s34, 0x2000
	s_nop 0
	global_load_lds_dwordx4 v[82:83], off
	ds_read_b128 v[240:243], v199 offset:56320
	v_lshl_add_u64 v[82:83], v[176:177], 0, s[70:71]
	s_mov_b32 m0, s45
	s_nop 0
	global_load_lds_dwordx4 v[82:83], off
	v_lshl_add_u64 v[82:83], v[200:201], 0, s[70:71]
	s_mov_b32 m0, s46
	s_nop 0
	global_load_lds_dwordx4 v[82:83], off
	s_nop 0
	s_waitcnt vmcnt(8)
	s_waitcnt lgkmcnt(0)
	s_barrier
	s_setprio 1
	s_waitcnt lgkmcnt(0)
	v_mfma_f32_16x16x32_bf16 v[82:85], v[42:45], v[66:69], v[94:97]
	v_mfma_f32_16x16x32_bf16 v[94:97], v[46:49], v[70:73], v[82:85]
	v_mfma_f32_16x16x32_bf16 v[82:85], v[50:53], v[66:69], v[90:93]
	v_mfma_f32_16x16x32_bf16 v[78:81], v[42:45], v[220:223], v[78:81]
	v_mfma_f32_16x16x32_bf16 v[74:77], v[50:53], v[220:223], v[74:77]
	v_mfma_f32_16x16x32_bf16 v[62:65], v[42:45], v[228:231], v[62:65]
	v_mfma_f32_16x16x32_bf16 v[58:61], v[50:53], v[228:231], v[58:61]
	v_mfma_f32_16x16x32_bf16 v[14:17], v[42:45], v[236:239], v[14:17]
	v_mfma_f32_16x16x32_bf16 v[10:13], v[50:53], v[236:239], v[10:13]
	v_mfma_f32_16x16x32_bf16 v[90:93], v[54:57], v[70:73], v[82:85]
	v_mfma_f32_16x16x32_bf16 v[78:81], v[46:49], v[224:227], v[78:81]
	v_mfma_f32_16x16x32_bf16 v[74:77], v[54:57], v[224:227], v[74:77]
	v_mfma_f32_16x16x32_bf16 v[62:65], v[46:49], v[232:235], v[62:65]
	v_mfma_f32_16x16x32_bf16 v[58:61], v[54:57], v[232:235], v[58:61]
	v_mfma_f32_16x16x32_bf16 v[14:17], v[46:49], v[240:243], v[14:17]
	v_mfma_f32_16x16x32_bf16 v[10:13], v[54:57], v[240:243], v[10:13]
	s_setprio 0
	s_setprio 1
	v_mfma_f32_16x16x32_bf16 v[18:21], v[182:185], v[66:69], v[18:21]
	v_mfma_f32_16x16x32_bf16 v[86:89], v[186:189], v[70:73], v[18:21]
	v_mfma_f32_16x16x32_bf16 v[18:21], v[212:215], v[66:69], v[22:25]
	v_mfma_f32_16x16x32_bf16 v[82:85], v[216:219], v[70:73], v[18:21]
	v_mfma_f32_16x16x32_bf16 v[18:21], v[182:185], v[220:223], v[26:29]
	v_mfma_f32_16x16x32_bf16 v[70:73], v[186:189], v[224:227], v[18:21]
	v_mfma_f32_16x16x32_bf16 v[18:21], v[212:215], v[220:223], v[30:33]
	v_mfma_f32_16x16x32_bf16 v[66:69], v[216:219], v[224:227], v[18:21]
	v_mfma_f32_16x16x32_bf16 v[18:21], v[182:185], v[228:231], v[38:41]
	v_mfma_f32_16x16x32_bf16 v[38:41], v[186:189], v[232:235], v[18:21]
	v_mfma_f32_16x16x32_bf16 v[18:21], v[212:215], v[228:231], v[34:37]
	v_mfma_f32_16x16x32_bf16 v[6:9], v[182:185], v[236:239], v[6:9]
	v_mfma_f32_16x16x32_bf16 v[2:5], v[212:215], v[236:239], v[2:5]
	v_mfma_f32_16x16x32_bf16 v[34:37], v[216:219], v[232:235], v[18:21]
	v_mfma_f32_16x16x32_bf16 v[6:9], v[186:189], v[240:243], v[6:9]
	v_mfma_f32_16x16x32_bf16 v[2:5], v[216:219], v[240:243], v[2:5]
	s_setprio 0
	s_barrier
	s_add_i32 s51, s51, 2
	s_add_u32 s49, s49, 0x100
	s_addc_u32 s50, s50, 0
	s_add_u32 s28, s28, 0x100
	s_addc_u32 s29, s29, 0
	s_cmpk_gt_u32 s51, 0x7d
	s_cbranch_scc0 .LBB0_126
	s_and_b64 vcc, exec, s[12:13]
	s_cbranch_vccz .LBB0_129
	s_barrier

; #define PG8_STAGE(bufoff, gbase, voff) do { _Pragma("unroll") for (int _i = 0; _i < 2; ++_i) \
;         __builtin_amdgcn_global_load_lds((const unsigned*)((const char*)(gbase) + (voff)[_i]), (LAS unsigned*)(lds + (bufoff) + ldsw + _i * 8192), 16, 0, 0); } while (0)
; #define PG8_LDA(dst, b, h) do { _Pragma("unroll") for (int m = 0; m < 4; ++m) _Pragma("unroll") for (int k = 0; k < 2; ++k) dst[m][k] = *(const LAS bf16x8*)(lds + PG8_SA(b, h) + aoff + m * 2048 + k * 1024); } while (0)
; #define PG8_LDB(dst, b, h) do { _Pragma("unroll") for (int n = 0; n < 2; ++n) _Pragma("unroll") for (int k = 0; k < 2; ++k) dst[n][k] = *(const LAS bf16x8*)(lds + PG8_SB(b, h) + boff + n * 2048 + k * 1024); } while (0)
; #define PG8_WAIT_V(n) asm volatile("s_waitcnt vmcnt(" #n ")" ::: "memory")
; #define PG8_WAIT_L(n) asm volatile("s_waitcnt lgkmcnt(" #n ")" ::: "memory")
; #define PG8_BAR __builtin_amdgcn_s_barrier()
; #define PG8_SCHED __builtin_amdgcn_sched_barrier(0)
; template <class Epi>
; __device__ __forceinline__ void gemm_phase(LAS unsigned char* lds, const Gemm g, const StaticOrder& S, const Epi& E, const int tid) {
;     ...
;         for (int t = 0; t < ntt; t += 2) {
;             const bool last = (t == ntt - 2);
;             const bool s1 = Epi::TWO && (t >= nt), s2 = Epi::TWO && (t + 2 >= nt);
;             const char* a1 = (s1 ? cA2 + (size_t)(t - nt + 1) * kstep : cA + (size_t)(t + 1) * kstep);
;             const char* a2 = last ? nA : (s2 ? cA2 + (size_t)(t + 2 - nt) * kstep : cA + (size_t)(t + 2) * kstep);
;             const char* b2 = last ? nB : (s2 ? cB2 + (size_t)(t + 2 - nt) * kstep : cB + (size_t)(t + 2) * kstep);
;             const char* a3 = a2 + kstep; const char* b3 = b2 + kstep;
;             if constexpr (Epi::TWO) { if (t == nt) E.mid(acc, cur, wr, wc, fr, fq); }
;             if constexpr (SP2) {
;             PG8_LDB(B0, 0, 0); PG8_LDB(B1, 0, 1); PG8_SCHED; PG8_LDA(At, 0, 0); PG8_STAGE(PG8_SA(1, 1), a1 + hstep, voffA);
;             PG8_WAIT_V(8); PG8_WAIT_L(0); PG8_BAR; PG8_MMA(0, 0, At, B0); PG8_MMA(0, 1, At, B1); PG8_BAR; PG8_SCHED;
;             PG8_LDA(At, 0, 1); PG8_STAGE(PG8_SB(0, 0), b2, voffB); PG8_STAGE(PG8_SB(0, 1), b2 + bhs, voffB); PG8_STAGE(PG8_SA(0, 0), a2, voffA);
;             PG8_WAIT_V(8); PG8_WAIT_L(0); PG8_BAR; PG8_MMA(1, 0, At, B0); PG8_MMA(1, 1, At, B1); PG8_BAR; PG8_SCHED;
.LBB0_173:
	s_add_u32 s28, s26, 0xfff80080
	s_addc_u32 s29, s27, -1
	s_add_i32 s47, 0, 0x10000
	s_cmp_eq_u32 s46, 28
	s_cselect_b32 s31, s17, s29
	s_cselect_b32 s30, s42, s28
	v_add_u32_e32 v142, s47, v149
	s_cselect_b32 s29, s15, s45
	s_cselect_b32 s28, s43, s44
	s_add_i32 s50, 0, 0x14000
	ds_read_b128 v[156:159], v142
	ds_read_b128 v[160:163], v142 offset:1024
	ds_read_b128 v[164:167], v142 offset:2048
	ds_read_b128 v[178:181], v142 offset:3072
	v_add_u32_e32 v142, s50, v149
	ds_read_b128 v[182:185], v142
	ds_read_b128 v[186:189], v142 offset:1024
	ds_read_b128 v[190:193], v142 offset:2048
	ds_read_b128 v[194:197], v142 offset:3072
	v_lshl_add_u64 v[142:143], s[26:27], 0, v[140:141]
	s_add_i32 m0, s2, 0xc000
	ds_read_b128 v[198:201], v154
	global_load_lds_dwordx4 v[142:143], off
	ds_read_b128 v[212:215], v154 offset:1024
	ds_read_b128 v[216:219], v154 offset:2048
	v_lshl_add_u64 v[142:143], s[26:27], 0, v[138:139]
	s_add_i32 m0, s2, 0xe000
	s_nop 0
	global_load_lds_dwordx4 v[142:143], off
	ds_read_b128 v[220:223], v154 offset:3072
	ds_read_b128 v[224:227], v154 offset:4096
	ds_read_b128 v[228:231], v154 offset:5120
	ds_read_b128 v[232:235], v154 offset:6144
	ds_read_b128 v[236:239], v154 offset:7168
	s_waitcnt vmcnt(8)
	s_waitcnt lgkmcnt(0)
	s_barrier
	s_setprio 1
	s_waitcnt lgkmcnt(0)
	v_mfma_f32_16x16x32_bf16 v[126:129], v[156:159], v[198:201], v[126:129]
	v_mfma_f32_16x16x32_bf16 v[122:125], v[164:167], v[198:201], v[122:125]
	v_mfma_f32_16x16x32_bf16 v[110:113], v[156:159], v[216:219], v[110:113]
	v_mfma_f32_16x16x32_bf16 v[106:109], v[164:167], v[216:219], v[106:109]
	v_mfma_f32_16x16x32_bf16 v[94:97], v[156:159], v[224:227], v[94:97]
	v_mfma_f32_16x16x32_bf16 v[90:93], v[164:167], v[224:227], v[90:93]
	v_mfma_f32_16x16x32_bf16 v[78:81], v[156:159], v[232:235], v[78:81]
	v_mfma_f32_16x16x32_bf16 v[74:77], v[164:167], v[232:235], v[74:77]
	v_mfma_f32_16x16x32_bf16 v[126:129], v[160:163], v[212:215], v[126:129]
	v_mfma_f32_16x16x32_bf16 v[122:125], v[178:181], v[212:215], v[122:125]
	v_mfma_f32_16x16x32_bf16 v[110:113], v[160:163], v[220:223], v[110:113]
	v_mfma_f32_16x16x32_bf16 v[106:109], v[178:181], v[220:223], v[106:109]
	v_mfma_f32_16x16x32_bf16 v[94:97], v[160:163], v[228:231], v[94:97]
	v_mfma_f32_16x16x32_bf16 v[90:93], v[178:181], v[228:231], v[90:93]
	v_mfma_f32_16x16x32_bf16 v[78:81], v[160:163], v[236:239], v[78:81]
	v_mfma_f32_16x16x32_bf16 v[74:77], v[178:181], v[236:239], v[74:77]
	s_setprio 0
	s_setprio 1
	v_mfma_f32_16x16x32_bf16 v[118:121], v[182:185], v[198:201], v[118:121]
	v_mfma_f32_16x16x32_bf16 v[114:117], v[190:193], v[198:201], v[114:117]
	v_mfma_f32_16x16x32_bf16 v[102:105], v[182:185], v[216:219], v[102:105]
	v_mfma_f32_16x16x32_bf16 v[98:101], v[190:193], v[216:219], v[98:101]
	v_mfma_f32_16x16x32_bf16 v[86:89], v[182:185], v[224:227], v[86:89]
	v_mfma_f32_16x16x32_bf16 v[82:85], v[190:193], v[224:227], v[82:85]
	v_mfma_f32_16x16x32_bf16 v[70:73], v[182:185], v[232:235], v[70:73]
	v_mfma_f32_16x16x32_bf16 v[66:69], v[190:193], v[232:235], v[66:69]
	v_mfma_f32_16x16x32_bf16 v[118:121], v[186:189], v[212:215], v[118:121]
	v_mfma_f32_16x16x32_bf16 v[114:117], v[194:197], v[212:215], v[114:117]
	v_mfma_f32_16x16x32_bf16 v[102:105], v[186:189], v[220:223], v[102:105]
	v_mfma_f32_16x16x32_bf16 v[98:101], v[194:197], v[220:223], v[98:101]
	v_mfma_f32_16x16x32_bf16 v[86:89], v[186:189], v[228:231], v[86:89]
	v_mfma_f32_16x16x32_bf16 v[82:85], v[194:197], v[228:231], v[82:85]
	v_mfma_f32_16x16x32_bf16 v[70:73], v[186:189], v[236:239], v[70:73]
	v_mfma_f32_16x16x32_bf16 v[66:69], v[194:197], v[236:239], v[66:69]
	s_setprio 0
	s_barrier
	s_add_i32 s47, s47, s34
	v_lshl_add_u64 v[142:143], s[28:29], 0, v[0:1]
	s_mov_b32 m0, s47
	ds_read_b128 v[198:201], v154 offset:16384
	global_load_lds_dwordx4 v[142:143], off
	ds_read_b128 v[212:215], v154 offset:17408
	ds_read_b128 v[216:219], v154 offset:18432
	s_add_i32 m0, s47, 0x2000
	s_add_u32 s48, s28, 0x8000
	v_lshl_add_u64 v[168:169], s[28:29], 0, v[134:135]
	s_addc_u32 s49, s29, 0
	s_add_i32 s47, s50, s34
	global_load_lds_dwordx4 v[168:169], off
	ds_read_b128 v[220:223], v154 offset:19456
	ds_read_b128 v[224:227], v154 offset:20480
	v_lshl_add_u64 v[172:173], s[48:49], 0, v[0:1]
	s_mov_b32 m0, s47
	v_lshl_add_u64 v[174:175], s[30:31], 0, v[132:133]
	global_load_lds_dwordx4 v[172:173], off
	ds_read_b128 v[228:231], v154 offset:21504
	ds_read_b128 v[232:235], v154 offset:22528
	v_lshl_add_u64 v[172:173], s[48:49], 0, v[134:135]
	s_add_i32 m0, s47, 0x2000
	s_nop 0
	global_load_lds_dwordx4 v[172:173], off
	ds_read_b128 v[236:239], v154 offset:23552
	v_lshl_add_u64 v[172:173], s[30:31], 0, v[130:131]
	s_mov_b32 m0, s2
	s_nop 0
	global_load_lds_dwordx4 v[172:173], off
	s_mov_b32 m0, s25
	s_nop 0
	global_load_lds_dwordx4 v[174:175], off
	s_nop 0
	s_waitcnt vmcnt(8)
	s_waitcnt lgkmcnt(0)
	s_barrier
; #define PG8_STAGE(bufoff, gbase, voff) do { _Pragma("unroll") for (int _i = 0; _i < 2; ++_i) \
;         __builtin_amdgcn_global_load_lds((const unsigned*)((const char*)(gbase) + (voff)[_i]), (LAS unsigned*)(lds + (bufoff) + ldsw + _i * 8192), 16, 0, 0); } while (0)
; #define PG8_LDA(dst, b, h) do { _Pragma("unroll") for (int m = 0; m < 4; ++m) _Pragma("unroll") for (int k = 0; k < 2; ++k) dst[m][k] = *(const LAS bf16x8*)(lds + PG8_SA(b, h) + aoff + m * 2048 + k * 1024); } while (0)
; #define PG8_LDB(dst, b, h) do { _Pragma("unroll") for (int n = 0; n < 2; ++n) _Pragma("unroll") for (int k = 0; k < 2; ++k) dst[n][k] = *(const LAS bf16x8*)(lds + PG8_SB(b, h) + boff + n * 2048 + k * 1024); } while (0)
; #define PG8_MMA(ai, bj, At, Bt) do { __builtin_amdgcn_s_setprio(1); _Pragma("unroll") for (int m = 0; m < 4; ++m) _Pragma("unroll") for (int n = 0; n < 2; ++n) _Pragma("unroll") for (int k = 0; k < 2; ++k) \
;         acc[ai][bj][m][n] = __builtin_amdgcn_mfma_f32_16x16x32_bf16(Bt[n][k], At[m][k], acc[ai][bj][m][n], 0, 0, 0); __builtin_amdgcn_s_setprio(0); } while (0)
; #define PG8_WAIT_V(n) asm volatile("s_waitcnt vmcnt(" #n ")" ::: "memory")
; #define PG8_WAIT_L(n) asm volatile("s_waitcnt lgkmcnt(" #n ")" ::: "memory")
; #define PG8_BAR __builtin_amdgcn_s_barrier()
; #define PG8_SCHED __builtin_amdgcn_sched_barrier(0)
; template <class Epi>
; __device__ __forceinline__ void gemm_phase(LAS unsigned char* lds, const Gemm g, const StaticOrder& S, const Epi& E, const int tid) {
;     ...
;             PG8_LDA(At, 0, 1); PG8_STAGE(PG8_SB(0, 0), b2, voffB); PG8_STAGE(PG8_SB(0, 1), b2 + bhs, voffB); PG8_STAGE(PG8_SA(0, 0), a2, voffA);
;             PG8_WAIT_V(8); PG8_WAIT_L(0); PG8_BAR; PG8_MMA(1, 0, At, B0); PG8_MMA(1, 1, At, B1); PG8_BAR; PG8_SCHED;
;             PG8_LDB(B0, 1, 0); PG8_LDB(B1, 1, 1); PG8_SCHED; PG8_LDA(At, 1, 0); PG8_STAGE(PG8_SA(0, 1), a2 + hstep, voffA);
;             PG8_WAIT_V(8); PG8_WAIT_L(0); PG8_BAR; PG8_MMA(0, 0, At, B0); PG8_MMA(0, 1, At, B1); PG8_BAR; PG8_SCHED;
	s_setprio 1
	s_waitcnt lgkmcnt(0)
	v_mfma_f32_16x16x32_bf16 v[62:65], v[156:159], v[198:201], v[62:65]
	v_mfma_f32_16x16x32_bf16 v[58:61], v[164:167], v[198:201], v[58:61]
	v_mfma_f32_16x16x32_bf16 v[46:49], v[156:159], v[216:219], v[46:49]
	v_mfma_f32_16x16x32_bf16 v[42:45], v[164:167], v[216:219], v[42:45]
	v_mfma_f32_16x16x32_bf16 v[30:33], v[156:159], v[224:227], v[30:33]
	v_mfma_f32_16x16x32_bf16 v[26:29], v[164:167], v[224:227], v[26:29]
	v_mfma_f32_16x16x32_bf16 v[14:17], v[156:159], v[232:235], v[14:17]
	v_mfma_f32_16x16x32_bf16 v[10:13], v[164:167], v[232:235], v[10:13]
	v_mfma_f32_16x16x32_bf16 v[62:65], v[160:163], v[212:215], v[62:65]
	v_mfma_f32_16x16x32_bf16 v[58:61], v[178:181], v[212:215], v[58:61]
	v_mfma_f32_16x16x32_bf16 v[46:49], v[160:163], v[220:223], v[46:49]
	v_mfma_f32_16x16x32_bf16 v[42:45], v[178:181], v[220:223], v[42:45]
	v_mfma_f32_16x16x32_bf16 v[30:33], v[160:163], v[228:231], v[30:33]
	v_mfma_f32_16x16x32_bf16 v[26:29], v[178:181], v[228:231], v[26:29]
	v_mfma_f32_16x16x32_bf16 v[14:17], v[160:163], v[236:239], v[14:17]
	v_mfma_f32_16x16x32_bf16 v[10:13], v[178:181], v[236:239], v[10:13]
	s_setprio 0
	s_setprio 1
	v_mfma_f32_16x16x32_bf16 v[54:57], v[182:185], v[198:201], v[54:57]
	v_mfma_f32_16x16x32_bf16 v[50:53], v[190:193], v[198:201], v[50:53]
	v_mfma_f32_16x16x32_bf16 v[38:41], v[182:185], v[216:219], v[38:41]
	v_mfma_f32_16x16x32_bf16 v[34:37], v[190:193], v[216:219], v[34:37]
	v_mfma_f32_16x16x32_bf16 v[22:25], v[182:185], v[224:227], v[22:25]
	v_mfma_f32_16x16x32_bf16 v[18:21], v[190:193], v[224:227], v[18:21]
	v_mfma_f32_16x16x32_bf16 v[6:9], v[182:185], v[232:235], v[6:9]
	v_mfma_f32_16x16x32_bf16 v[2:5], v[190:193], v[232:235], v[2:5]
	v_mfma_f32_16x16x32_bf16 v[54:57], v[186:189], v[212:215], v[54:57]
	v_mfma_f32_16x16x32_bf16 v[50:53], v[194:197], v[212:215], v[50:53]
	v_mfma_f32_16x16x32_bf16 v[38:41], v[186:189], v[220:223], v[38:41]
	v_mfma_f32_16x16x32_bf16 v[34:37], v[194:197], v[220:223], v[34:37]
	v_mfma_f32_16x16x32_bf16 v[22:25], v[186:189], v[228:231], v[22:25]
	v_mfma_f32_16x16x32_bf16 v[18:21], v[194:197], v[228:231], v[18:21]
	v_mfma_f32_16x16x32_bf16 v[6:9], v[186:189], v[236:239], v[6:9]
	v_mfma_f32_16x16x32_bf16 v[2:5], v[194:197], v[236:239], v[2:5]
	s_setprio 0
	s_barrier
	s_add_i32 s47, 0, 0x18000
	v_add_u32_e32 v155, s47, v149
	s_add_i32 s48, 0, 0x1c000
	ds_read_b128 v[156:159], v155
	ds_read_b128 v[160:163], v155 offset:1024
	ds_read_b128 v[164:167], v155 offset:2048
	ds_read_b128 v[178:181], v155 offset:3072
	v_add_u32_e32 v155, s48, v149
	ds_read_b128 v[182:185], v155
	ds_read_b128 v[186:189], v155 offset:1024
	ds_read_b128 v[190:193], v155 offset:2048
	ds_read_b128 v[194:197], v155 offset:3072
	s_add_u32 s30, s30, 0x80000
	s_addc_u32 s31, s31, 0
	s_mov_b32 m0, s35
	v_lshl_add_u64 v[176:177], s[30:31], 0, v[130:131]
	ds_read_b128 v[198:201], v154 offset:32768
	global_load_lds_dwordx4 v[176:177], off
	ds_read_b128 v[212:215], v154 offset:33792
	ds_read_b128 v[216:219], v154 offset:34816
	v_lshl_add_u64 v[176:177], s[30:31], 0, v[132:133]
	s_mov_b32 m0, s36
	s_nop 0
	global_load_lds_dwordx4 v[176:177], off
	ds_read_b128 v[220:223], v154 offset:35840
	ds_read_b128 v[224:227], v154 offset:36864
	ds_read_b128 v[228:231], v154 offset:37888
	ds_read_b128 v[232:235], v154 offset:38912
	ds_read_b128 v[236:239], v154 offset:39936
	s_nop 0
	s_waitcnt vmcnt(8)
	s_waitcnt lgkmcnt(0)
	s_barrier
	s_setprio 1
	s_waitcnt lgkmcnt(0)
	v_mfma_f32_16x16x32_bf16 v[126:129], v[156:159], v[198:201], v[126:129]
	v_mfma_f32_16x16x32_bf16 v[122:125], v[164:167], v[198:201], v[122:125]
	v_mfma_f32_16x16x32_bf16 v[110:113], v[156:159], v[216:219], v[110:113]
	v_mfma_f32_16x16x32_bf16 v[106:109], v[164:167], v[216:219], v[106:109]
	v_mfma_f32_16x16x32_bf16 v[94:97], v[156:159], v[224:227], v[94:97]
	v_mfma_f32_16x16x32_bf16 v[90:93], v[164:167], v[224:227], v[90:93]
	v_mfma_f32_16x16x32_bf16 v[78:81], v[156:159], v[232:235], v[78:81]
	v_mfma_f32_16x16x32_bf16 v[74:77], v[164:167], v[232:235], v[74:77]
	v_mfma_f32_16x16x32_bf16 v[126:129], v[160:163], v[212:215], v[126:129]
	v_mfma_f32_16x16x32_bf16 v[122:125], v[178:181], v[212:215], v[122:125]
	v_mfma_f32_16x16x32_bf16 v[110:113], v[160:163], v[220:223], v[110:113]
	v_mfma_f32_16x16x32_bf16 v[106:109], v[178:181], v[220:223], v[106:109]
	v_mfma_f32_16x16x32_bf16 v[94:97], v[160:163], v[228:231], v[94:97]
	v_mfma_f32_16x16x32_bf16 v[90:93], v[178:181], v[228:231], v[90:93]
	v_mfma_f32_16x16x32_bf16 v[78:81], v[160:163], v[236:239], v[78:81]
	v_mfma_f32_16x16x32_bf16 v[74:77], v[178:181], v[236:239], v[74:77]
	s_setprio 0
	s_setprio 1
	v_mfma_f32_16x16x32_bf16 v[118:121], v[182:185], v[198:201], v[118:121]
	v_mfma_f32_16x16x32_bf16 v[114:117], v[190:193], v[198:201], v[114:117]
	v_mfma_f32_16x16x32_bf16 v[102:105], v[182:185], v[216:219], v[102:105]
	v_mfma_f32_16x16x32_bf16 v[98:101], v[190:193], v[216:219], v[98:101]
	v_mfma_f32_16x16x32_bf16 v[86:89], v[182:185], v[224:227], v[86:89]
	v_mfma_f32_16x16x32_bf16 v[82:85], v[190:193], v[224:227], v[82:85]
	v_mfma_f32_16x16x32_bf16 v[70:73], v[182:185], v[232:235], v[70:73]
	v_mfma_f32_16x16x32_bf16 v[66:69], v[190:193], v[232:235], v[66:69]
	v_mfma_f32_16x16x32_bf16 v[118:121], v[186:189], v[212:215], v[118:121]
	v_mfma_f32_16x16x32_bf16 v[114:117], v[194:197], v[212:215], v[114:117]
	v_mfma_f32_16x16x32_bf16 v[102:105], v[186:189], v[220:223], v[102:105]
	v_mfma_f32_16x16x32_bf16 v[98:101], v[194:197], v[220:223], v[98:101]
	v_mfma_f32_16x16x32_bf16 v[86:89], v[186:189], v[228:231], v[86:89]
	v_mfma_f32_16x16x32_bf16 v[82:85], v[194:197], v[228:231], v[82:85]
	v_mfma_f32_16x16x32_bf16 v[70:73], v[186:189], v[236:239], v[70:73]
	v_mfma_f32_16x16x32_bf16 v[66:69], v[194:197], v[236:239], v[66:69]
	s_setprio 0
	s_barrier
; #define PG8_STAGE(bufoff, gbase, voff) do { _Pragma("unroll") for (int _i = 0; _i < 2; ++_i) \
;         __builtin_amdgcn_global_load_lds((const unsigned*)((const char*)(gbase) + (voff)[_i]), (LAS unsigned*)(lds + (bufoff) + ldsw + _i * 8192), 16, 0, 0); } while (0)
; #define PG8_LDA(dst, b, h) do { _Pragma("unroll") for (int m = 0; m < 4; ++m) _Pragma("unroll") for (int k = 0; k < 2; ++k) dst[m][k] = *(const LAS bf16x8*)(lds + PG8_SA(b, h) + aoff + m * 2048 + k * 1024); } while (0)
; #define PG8_MMA(ai, bj, At, Bt) do { __builtin_amdgcn_s_setprio(1); _Pragma("unroll") for (int m = 0; m < 4; ++m) _Pragma("unroll") for (int n = 0; n < 2; ++n) _Pragma("unroll") for (int k = 0; k < 2; ++k) \
;         acc[ai][bj][m][n] = __builtin_amdgcn_mfma_f32_16x16x32_bf16(Bt[n][k], At[m][k], acc[ai][bj][m][n], 0, 0, 0); __builtin_amdgcn_s_setprio(0); } while (0)
; #define PG8_WAIT_V(n) asm volatile("s_waitcnt vmcnt(" #n ")" ::: "memory")
; #define PG8_WAIT_L(n) asm volatile("s_waitcnt lgkmcnt(" #n ")" ::: "memory")
; #define PG8_BAR __builtin_amdgcn_s_barrier()
; #define PG8_SCHED __builtin_amdgcn_sched_barrier(0)
; template <class Epi>
; __device__ __forceinline__ void gemm_phase(LAS unsigned char* lds, const Gemm g, const StaticOrder& S, const Epi& E, const int tid) {
;     ...
;             PG8_WAIT_V(8); PG8_WAIT_L(0); PG8_BAR; PG8_MMA(0, 0, At, B0); PG8_MMA(0, 1, At, B1); PG8_BAR; PG8_SCHED;
;             PG8_LDA(At, 1, 1); PG8_STAGE(PG8_SB(1, 0), b3, voffB); PG8_STAGE(PG8_SB(1, 1), b3 + bhs, voffB); PG8_STAGE(PG8_SA(1, 0), a3, voffA);
;             PG8_WAIT_V(8); PG8_WAIT_L(0); PG8_BAR; PG8_MMA(1, 0, At, B0); PG8_MMA(1, 1, At, B1); PG8_BAR; PG8_SCHED;
	s_add_i32 s30, s47, s34
	v_lshl_add_u64 v[142:143], v[142:143], 0, s[70:71]
	s_mov_b32 m0, s30
	ds_read_b128 v[198:201], v154 offset:49152
	global_load_lds_dwordx4 v[142:143], off
	ds_read_b128 v[212:215], v154 offset:50176
	ds_read_b128 v[216:219], v154 offset:51200
	s_add_i32 m0, s30, 0x2000
	s_add_u32 s28, s28, 0x8080
	v_lshl_add_u64 v[142:143], v[168:169], 0, s[70:71]
	s_addc_u32 s29, s29, 0
	s_add_i32 s30, s48, s34
	global_load_lds_dwordx4 v[142:143], off
	ds_read_b128 v[220:223], v154 offset:52224
	ds_read_b128 v[224:227], v154 offset:53248
	v_lshl_add_u64 v[142:143], s[28:29], 0, v[0:1]
	s_mov_b32 m0, s30
	s_nop 0
	global_load_lds_dwordx4 v[142:143], off
	ds_read_b128 v[228:231], v154 offset:54272
	ds_read_b128 v[232:235], v154 offset:55296
	v_lshl_add_u64 v[142:143], s[28:29], 0, v[134:135]
	s_add_i32 m0, s30, 0x2000
	s_nop 0
	global_load_lds_dwordx4 v[142:143], off
	ds_read_b128 v[236:239], v154 offset:56320
	v_lshl_add_u64 v[142:143], v[172:173], 0, s[70:71]
	s_mov_b32 m0, s37
	s_nop 0
	global_load_lds_dwordx4 v[142:143], off
	v_lshl_add_u64 v[142:143], v[174:175], 0, s[70:71]
	s_mov_b32 m0, s38
	s_nop 0
	global_load_lds_dwordx4 v[142:143], off
	s_waitcnt vmcnt(8)
	s_waitcnt lgkmcnt(0)
	s_barrier
	s_setprio 1
	s_waitcnt lgkmcnt(0)
	v_mfma_f32_16x16x32_bf16 v[62:65], v[156:159], v[198:201], v[62:65]
	v_mfma_f32_16x16x32_bf16 v[58:61], v[164:167], v[198:201], v[58:61]
	v_mfma_f32_16x16x32_bf16 v[46:49], v[156:159], v[216:219], v[46:49]
	v_mfma_f32_16x16x32_bf16 v[42:45], v[164:167], v[216:219], v[42:45]
	v_mfma_f32_16x16x32_bf16 v[30:33], v[156:159], v[224:227], v[30:33]
	v_mfma_f32_16x16x32_bf16 v[26:29], v[164:167], v[224:227], v[26:29]
	v_mfma_f32_16x16x32_bf16 v[14:17], v[156:159], v[232:235], v[14:17]
	v_mfma_f32_16x16x32_bf16 v[10:13], v[164:167], v[232:235], v[10:13]
	v_mfma_f32_16x16x32_bf16 v[62:65], v[160:163], v[212:215], v[62:65]
	v_mfma_f32_16x16x32_bf16 v[58:61], v[178:181], v[212:215], v[58:61]
	v_mfma_f32_16x16x32_bf16 v[46:49], v[160:163], v[220:223], v[46:49]
	v_mfma_f32_16x16x32_bf16 v[42:45], v[178:181], v[220:223], v[42:45]
	v_mfma_f32_16x16x32_bf16 v[30:33], v[160:163], v[228:231], v[30:33]
	v_mfma_f32_16x16x32_bf16 v[26:29], v[178:181], v[228:231], v[26:29]
	v_mfma_f32_16x16x32_bf16 v[14:17], v[160:163], v[236:239], v[14:17]
	v_mfma_f32_16x16x32_bf16 v[10:13], v[178:181], v[236:239], v[10:13]
	s_setprio 0
	s_setprio 1
	v_mfma_f32_16x16x32_bf16 v[54:57], v[182:185], v[198:201], v[54:57]
	v_mfma_f32_16x16x32_bf16 v[50:53], v[190:193], v[198:201], v[50:53]
	v_mfma_f32_16x16x32_bf16 v[38:41], v[182:185], v[216:219], v[38:41]
	v_mfma_f32_16x16x32_bf16 v[34:37], v[190:193], v[216:219], v[34:37]
	v_mfma_f32_16x16x32_bf16 v[22:25], v[182:185], v[224:227], v[22:25]
	v_mfma_f32_16x16x32_bf16 v[18:21], v[190:193], v[224:227], v[18:21]
	v_mfma_f32_16x16x32_bf16 v[6:9], v[182:185], v[232:235], v[6:9]
	v_mfma_f32_16x16x32_bf16 v[2:5], v[190:193], v[232:235], v[2:5]
	v_mfma_f32_16x16x32_bf16 v[54:57], v[186:189], v[212:215], v[54:57]
	v_mfma_f32_16x16x32_bf16 v[50:53], v[194:197], v[212:215], v[50:53]
	v_mfma_f32_16x16x32_bf16 v[38:41], v[186:189], v[220:223], v[38:41]
	v_mfma_f32_16x16x32_bf16 v[34:37], v[194:197], v[220:223], v[34:37]
	v_mfma_f32_16x16x32_bf16 v[22:25], v[186:189], v[228:231], v[22:25]
	v_mfma_f32_16x16x32_bf16 v[18:21], v[194:197], v[228:231], v[18:21]
	v_mfma_f32_16x16x32_bf16 v[6:9], v[186:189], v[236:239], v[6:9]
	v_mfma_f32_16x16x32_bf16 v[2:5], v[194:197], v[236:239], v[2:5]
	s_setprio 0
	s_barrier
	s_add_i32 s46, s46, 2
	s_add_u32 s44, s44, 0x100
	s_addc_u32 s45, s45, 0
	s_add_u32 s26, s26, 0x100
	s_addc_u32 s27, s27, 0
	s_cmp_gt_u32 s46, 29
	s_cbranch_scc0 .LBB0_173
	v_readlane_b32 s42, v251, 53
	s_and_b64 vcc, exec, s[12:13]
	v_readlane_b32 s43, v251, 54
	s_cbranch_vccz .LBB0_176
	s_barrier

; #define PG8_STAGE(bufoff, gbase, voff) do { _Pragma("unroll") for (int _i = 0; _i < 2; ++_i) \
;         __builtin_amdgcn_global_load_lds((const unsigned*)((const char*)(gbase) + (voff)[_i]), (LAS unsigned*)(lds + (bufoff) + ldsw + _i * 8192), 16, 0, 0); } while (0)
; #define PG8_LDA(dst, b, h) do { _Pragma("unroll") for (int m = 0; m < 4; ++m) _Pragma("unroll") for (int k = 0; k < 2; ++k) dst[m][k] = *(const LAS bf16x8*)(lds + PG8_SA(b, h) + aoff + m * 2048 + k * 1024); } while (0)
; #define PG8_LDB(dst, b, h) do { _Pragma("unroll") for (int n = 0; n < 2; ++n) _Pragma("unroll") for (int k = 0; k < 2; ++k) dst[n][k] = *(const LAS bf16x8*)(lds + PG8_SB(b, h) + boff + n * 2048 + k * 1024); } while (0)
; #define PG8_WAIT_V(n) asm volatile("s_waitcnt vmcnt(" #n ")" ::: "memory")
; #define PG8_WAIT_L(n) asm volatile("s_waitcnt lgkmcnt(" #n ")" ::: "memory")
; #define PG8_BAR __builtin_amdgcn_s_barrier()
; #define PG8_SCHED __builtin_amdgcn_sched_barrier(0)
; template <class Epi>
; __device__ __forceinline__ void gemm_phase(LAS unsigned char* lds, const Gemm g, const StaticOrder& S, const Epi& E, const int tid) {
;     ...
;         for (int t = 0; t < ntt; t += 2) {
;             const bool last = (t == ntt - 2);
;             const bool s1 = Epi::TWO && (t >= nt), s2 = Epi::TWO && (t + 2 >= nt);
;             const char* a1 = (s1 ? cA2 + (size_t)(t - nt + 1) * kstep : cA + (size_t)(t + 1) * kstep);
;             const char* a2 = last ? nA : (s2 ? cA2 + (size_t)(t + 2 - nt) * kstep : cA + (size_t)(t + 2) * kstep);
;             const char* b2 = last ? nB : (s2 ? cB2 + (size_t)(t + 2 - nt) * kstep : cB + (size_t)(t + 2) * kstep);
;             const char* a3 = a2 + kstep; const char* b3 = b2 + kstep;
;             if constexpr (Epi::TWO) { if (t == nt) E.mid(acc, cur, wr, wc, fr, fq); }
;             if constexpr (SP2) {
;             PG8_LDB(B0, 0, 0); PG8_LDB(B1, 0, 1); PG8_SCHED; PG8_LDA(At, 0, 0); PG8_STAGE(PG8_SA(1, 1), a1 + hstep, voffA);
;             PG8_WAIT_V(8); PG8_WAIT_L(0); PG8_BAR; PG8_MMA(0, 0, At, B0); PG8_MMA(0, 1, At, B1); PG8_BAR; PG8_SCHED;
;             PG8_LDA(At, 0, 1); PG8_STAGE(PG8_SB(0, 0), b2, voffB); PG8_STAGE(PG8_SB(0, 1), b2 + bhs, voffB); PG8_STAGE(PG8_SA(0, 0), a2, voffA);
;             PG8_WAIT_V(8); PG8_WAIT_L(0); PG8_BAR; PG8_MMA(1, 0, At, B0); PG8_MMA(1, 1, At, B1); PG8_BAR; PG8_SCHED;
.LBB0_206:
	s_add_u32 s30, s28, 0xfffe0080
	s_addc_u32 s31, s29, -1
	s_add_i32 s52, 0, 0x10000
	s_cmp_eq_u32 s51, 4
	s_cselect_b32 s35, s17, s31
	s_cselect_b32 s34, s27, s30
	s_cselect_b32 s31, s15, s50
	s_cselect_b32 s30, s33, s49
	s_add_i32 s54, 0, 0x14000
	v_add_u32_e32 v30, s52, v193
	v_add_u32_e32 v54, s54, v193
	ds_read_b128 v[18:21], v30
	ds_read_b128 v[22:25], v30 offset:1024
	ds_read_b128 v[26:29], v30 offset:2048
	ds_read_b128 v[30:33], v30 offset:3072
	ds_read_b128 v[42:45], v54
	ds_read_b128 v[46:49], v54 offset:1024
	ds_read_b128 v[50:53], v54 offset:2048
	ds_read_b128 v[54:57], v54 offset:3072
	v_lshl_add_u64 v[172:173], s[28:29], 0, v[180:181]
	s_add_i32 m0, s37, 0xc000
	ds_read_b128 v[182:185], v199
	global_load_lds_dwordx4 v[172:173], off
	ds_read_b128 v[186:189], v199 offset:1024
	ds_read_b128 v[212:215], v199 offset:2048
	v_lshl_add_u64 v[172:173], s[28:29], 0, v[178:179]
	s_add_i32 m0, s37, 0xe000
	s_nop 0
	global_load_lds_dwordx4 v[172:173], off
	ds_read_b128 v[216:219], v199 offset:3072
	ds_read_b128 v[220:223], v199 offset:4096
	ds_read_b128 v[224:227], v199 offset:5120
	ds_read_b128 v[228:231], v199 offset:6144
	ds_read_b128 v[232:235], v199 offset:7168
	s_waitcnt vmcnt(8)
	s_waitcnt lgkmcnt(0)
	s_barrier
	s_setprio 1
	s_waitcnt lgkmcnt(0)
	v_mfma_f32_16x16x32_bf16 v[158:161], v[18:21], v[182:185], v[158:161]
	v_mfma_f32_16x16x32_bf16 v[154:157], v[26:29], v[182:185], v[154:157]
	v_mfma_f32_16x16x32_bf16 v[142:145], v[18:21], v[212:215], v[142:145]
	v_mfma_f32_16x16x32_bf16 v[138:141], v[26:29], v[212:215], v[138:141]
	v_mfma_f32_16x16x32_bf16 v[126:129], v[18:21], v[220:223], v[126:129]
	v_mfma_f32_16x16x32_bf16 v[122:125], v[26:29], v[220:223], v[122:125]
	v_mfma_f32_16x16x32_bf16 v[110:113], v[18:21], v[228:231], v[110:113]
	v_mfma_f32_16x16x32_bf16 v[106:109], v[26:29], v[228:231], v[106:109]
	v_mfma_f32_16x16x32_bf16 v[158:161], v[22:25], v[186:189], v[158:161]
	v_mfma_f32_16x16x32_bf16 v[154:157], v[30:33], v[186:189], v[154:157]
	v_mfma_f32_16x16x32_bf16 v[142:145], v[22:25], v[216:219], v[142:145]
	v_mfma_f32_16x16x32_bf16 v[138:141], v[30:33], v[216:219], v[138:141]
	v_mfma_f32_16x16x32_bf16 v[126:129], v[22:25], v[224:227], v[126:129]
	v_mfma_f32_16x16x32_bf16 v[122:125], v[30:33], v[224:227], v[122:125]
	v_mfma_f32_16x16x32_bf16 v[110:113], v[22:25], v[232:235], v[110:113]
	v_mfma_f32_16x16x32_bf16 v[106:109], v[30:33], v[232:235], v[106:109]
	s_setprio 0
	s_setprio 1
	v_mfma_f32_16x16x32_bf16 v[150:153], v[42:45], v[182:185], v[150:153]
	v_mfma_f32_16x16x32_bf16 v[146:149], v[50:53], v[182:185], v[146:149]
	v_mfma_f32_16x16x32_bf16 v[134:137], v[42:45], v[212:215], v[134:137]
	v_mfma_f32_16x16x32_bf16 v[130:133], v[50:53], v[212:215], v[130:133]
	v_mfma_f32_16x16x32_bf16 v[118:121], v[42:45], v[220:223], v[118:121]
	v_mfma_f32_16x16x32_bf16 v[114:117], v[50:53], v[220:223], v[114:117]
	v_mfma_f32_16x16x32_bf16 v[102:105], v[42:45], v[228:231], v[102:105]
	v_mfma_f32_16x16x32_bf16 v[98:101], v[50:53], v[228:231], v[98:101]
	v_mfma_f32_16x16x32_bf16 v[150:153], v[46:49], v[186:189], v[150:153]
	v_mfma_f32_16x16x32_bf16 v[146:149], v[54:57], v[186:189], v[146:149]
	v_mfma_f32_16x16x32_bf16 v[134:137], v[46:49], v[216:219], v[134:137]
	v_mfma_f32_16x16x32_bf16 v[130:133], v[54:57], v[216:219], v[130:133]
	v_mfma_f32_16x16x32_bf16 v[118:121], v[46:49], v[224:227], v[118:121]
	v_mfma_f32_16x16x32_bf16 v[114:117], v[54:57], v[224:227], v[114:117]
	v_mfma_f32_16x16x32_bf16 v[102:105], v[46:49], v[232:235], v[102:105]
	v_mfma_f32_16x16x32_bf16 v[98:101], v[54:57], v[232:235], v[98:101]
	s_setprio 0
	s_barrier
	s_add_i32 s52, s52, s36
	v_lshl_add_u64 v[172:173], s[30:31], 0, v[0:1]
	s_mov_b32 m0, s52
	ds_read_b128 v[182:185], v199 offset:16384
	global_load_lds_dwordx4 v[172:173], off
	ds_read_b128 v[186:189], v199 offset:17408
	ds_read_b128 v[212:215], v199 offset:18432
	s_add_i32 m0, s52, 0x2000
	s_add_u32 s52, s30, 0x2000
	v_lshl_add_u64 v[174:175], s[30:31], 0, v[166:167]
	s_addc_u32 s53, s31, 0
	s_add_i32 s54, s54, s36
	global_load_lds_dwordx4 v[174:175], off
	ds_read_b128 v[216:219], v199 offset:19456
	ds_read_b128 v[220:223], v199 offset:20480
	v_lshl_add_u64 v[176:177], s[52:53], 0, v[0:1]
	s_mov_b32 m0, s54
	v_lshl_add_u64 v[200:201], s[34:35], 0, v[164:165]
	global_load_lds_dwordx4 v[176:177], off
	ds_read_b128 v[224:227], v199 offset:21504
	ds_read_b128 v[228:231], v199 offset:22528
	v_lshl_add_u64 v[176:177], s[52:53], 0, v[166:167]
	s_add_i32 m0, s54, 0x2000
	s_nop 0
	global_load_lds_dwordx4 v[176:177], off
	ds_read_b128 v[232:235], v199 offset:23552
	v_lshl_add_u64 v[176:177], s[34:35], 0, v[162:163]
	s_mov_b32 m0, s37
	s_nop 0
	global_load_lds_dwordx4 v[176:177], off
	s_mov_b32 m0, s38
	s_nop 0
	global_load_lds_dwordx4 v[200:201], off
	s_nop 0
	s_waitcnt vmcnt(8)
	s_waitcnt lgkmcnt(0)
	s_barrier
; #define PG8_STAGE(bufoff, gbase, voff) do { _Pragma("unroll") for (int _i = 0; _i < 2; ++_i) \
;         __builtin_amdgcn_global_load_lds((const unsigned*)((const char*)(gbase) + (voff)[_i]), (LAS unsigned*)(lds + (bufoff) + ldsw + _i * 8192), 16, 0, 0); } while (0)
; #define PG8_LDA(dst, b, h) do { _Pragma("unroll") for (int m = 0; m < 4; ++m) _Pragma("unroll") for (int k = 0; k < 2; ++k) dst[m][k] = *(const LAS bf16x8*)(lds + PG8_SA(b, h) + aoff + m * 2048 + k * 1024); } while (0)
; #define PG8_LDB(dst, b, h) do { _Pragma("unroll") for (int n = 0; n < 2; ++n) _Pragma("unroll") for (int k = 0; k < 2; ++k) dst[n][k] = *(const LAS bf16x8*)(lds + PG8_SB(b, h) + boff + n * 2048 + k * 1024); } while (0)
; #define PG8_MMA(ai, bj, At, Bt) do { __builtin_amdgcn_s_setprio(1); _Pragma("unroll") for (int m = 0; m < 4; ++m) _Pragma("unroll") for (int n = 0; n < 2; ++n) _Pragma("unroll") for (int k = 0; k < 2; ++k) \
;         acc[ai][bj][m][n] = __builtin_amdgcn_mfma_f32_16x16x32_bf16(Bt[n][k], At[m][k], acc[ai][bj][m][n], 0, 0, 0); __builtin_amdgcn_s_setprio(0); } while (0)
; #define PG8_WAIT_V(n) asm volatile("s_waitcnt vmcnt(" #n ")" ::: "memory")
; #define PG8_WAIT_L(n) asm volatile("s_waitcnt lgkmcnt(" #n ")" ::: "memory")
; #define PG8_BAR __builtin_amdgcn_s_barrier()
; #define PG8_SCHED __builtin_amdgcn_sched_barrier(0)
; template <class Epi>
; __device__ __forceinline__ void gemm_phase(LAS unsigned char* lds, const Gemm g, const StaticOrder& S, const Epi& E, const int tid) {
;     ...
;             PG8_LDA(At, 0, 1); PG8_STAGE(PG8_SB(0, 0), b2, voffB); PG8_STAGE(PG8_SB(0, 1), b2 + bhs, voffB); PG8_STAGE(PG8_SA(0, 0), a2, voffA);
;             PG8_WAIT_V(8); PG8_WAIT_L(0); PG8_BAR; PG8_MMA(1, 0, At, B0); PG8_MMA(1, 1, At, B1); PG8_BAR; PG8_SCHED;
;             PG8_LDB(B0, 1, 0); PG8_LDB(B1, 1, 1); PG8_SCHED; PG8_LDA(At, 1, 0); PG8_STAGE(PG8_SA(0, 1), a2 + hstep, voffA);
;             PG8_WAIT_V(8); PG8_WAIT_L(0); PG8_BAR; PG8_MMA(0, 0, At, B0); PG8_MMA(0, 1, At, B1); PG8_BAR; PG8_SCHED;
	s_setprio 1
	s_waitcnt lgkmcnt(0)
	v_mfma_f32_16x16x32_bf16 v[94:97], v[18:21], v[182:185], v[94:97]
	v_mfma_f32_16x16x32_bf16 v[90:93], v[26:29], v[182:185], v[90:93]
	v_mfma_f32_16x16x32_bf16 v[78:81], v[18:21], v[212:215], v[78:81]
	v_mfma_f32_16x16x32_bf16 v[74:77], v[26:29], v[212:215], v[74:77]
	v_mfma_f32_16x16x32_bf16 v[62:65], v[18:21], v[220:223], v[62:65]
	v_mfma_f32_16x16x32_bf16 v[58:61], v[26:29], v[220:223], v[58:61]
	v_mfma_f32_16x16x32_bf16 v[14:17], v[18:21], v[228:231], v[14:17]
	v_mfma_f32_16x16x32_bf16 v[10:13], v[26:29], v[228:231], v[10:13]
	v_mfma_f32_16x16x32_bf16 v[94:97], v[22:25], v[186:189], v[94:97]
	v_mfma_f32_16x16x32_bf16 v[90:93], v[30:33], v[186:189], v[90:93]
	v_mfma_f32_16x16x32_bf16 v[78:81], v[22:25], v[216:219], v[78:81]
	v_mfma_f32_16x16x32_bf16 v[74:77], v[30:33], v[216:219], v[74:77]
	v_mfma_f32_16x16x32_bf16 v[62:65], v[22:25], v[224:227], v[62:65]
	v_mfma_f32_16x16x32_bf16 v[58:61], v[30:33], v[224:227], v[58:61]
	v_mfma_f32_16x16x32_bf16 v[14:17], v[22:25], v[232:235], v[14:17]
	v_mfma_f32_16x16x32_bf16 v[10:13], v[30:33], v[232:235], v[10:13]
	s_setprio 0
	s_setprio 1
	v_mfma_f32_16x16x32_bf16 v[38:41], v[42:45], v[220:223], v[38:41]
	v_mfma_f32_16x16x32_bf16 v[34:37], v[50:53], v[220:223], v[34:37]
	v_mfma_f32_16x16x32_bf16 v[6:9], v[42:45], v[228:231], v[6:9]
	v_mfma_f32_16x16x32_bf16 v[2:5], v[50:53], v[228:231], v[2:5]
	v_mfma_f32_16x16x32_bf16 v[18:21], v[42:45], v[182:185], v[86:89]
	v_mfma_f32_16x16x32_bf16 v[22:25], v[50:53], v[182:185], v[82:85]
	v_mfma_f32_16x16x32_bf16 v[26:29], v[42:45], v[212:215], v[70:73]
	v_mfma_f32_16x16x32_bf16 v[30:33], v[50:53], v[212:215], v[66:69]
	v_mfma_f32_16x16x32_bf16 v[38:41], v[46:49], v[224:227], v[38:41]
	v_mfma_f32_16x16x32_bf16 v[34:37], v[54:57], v[224:227], v[34:37]
	v_mfma_f32_16x16x32_bf16 v[6:9], v[46:49], v[232:235], v[6:9]
	v_mfma_f32_16x16x32_bf16 v[2:5], v[54:57], v[232:235], v[2:5]
	v_mfma_f32_16x16x32_bf16 v[18:21], v[46:49], v[186:189], v[18:21]
	v_mfma_f32_16x16x32_bf16 v[22:25], v[54:57], v[186:189], v[22:25]
	v_mfma_f32_16x16x32_bf16 v[26:29], v[46:49], v[216:219], v[26:29]
	v_mfma_f32_16x16x32_bf16 v[30:33], v[54:57], v[216:219], v[30:33]
	s_setprio 0
	s_barrier
	s_add_i32 s52, 0, 0x18000
	s_add_i32 s53, 0, 0x1c000
	v_add_u32_e32 v54, s52, v193
	v_add_u32_e32 v66, s53, v193
	ds_read_b128 v[42:45], v54
	ds_read_b128 v[46:49], v54 offset:1024
	ds_read_b128 v[50:53], v54 offset:2048
	ds_read_b128 v[54:57], v54 offset:3072
	ds_read_b128 v[182:185], v66
	ds_read_b128 v[186:189], v66 offset:1024
	ds_read_b128 v[212:215], v66 offset:2048
	ds_read_b128 v[216:219], v66 offset:3072
	s_add_u32 s34, s34, 0x20000
	s_addc_u32 s35, s35, 0
	s_mov_b32 m0, s39
	v_lshl_add_u64 v[236:237], s[34:35], 0, v[162:163]
	ds_read_b128 v[66:69], v199 offset:32768
	global_load_lds_dwordx4 v[236:237], off
	ds_read_b128 v[70:73], v199 offset:33792
	ds_read_b128 v[82:85], v199 offset:34816
	v_lshl_add_u64 v[236:237], s[34:35], 0, v[164:165]
	s_mov_b32 m0, s44
	s_nop 0
	global_load_lds_dwordx4 v[236:237], off
	ds_read_b128 v[86:89], v199 offset:35840
	ds_read_b128 v[220:223], v199 offset:36864
	ds_read_b128 v[224:227], v199 offset:37888
	ds_read_b128 v[228:231], v199 offset:38912
	ds_read_b128 v[232:235], v199 offset:39936
	s_nop 0
	s_waitcnt vmcnt(8)
	s_waitcnt lgkmcnt(0)
	s_barrier
	s_setprio 1
	s_waitcnt lgkmcnt(0)
	v_mfma_f32_16x16x32_bf16 v[158:161], v[42:45], v[66:69], v[158:161]
	v_mfma_f32_16x16x32_bf16 v[154:157], v[50:53], v[66:69], v[154:157]
	v_mfma_f32_16x16x32_bf16 v[142:145], v[42:45], v[82:85], v[142:145]
	v_mfma_f32_16x16x32_bf16 v[138:141], v[50:53], v[82:85], v[138:141]
	v_mfma_f32_16x16x32_bf16 v[126:129], v[42:45], v[220:223], v[126:129]
	v_mfma_f32_16x16x32_bf16 v[122:125], v[50:53], v[220:223], v[122:125]
	v_mfma_f32_16x16x32_bf16 v[110:113], v[42:45], v[228:231], v[110:113]
	v_mfma_f32_16x16x32_bf16 v[106:109], v[50:53], v[228:231], v[106:109]
	v_mfma_f32_16x16x32_bf16 v[158:161], v[46:49], v[70:73], v[158:161]
	v_mfma_f32_16x16x32_bf16 v[154:157], v[54:57], v[70:73], v[154:157]
	v_mfma_f32_16x16x32_bf16 v[142:145], v[46:49], v[86:89], v[142:145]
	v_mfma_f32_16x16x32_bf16 v[138:141], v[54:57], v[86:89], v[138:141]
	v_mfma_f32_16x16x32_bf16 v[126:129], v[46:49], v[224:227], v[126:129]
	v_mfma_f32_16x16x32_bf16 v[122:125], v[54:57], v[224:227], v[122:125]
	v_mfma_f32_16x16x32_bf16 v[110:113], v[46:49], v[232:235], v[110:113]
	v_mfma_f32_16x16x32_bf16 v[106:109], v[54:57], v[232:235], v[106:109]
	s_setprio 0
	s_setprio 1
	v_mfma_f32_16x16x32_bf16 v[150:153], v[182:185], v[66:69], v[150:153]
	v_mfma_f32_16x16x32_bf16 v[66:69], v[212:215], v[66:69], v[146:149]
	v_mfma_f32_16x16x32_bf16 v[146:149], v[216:219], v[70:73], v[66:69]
	v_mfma_f32_16x16x32_bf16 v[66:69], v[182:185], v[82:85], v[134:137]
	v_mfma_f32_16x16x32_bf16 v[134:137], v[186:189], v[86:89], v[66:69]
	v_mfma_f32_16x16x32_bf16 v[66:69], v[212:215], v[82:85], v[130:133]
	v_mfma_f32_16x16x32_bf16 v[130:133], v[216:219], v[86:89], v[66:69]
	v_mfma_f32_16x16x32_bf16 v[66:69], v[182:185], v[220:223], v[118:121]
	v_mfma_f32_16x16x32_bf16 v[118:121], v[186:189], v[224:227], v[66:69]
	v_mfma_f32_16x16x32_bf16 v[66:69], v[212:215], v[220:223], v[114:117]
	v_mfma_f32_16x16x32_bf16 v[114:117], v[216:219], v[224:227], v[66:69]
	v_mfma_f32_16x16x32_bf16 v[66:69], v[182:185], v[228:231], v[102:105]
	v_mfma_f32_16x16x32_bf16 v[102:105], v[186:189], v[232:235], v[66:69]
	v_mfma_f32_16x16x32_bf16 v[66:69], v[212:215], v[228:231], v[98:101]
	v_mfma_f32_16x16x32_bf16 v[150:153], v[186:189], v[70:73], v[150:153]
	v_mfma_f32_16x16x32_bf16 v[98:101], v[216:219], v[232:235], v[66:69]
	s_setprio 0
	s_barrier
; #define PG8_STAGE(bufoff, gbase, voff) do { _Pragma("unroll") for (int _i = 0; _i < 2; ++_i) \
;         __builtin_amdgcn_global_load_lds((const unsigned*)((const char*)(gbase) + (voff)[_i]), (LAS unsigned*)(lds + (bufoff) + ldsw + _i * 8192), 16, 0, 0); } while (0)
; #define PG8_LDA(dst, b, h) do { _Pragma("unroll") for (int m = 0; m < 4; ++m) _Pragma("unroll") for (int k = 0; k < 2; ++k) dst[m][k] = *(const LAS bf16x8*)(lds + PG8_SA(b, h) + aoff + m * 2048 + k * 1024); } while (0)
; #define PG8_MMA(ai, bj, At, Bt) do { __builtin_amdgcn_s_setprio(1); _Pragma("unroll") for (int m = 0; m < 4; ++m) _Pragma("unroll") for (int n = 0; n < 2; ++n) _Pragma("unroll") for (int k = 0; k < 2; ++k) \
;         acc[ai][bj][m][n] = __builtin_amdgcn_mfma_f32_16x16x32_bf16(Bt[n][k], At[m][k], acc[ai][bj][m][n], 0, 0, 0); __builtin_amdgcn_s_setprio(0); } while (0)
; #define PG8_WAIT_V(n) asm volatile("s_waitcnt vmcnt(" #n ")" ::: "memory")
; #define PG8_WAIT_L(n) asm volatile("s_waitcnt lgkmcnt(" #n ")" ::: "memory")
; #define PG8_BAR __builtin_amdgcn_s_barrier()
; #define PG8_SCHED __builtin_amdgcn_sched_barrier(0)
; template <class Epi>
; __device__ __forceinline__ void gemm_phase(LAS unsigned char* lds, const Gemm g, const StaticOrder& S, const Epi& E, const int tid) {
;     ...
;             PG8_WAIT_V(8); PG8_WAIT_L(0); PG8_BAR; PG8_MMA(0, 0, At, B0); PG8_MMA(0, 1, At, B1); PG8_BAR; PG8_SCHED;
;             PG8_LDA(At, 1, 1); PG8_STAGE(PG8_SB(1, 0), b3, voffB); PG8_STAGE(PG8_SB(1, 1), b3 + bhs, voffB); PG8_STAGE(PG8_SA(1, 0), a3, voffA);
;             PG8_WAIT_V(8); PG8_WAIT_L(0); PG8_BAR; PG8_MMA(1, 0, At, B0); PG8_MMA(1, 1, At, B1); PG8_BAR; PG8_SCHED;
	s_add_i32 s34, s52, s36
	v_lshl_add_u64 v[82:83], v[172:173], 0, s[70:71]
	s_mov_b32 m0, s34
	s_nop 0
	ds_read_b128 v[66:69], v199 offset:49152
	global_load_lds_dwordx4 v[82:83], off
	ds_read_b128 v[70:73], v199 offset:50176
	ds_read_b128 v[220:223], v199 offset:51200
	s_add_i32 m0, s34, 0x2000
	s_add_u32 s30, s30, 0x2080
	v_lshl_add_u64 v[82:83], v[174:175], 0, s[70:71]
	s_addc_u32 s31, s31, 0
	s_add_i32 s34, s53, s36
	global_load_lds_dwordx4 v[82:83], off
	ds_read_b128 v[224:227], v199 offset:52224
	ds_read_b128 v[228:231], v199 offset:53248
	v_lshl_add_u64 v[82:83], s[30:31], 0, v[0:1]
	s_mov_b32 m0, s34
	s_nop 0
	global_load_lds_dwordx4 v[82:83], off
	ds_read_b128 v[232:235], v199 offset:54272
	ds_read_b128 v[236:239], v199 offset:55296
	v_lshl_add_u64 v[82:83], s[30:31], 0, v[166:167]
	s_add_i32 m0, s34, 0x2000
	s_nop 0
	global_load_lds_dwordx4 v[82:83], off
	ds_read_b128 v[240:243], v199 offset:56320
	v_lshl_add_u64 v[82:83], v[176:177], 0, s[70:71]
	s_mov_b32 m0, s45
	s_nop 0
	global_load_lds_dwordx4 v[82:83], off
	v_lshl_add_u64 v[82:83], v[200:201], 0, s[70:71]
	s_mov_b32 m0, s46
	s_nop 0
	global_load_lds_dwordx4 v[82:83], off
	s_nop 0
	s_waitcnt vmcnt(8)
	s_waitcnt lgkmcnt(0)
	s_barrier
	s_setprio 1
	s_waitcnt lgkmcnt(0)
	v_mfma_f32_16x16x32_bf16 v[82:85], v[42:45], v[66:69], v[94:97]
	v_mfma_f32_16x16x32_bf16 v[94:97], v[46:49], v[70:73], v[82:85]
	v_mfma_f32_16x16x32_bf16 v[82:85], v[50:53], v[66:69], v[90:93]
	v_mfma_f32_16x16x32_bf16 v[78:81], v[42:45], v[220:223], v[78:81]
	v_mfma_f32_16x16x32_bf16 v[74:77], v[50:53], v[220:223], v[74:77]
	v_mfma_f32_16x16x32_bf16 v[62:65], v[42:45], v[228:231], v[62:65]
	v_mfma_f32_16x16x32_bf16 v[58:61], v[50:53], v[228:231], v[58:61]
	v_mfma_f32_16x16x32_bf16 v[14:17], v[42:45], v[236:239], v[14:17]
	v_mfma_f32_16x16x32_bf16 v[10:13], v[50:53], v[236:239], v[10:13]
	v_mfma_f32_16x16x32_bf16 v[90:93], v[54:57], v[70:73], v[82:85]
	v_mfma_f32_16x16x32_bf16 v[78:81], v[46:49], v[224:227], v[78:81]
	v_mfma_f32_16x16x32_bf16 v[74:77], v[54:57], v[224:227], v[74:77]
	v_mfma_f32_16x16x32_bf16 v[62:65], v[46:49], v[232:235], v[62:65]
	v_mfma_f32_16x16x32_bf16 v[58:61], v[54:57], v[232:235], v[58:61]
	v_mfma_f32_16x16x32_bf16 v[14:17], v[46:49], v[240:243], v[14:17]
	v_mfma_f32_16x16x32_bf16 v[10:13], v[54:57], v[240:243], v[10:13]
	s_setprio 0
	s_setprio 1
	v_mfma_f32_16x16x32_bf16 v[18:21], v[182:185], v[66:69], v[18:21]
	v_mfma_f32_16x16x32_bf16 v[86:89], v[186:189], v[70:73], v[18:21]
	v_mfma_f32_16x16x32_bf16 v[18:21], v[212:215], v[66:69], v[22:25]
	v_mfma_f32_16x16x32_bf16 v[82:85], v[216:219], v[70:73], v[18:21]
	v_mfma_f32_16x16x32_bf16 v[18:21], v[182:185], v[220:223], v[26:29]
	v_mfma_f32_16x16x32_bf16 v[70:73], v[186:189], v[224:227], v[18:21]
	v_mfma_f32_16x16x32_bf16 v[18:21], v[212:215], v[220:223], v[30:33]
	v_mfma_f32_16x16x32_bf16 v[66:69], v[216:219], v[224:227], v[18:21]
	v_mfma_f32_16x16x32_bf16 v[18:21], v[182:185], v[228:231], v[38:41]
	v_mfma_f32_16x16x32_bf16 v[38:41], v[186:189], v[232:235], v[18:21]
	v_mfma_f32_16x16x32_bf16 v[18:21], v[212:215], v[228:231], v[34:37]
	v_mfma_f32_16x16x32_bf16 v[6:9], v[182:185], v[236:239], v[6:9]
	v_mfma_f32_16x16x32_bf16 v[2:5], v[212:215], v[236:239], v[2:5]
	v_mfma_f32_16x16x32_bf16 v[34:37], v[216:219], v[232:235], v[18:21]
	v_mfma_f32_16x16x32_bf16 v[6:9], v[186:189], v[240:243], v[6:9]
	v_mfma_f32_16x16x32_bf16 v[2:5], v[216:219], v[240:243], v[2:5]
	s_setprio 0
	s_barrier
	s_add_i32 s51, s51, 2
	s_add_u32 s49, s49, 0x100
	s_addc_u32 s50, s50, 0
	s_add_u32 s28, s28, 0x100
	s_addc_u32 s29, s29, 0
	s_cmp_gt_u32 s51, 5
	s_cbranch_scc0 .LBB0_206
	s_and_b64 vcc, exec, s[12:13]
	s_cbranch_vccz .LBB0_209
	s_barrier

; #define PG8_STAGE(bufoff, gbase, voff) do { _Pragma("unroll") for (int _i = 0; _i < 2; ++_i) \
;         __builtin_amdgcn_global_load_lds((const unsigned*)((const char*)(gbase) + (voff)[_i]), (LAS unsigned*)(lds + (bufoff) + ldsw + _i * 8192), 16, 0, 0); } while (0)
; #define PG8_LDA(dst, b, h) do { _Pragma("unroll") for (int m = 0; m < 4; ++m) _Pragma("unroll") for (int k = 0; k < 2; ++k) dst[m][k] = *(const LAS bf16x8*)(lds + PG8_SA(b, h) + aoff + m * 2048 + k * 1024); } while (0)
; #define PG8_LDB(dst, b, h) do { _Pragma("unroll") for (int n = 0; n < 2; ++n) _Pragma("unroll") for (int k = 0; k < 2; ++k) dst[n][k] = *(const LAS bf16x8*)(lds + PG8_SB(b, h) + boff + n * 2048 + k * 1024); } while (0)
; #define PG8_WAIT_V(n) asm volatile("s_waitcnt vmcnt(" #n ")" ::: "memory")
; #define PG8_WAIT_L(n) asm volatile("s_waitcnt lgkmcnt(" #n ")" ::: "memory")
; #define PG8_BAR __builtin_amdgcn_s_barrier()
; #define PG8_SCHED __builtin_amdgcn_sched_barrier(0)
; template <class Epi>
; __device__ __forceinline__ void gemm_phase(LAS unsigned char* lds, const Gemm g, const StaticOrder& S, const Epi& E, const int tid) {
;     ...
;         for (int t = 0; t < ntt; t += 2) {
;             const bool last = (t == ntt - 2);
;             const bool s1 = Epi::TWO && (t >= nt), s2 = Epi::TWO && (t + 2 >= nt);
;             const char* a1 = (s1 ? cA2 + (size_t)(t - nt + 1) * kstep : cA + (size_t)(t + 1) * kstep);
;             const char* a2 = last ? nA : (s2 ? cA2 + (size_t)(t + 2 - nt) * kstep : cA + (size_t)(t + 2) * kstep);
;             const char* b2 = last ? nB : (s2 ? cB2 + (size_t)(t + 2 - nt) * kstep : cB + (size_t)(t + 2) * kstep);
;             const char* a3 = a2 + kstep; const char* b3 = b2 + kstep;
;             if constexpr (Epi::TWO) { if (t == nt) E.mid(acc, cur, wr, wc, fr, fq); }
;             if constexpr (SP2) {
;             PG8_LDB(B0, 0, 0); PG8_LDB(B1, 0, 1); PG8_SCHED; PG8_LDA(At, 0, 0); PG8_STAGE(PG8_SA(1, 1), a1 + hstep, voffA);
;             PG8_WAIT_V(8); PG8_WAIT_L(0); PG8_BAR; PG8_MMA(0, 0, At, B0); PG8_MMA(0, 1, At, B1); PG8_BAR; PG8_SCHED;
;             PG8_LDA(At, 0, 1); PG8_STAGE(PG8_SB(0, 0), b2, voffB); PG8_STAGE(PG8_SB(0, 1), b2 + bhs, voffB); PG8_STAGE(PG8_SA(0, 0), a2, voffA);
;             PG8_WAIT_V(8); PG8_WAIT_L(0); PG8_BAR; PG8_MMA(1, 0, At, B0); PG8_MMA(1, 1, At, B1); PG8_BAR; PG8_SCHED;
.LBB0_261:
	s_add_u32 s30, s28, 0xfff80080
	s_addc_u32 s31, s29, -1
	s_add_i32 s49, 0, 0x10000
	s_cmp_eq_u32 s48, 28
	s_cselect_b32 s35, s19, s31
	s_cselect_b32 s34, s44, s30
	v_add_u32_e32 v142, s49, v149
	s_cselect_b32 s31, s17, s47
	s_cselect_b32 s30, s45, s46
	s_add_i32 s52, 0, 0x14000
	ds_read_b128 v[156:159], v142
	ds_read_b128 v[160:163], v142 offset:1024
	ds_read_b128 v[164:167], v142 offset:2048
	ds_read_b128 v[178:181], v142 offset:3072
	v_add_u32_e32 v142, s52, v149
	ds_read_b128 v[182:185], v142
	ds_read_b128 v[186:189], v142 offset:1024
	ds_read_b128 v[190:193], v142 offset:2048
	ds_read_b128 v[194:197], v142 offset:3072
	v_lshl_add_u64 v[142:143], s[28:29], 0, v[140:141]
	s_add_i32 m0, s2, 0xc000
	ds_read_b128 v[198:201], v154
	global_load_lds_dwordx4 v[142:143], off
	ds_read_b128 v[212:215], v154 offset:1024
	ds_read_b128 v[216:219], v154 offset:2048
	v_lshl_add_u64 v[142:143], s[28:29], 0, v[138:139]
	s_add_i32 m0, s2, 0xe000
	s_nop 0
	global_load_lds_dwordx4 v[142:143], off
	ds_read_b128 v[220:223], v154 offset:3072
	ds_read_b128 v[224:227], v154 offset:4096
	ds_read_b128 v[228:231], v154 offset:5120
	ds_read_b128 v[232:235], v154 offset:6144
	ds_read_b128 v[236:239], v154 offset:7168
	s_nop 0
	s_waitcnt vmcnt(8)
	s_waitcnt lgkmcnt(0)
	s_barrier
	s_setprio 1
	s_waitcnt lgkmcnt(0)
	v_mfma_f32_16x16x32_bf16 v[126:129], v[156:159], v[198:201], v[126:129]
	v_mfma_f32_16x16x32_bf16 v[122:125], v[164:167], v[198:201], v[122:125]
	v_mfma_f32_16x16x32_bf16 v[110:113], v[156:159], v[216:219], v[110:113]
	v_mfma_f32_16x16x32_bf16 v[106:109], v[164:167], v[216:219], v[106:109]
	v_mfma_f32_16x16x32_bf16 v[94:97], v[156:159], v[224:227], v[94:97]
	v_mfma_f32_16x16x32_bf16 v[90:93], v[164:167], v[224:227], v[90:93]
	v_mfma_f32_16x16x32_bf16 v[78:81], v[156:159], v[232:235], v[78:81]
	v_mfma_f32_16x16x32_bf16 v[74:77], v[164:167], v[232:235], v[74:77]
	v_mfma_f32_16x16x32_bf16 v[126:129], v[160:163], v[212:215], v[126:129]
	v_mfma_f32_16x16x32_bf16 v[122:125], v[178:181], v[212:215], v[122:125]
	v_mfma_f32_16x16x32_bf16 v[110:113], v[160:163], v[220:223], v[110:113]
	v_mfma_f32_16x16x32_bf16 v[106:109], v[178:181], v[220:223], v[106:109]
	v_mfma_f32_16x16x32_bf16 v[94:97], v[160:163], v[228:231], v[94:97]
	v_mfma_f32_16x16x32_bf16 v[90:93], v[178:181], v[228:231], v[90:93]
	v_mfma_f32_16x16x32_bf16 v[78:81], v[160:163], v[236:239], v[78:81]
	v_mfma_f32_16x16x32_bf16 v[74:77], v[178:181], v[236:239], v[74:77]
	s_setprio 0
	s_setprio 1
	v_mfma_f32_16x16x32_bf16 v[118:121], v[182:185], v[198:201], v[118:121]
	v_mfma_f32_16x16x32_bf16 v[114:117], v[190:193], v[198:201], v[114:117]
	v_mfma_f32_16x16x32_bf16 v[102:105], v[182:185], v[216:219], v[102:105]
	v_mfma_f32_16x16x32_bf16 v[98:101], v[190:193], v[216:219], v[98:101]
	v_mfma_f32_16x16x32_bf16 v[86:89], v[182:185], v[224:227], v[86:89]
	v_mfma_f32_16x16x32_bf16 v[82:85], v[190:193], v[224:227], v[82:85]
	v_mfma_f32_16x16x32_bf16 v[70:73], v[182:185], v[232:235], v[70:73]
	v_mfma_f32_16x16x32_bf16 v[66:69], v[190:193], v[232:235], v[66:69]
	v_mfma_f32_16x16x32_bf16 v[118:121], v[186:189], v[212:215], v[118:121]
	v_mfma_f32_16x16x32_bf16 v[114:117], v[194:197], v[212:215], v[114:117]
	v_mfma_f32_16x16x32_bf16 v[102:105], v[186:189], v[220:223], v[102:105]
	v_mfma_f32_16x16x32_bf16 v[98:101], v[194:197], v[220:223], v[98:101]
	v_mfma_f32_16x16x32_bf16 v[86:89], v[186:189], v[228:231], v[86:89]
	v_mfma_f32_16x16x32_bf16 v[82:85], v[194:197], v[228:231], v[82:85]
	v_mfma_f32_16x16x32_bf16 v[70:73], v[186:189], v[236:239], v[70:73]
	v_mfma_f32_16x16x32_bf16 v[66:69], v[194:197], v[236:239], v[66:69]
	s_setprio 0
	s_barrier
	s_add_i32 s49, s49, s36
	v_lshl_add_u64 v[142:143], s[30:31], 0, v[0:1]
	s_mov_b32 m0, s49
	ds_read_b128 v[198:201], v154 offset:16384
	global_load_lds_dwordx4 v[142:143], off
	ds_read_b128 v[212:215], v154 offset:17408
	ds_read_b128 v[216:219], v154 offset:18432
	s_add_i32 m0, s49, 0x2000
	s_add_u32 s50, s30, 0x8000
	v_lshl_add_u64 v[168:169], s[30:31], 0, v[134:135]
	s_addc_u32 s51, s31, 0
	s_add_i32 s49, s52, s36
	global_load_lds_dwordx4 v[168:169], off
	ds_read_b128 v[220:223], v154 offset:19456
	ds_read_b128 v[224:227], v154 offset:20480
	v_lshl_add_u64 v[172:173], s[50:51], 0, v[0:1]
	s_mov_b32 m0, s49
	v_lshl_add_u64 v[174:175], s[34:35], 0, v[132:133]
	global_load_lds_dwordx4 v[172:173], off
	ds_read_b128 v[228:231], v154 offset:21504
	ds_read_b128 v[232:235], v154 offset:22528
	v_lshl_add_u64 v[172:173], s[50:51], 0, v[134:135]
	s_add_i32 m0, s49, 0x2000
	s_nop 0
	global_load_lds_dwordx4 v[172:173], off
	ds_read_b128 v[236:239], v154 offset:23552
	v_lshl_add_u64 v[172:173], s[34:35], 0, v[130:131]
	s_mov_b32 m0, s2
	s_nop 0
	global_load_lds_dwordx4 v[172:173], off
	s_mov_b32 m0, s27
	s_nop 0
	global_load_lds_dwordx4 v[174:175], off
	s_nop 0
	s_waitcnt vmcnt(8)
	s_waitcnt lgkmcnt(0)
	s_barrier
; #define PG8_STAGE(bufoff, gbase, voff) do { _Pragma("unroll") for (int _i = 0; _i < 2; ++_i) \
;         __builtin_amdgcn_global_load_lds((const unsigned*)((const char*)(gbase) + (voff)[_i]), (LAS unsigned*)(lds + (bufoff) + ldsw + _i * 8192), 16, 0, 0); } while (0)
; #define PG8_LDA(dst, b, h) do { _Pragma("unroll") for (int m = 0; m < 4; ++m) _Pragma("unroll") for (int k = 0; k < 2; ++k) dst[m][k] = *(const LAS bf16x8*)(lds + PG8_SA(b, h) + aoff + m * 2048 + k * 1024); } while (0)
; #define PG8_LDB(dst, b, h) do { _Pragma("unroll") for (int n = 0; n < 2; ++n) _Pragma("unroll") for (int k = 0; k < 2; ++k) dst[n][k] = *(const LAS bf16x8*)(lds + PG8_SB(b, h) + boff + n * 2048 + k * 1024); } while (0)
; #define PG8_MMA(ai, bj, At, Bt) do { __builtin_amdgcn_s_setprio(1); _Pragma("unroll") for (int m = 0; m < 4; ++m) _Pragma("unroll") for (int n = 0; n < 2; ++n) _Pragma("unroll") for (int k = 0; k < 2; ++k) \
;         acc[ai][bj][m][n] = __builtin_amdgcn_mfma_f32_16x16x32_bf16(Bt[n][k], At[m][k], acc[ai][bj][m][n], 0, 0, 0); __builtin_amdgcn_s_setprio(0); } while (0)
; #define PG8_WAIT_V(n) asm volatile("s_waitcnt vmcnt(" #n ")" ::: "memory")
; #define PG8_WAIT_L(n) asm volatile("s_waitcnt lgkmcnt(" #n ")" ::: "memory")
; #define PG8_BAR __builtin_amdgcn_s_barrier()
; #define PG8_SCHED __builtin_amdgcn_sched_barrier(0)
; template <class Epi>
; __device__ __forceinline__ void gemm_phase(LAS unsigned char* lds, const Gemm g, const StaticOrder& S, const Epi& E, const int tid) {
;     ...
;             PG8_LDA(At, 0, 1); PG8_STAGE(PG8_SB(0, 0), b2, voffB); PG8_STAGE(PG8_SB(0, 1), b2 + bhs, voffB); PG8_STAGE(PG8_SA(0, 0), a2, voffA);
;             PG8_WAIT_V(8); PG8_WAIT_L(0); PG8_BAR; PG8_MMA(1, 0, At, B0); PG8_MMA(1, 1, At, B1); PG8_BAR; PG8_SCHED;
;             PG8_LDB(B0, 1, 0); PG8_LDB(B1, 1, 1); PG8_SCHED; PG8_LDA(At, 1, 0); PG8_STAGE(PG8_SA(0, 1), a2 + hstep, voffA);
;             PG8_WAIT_V(8); PG8_WAIT_L(0); PG8_BAR; PG8_MMA(0, 0, At, B0); PG8_MMA(0, 1, At, B1); PG8_BAR; PG8_SCHED;
	s_setprio 1
	s_waitcnt lgkmcnt(0)
	v_mfma_f32_16x16x32_bf16 v[62:65], v[156:159], v[198:201], v[62:65]
	v_mfma_f32_16x16x32_bf16 v[58:61], v[164:167], v[198:201], v[58:61]
	v_mfma_f32_16x16x32_bf16 v[46:49], v[156:159], v[216:219], v[46:49]
	v_mfma_f32_16x16x32_bf16 v[42:45], v[164:167], v[216:219], v[42:45]
	v_mfma_f32_16x16x32_bf16 v[30:33], v[156:159], v[224:227], v[30:33]
	v_mfma_f32_16x16x32_bf16 v[26:29], v[164:167], v[224:227], v[26:29]
	v_mfma_f32_16x16x32_bf16 v[14:17], v[156:159], v[232:235], v[14:17]
	v_mfma_f32_16x16x32_bf16 v[10:13], v[164:167], v[232:235], v[10:13]
	v_mfma_f32_16x16x32_bf16 v[62:65], v[160:163], v[212:215], v[62:65]
	v_mfma_f32_16x16x32_bf16 v[58:61], v[178:181], v[212:215], v[58:61]
	v_mfma_f32_16x16x32_bf16 v[46:49], v[160:163], v[220:223], v[46:49]
	v_mfma_f32_16x16x32_bf16 v[42:45], v[178:181], v[220:223], v[42:45]
	v_mfma_f32_16x16x32_bf16 v[30:33], v[160:163], v[228:231], v[30:33]
	v_mfma_f32_16x16x32_bf16 v[26:29], v[178:181], v[228:231], v[26:29]
	v_mfma_f32_16x16x32_bf16 v[14:17], v[160:163], v[236:239], v[14:17]
	v_mfma_f32_16x16x32_bf16 v[10:13], v[178:181], v[236:239], v[10:13]
	s_setprio 0
	s_setprio 1
	v_mfma_f32_16x16x32_bf16 v[54:57], v[182:185], v[198:201], v[54:57]
	v_mfma_f32_16x16x32_bf16 v[50:53], v[190:193], v[198:201], v[50:53]
	v_mfma_f32_16x16x32_bf16 v[38:41], v[182:185], v[216:219], v[38:41]
	v_mfma_f32_16x16x32_bf16 v[34:37], v[190:193], v[216:219], v[34:37]
	v_mfma_f32_16x16x32_bf16 v[22:25], v[182:185], v[224:227], v[22:25]
	v_mfma_f32_16x16x32_bf16 v[18:21], v[190:193], v[224:227], v[18:21]
	v_mfma_f32_16x16x32_bf16 v[6:9], v[182:185], v[232:235], v[6:9]
	v_mfma_f32_16x16x32_bf16 v[2:5], v[190:193], v[232:235], v[2:5]
	v_mfma_f32_16x16x32_bf16 v[54:57], v[186:189], v[212:215], v[54:57]
	v_mfma_f32_16x16x32_bf16 v[50:53], v[194:197], v[212:215], v[50:53]
	v_mfma_f32_16x16x32_bf16 v[38:41], v[186:189], v[220:223], v[38:41]
	v_mfma_f32_16x16x32_bf16 v[34:37], v[194:197], v[220:223], v[34:37]
	v_mfma_f32_16x16x32_bf16 v[22:25], v[186:189], v[228:231], v[22:25]
	v_mfma_f32_16x16x32_bf16 v[18:21], v[194:197], v[228:231], v[18:21]
	v_mfma_f32_16x16x32_bf16 v[6:9], v[186:189], v[236:239], v[6:9]
	v_mfma_f32_16x16x32_bf16 v[2:5], v[194:197], v[236:239], v[2:5]
	s_setprio 0
	s_barrier
	s_add_i32 s49, 0, 0x18000
	v_add_u32_e32 v155, s49, v149
	s_add_i32 s50, 0, 0x1c000
	ds_read_b128 v[156:159], v155
	ds_read_b128 v[160:163], v155 offset:1024
	ds_read_b128 v[164:167], v155 offset:2048
	ds_read_b128 v[178:181], v155 offset:3072
	v_add_u32_e32 v155, s50, v149
	ds_read_b128 v[182:185], v155
	ds_read_b128 v[186:189], v155 offset:1024
	ds_read_b128 v[190:193], v155 offset:2048
	ds_read_b128 v[194:197], v155 offset:3072
	s_add_u32 s34, s34, 0x80000
	s_addc_u32 s35, s35, 0
	s_mov_b32 m0, s37
	v_lshl_add_u64 v[176:177], s[34:35], 0, v[130:131]
	ds_read_b128 v[198:201], v154 offset:32768
	global_load_lds_dwordx4 v[176:177], off
	ds_read_b128 v[212:215], v154 offset:33792
	ds_read_b128 v[216:219], v154 offset:34816
	v_lshl_add_u64 v[176:177], s[34:35], 0, v[132:133]
	s_mov_b32 m0, s38
	s_nop 0
	global_load_lds_dwordx4 v[176:177], off
	ds_read_b128 v[220:223], v154 offset:35840
	ds_read_b128 v[224:227], v154 offset:36864
	ds_read_b128 v[228:231], v154 offset:37888
	ds_read_b128 v[232:235], v154 offset:38912
	ds_read_b128 v[236:239], v154 offset:39936
	s_nop 0
	s_waitcnt vmcnt(8)
	s_waitcnt lgkmcnt(0)
	s_barrier
	s_setprio 1
	s_waitcnt lgkmcnt(0)
	v_mfma_f32_16x16x32_bf16 v[126:129], v[156:159], v[198:201], v[126:129]
	v_mfma_f32_16x16x32_bf16 v[122:125], v[164:167], v[198:201], v[122:125]
	v_mfma_f32_16x16x32_bf16 v[110:113], v[156:159], v[216:219], v[110:113]
	v_mfma_f32_16x16x32_bf16 v[106:109], v[164:167], v[216:219], v[106:109]
	v_mfma_f32_16x16x32_bf16 v[94:97], v[156:159], v[224:227], v[94:97]
	v_mfma_f32_16x16x32_bf16 v[90:93], v[164:167], v[224:227], v[90:93]
	v_mfma_f32_16x16x32_bf16 v[78:81], v[156:159], v[232:235], v[78:81]
	v_mfma_f32_16x16x32_bf16 v[74:77], v[164:167], v[232:235], v[74:77]
	v_mfma_f32_16x16x32_bf16 v[126:129], v[160:163], v[212:215], v[126:129]
	v_mfma_f32_16x16x32_bf16 v[122:125], v[178:181], v[212:215], v[122:125]
	v_mfma_f32_16x16x32_bf16 v[110:113], v[160:163], v[220:223], v[110:113]
	v_mfma_f32_16x16x32_bf16 v[106:109], v[178:181], v[220:223], v[106:109]
	v_mfma_f32_16x16x32_bf16 v[94:97], v[160:163], v[228:231], v[94:97]
	v_mfma_f32_16x16x32_bf16 v[90:93], v[178:181], v[228:231], v[90:93]
	v_mfma_f32_16x16x32_bf16 v[78:81], v[160:163], v[236:239], v[78:81]
	v_mfma_f32_16x16x32_bf16 v[74:77], v[178:181], v[236:239], v[74:77]
	s_setprio 0
	s_setprio 1
	v_mfma_f32_16x16x32_bf16 v[118:121], v[182:185], v[198:201], v[118:121]
	v_mfma_f32_16x16x32_bf16 v[114:117], v[190:193], v[198:201], v[114:117]
	v_mfma_f32_16x16x32_bf16 v[102:105], v[182:185], v[216:219], v[102:105]
	v_mfma_f32_16x16x32_bf16 v[98:101], v[190:193], v[216:219], v[98:101]
	v_mfma_f32_16x16x32_bf16 v[86:89], v[182:185], v[224:227], v[86:89]
	v_mfma_f32_16x16x32_bf16 v[82:85], v[190:193], v[224:227], v[82:85]
	v_mfma_f32_16x16x32_bf16 v[70:73], v[182:185], v[232:235], v[70:73]
	v_mfma_f32_16x16x32_bf16 v[66:69], v[190:193], v[232:235], v[66:69]
	v_mfma_f32_16x16x32_bf16 v[118:121], v[186:189], v[212:215], v[118:121]
	v_mfma_f32_16x16x32_bf16 v[114:117], v[194:197], v[212:215], v[114:117]
	v_mfma_f32_16x16x32_bf16 v[102:105], v[186:189], v[220:223], v[102:105]
	v_mfma_f32_16x16x32_bf16 v[98:101], v[194:197], v[220:223], v[98:101]
	v_mfma_f32_16x16x32_bf16 v[86:89], v[186:189], v[228:231], v[86:89]
	v_mfma_f32_16x16x32_bf16 v[82:85], v[194:197], v[228:231], v[82:85]
	v_mfma_f32_16x16x32_bf16 v[70:73], v[186:189], v[236:239], v[70:73]
	v_mfma_f32_16x16x32_bf16 v[66:69], v[194:197], v[236:239], v[66:69]
	s_setprio 0
	s_barrier
; #define PG8_STAGE(bufoff, gbase, voff) do { _Pragma("unroll") for (int _i = 0; _i < 2; ++_i) \
;         __builtin_amdgcn_global_load_lds((const unsigned*)((const char*)(gbase) + (voff)[_i]), (LAS unsigned*)(lds + (bufoff) + ldsw + _i * 8192), 16, 0, 0); } while (0)
; #define PG8_LDA(dst, b, h) do { _Pragma("unroll") for (int m = 0; m < 4; ++m) _Pragma("unroll") for (int k = 0; k < 2; ++k) dst[m][k] = *(const LAS bf16x8*)(lds + PG8_SA(b, h) + aoff + m * 2048 + k * 1024); } while (0)
; #define PG8_MMA(ai, bj, At, Bt) do { __builtin_amdgcn_s_setprio(1); _Pragma("unroll") for (int m = 0; m < 4; ++m) _Pragma("unroll") for (int n = 0; n < 2; ++n) _Pragma("unroll") for (int k = 0; k < 2; ++k) \
;         acc[ai][bj][m][n] = __builtin_amdgcn_mfma_f32_16x16x32_bf16(Bt[n][k], At[m][k], acc[ai][bj][m][n], 0, 0, 0); __builtin_amdgcn_s_setprio(0); } while (0)
; #define PG8_WAIT_V(n) asm volatile("s_waitcnt vmcnt(" #n ")" ::: "memory")
; #define PG8_WAIT_L(n) asm volatile("s_waitcnt lgkmcnt(" #n ")" ::: "memory")
; #define PG8_BAR __builtin_amdgcn_s_barrier()
; #define PG8_SCHED __builtin_amdgcn_sched_barrier(0)
; template <class Epi>
; __device__ __forceinline__ void gemm_phase(LAS unsigned char* lds, const Gemm g, const StaticOrder& S, const Epi& E, const int tid) {
;     ...
;             PG8_WAIT_V(8); PG8_WAIT_L(0); PG8_BAR; PG8_MMA(0, 0, At, B0); PG8_MMA(0, 1, At, B1); PG8_BAR; PG8_SCHED;
;             PG8_LDA(At, 1, 1); PG8_STAGE(PG8_SB(1, 0), b3, voffB); PG8_STAGE(PG8_SB(1, 1), b3 + bhs, voffB); PG8_STAGE(PG8_SA(1, 0), a3, voffA);
;             PG8_WAIT_V(8); PG8_WAIT_L(0); PG8_BAR; PG8_MMA(1, 0, At, B0); PG8_MMA(1, 1, At, B1); PG8_BAR; PG8_SCHED;
	s_add_i32 s34, s49, s36
	v_lshl_add_u64 v[142:143], v[142:143], 0, s[70:71]
	s_mov_b32 m0, s34
	ds_read_b128 v[198:201], v154 offset:49152
	global_load_lds_dwordx4 v[142:143], off
	ds_read_b128 v[212:215], v154 offset:50176
	ds_read_b128 v[216:219], v154 offset:51200
	s_add_i32 m0, s34, 0x2000
	s_add_u32 s30, s30, 0x8080
	v_lshl_add_u64 v[142:143], v[168:169], 0, s[70:71]
	s_addc_u32 s31, s31, 0
	s_add_i32 s34, s50, s36
	global_load_lds_dwordx4 v[142:143], off
	ds_read_b128 v[220:223], v154 offset:52224
	ds_read_b128 v[224:227], v154 offset:53248
	v_lshl_add_u64 v[142:143], s[30:31], 0, v[0:1]
	s_mov_b32 m0, s34
	s_nop 0
	global_load_lds_dwordx4 v[142:143], off
	ds_read_b128 v[228:231], v154 offset:54272
	ds_read_b128 v[232:235], v154 offset:55296
	v_lshl_add_u64 v[142:143], s[30:31], 0, v[134:135]
	s_add_i32 m0, s34, 0x2000
	s_nop 0
	global_load_lds_dwordx4 v[142:143], off
	ds_read_b128 v[236:239], v154 offset:56320
	v_lshl_add_u64 v[142:143], v[172:173], 0, s[70:71]
	s_mov_b32 m0, s39
	s_nop 0
	global_load_lds_dwordx4 v[142:143], off
	v_lshl_add_u64 v[142:143], v[174:175], 0, s[70:71]
	s_mov_b32 m0, s40
	s_nop 0
	global_load_lds_dwordx4 v[142:143], off
	s_waitcnt vmcnt(8)
	s_waitcnt lgkmcnt(0)
	s_barrier
	s_setprio 1
	s_waitcnt lgkmcnt(0)
	v_mfma_f32_16x16x32_bf16 v[62:65], v[156:159], v[198:201], v[62:65]
	v_mfma_f32_16x16x32_bf16 v[58:61], v[164:167], v[198:201], v[58:61]
	v_mfma_f32_16x16x32_bf16 v[46:49], v[156:159], v[216:219], v[46:49]
	v_mfma_f32_16x16x32_bf16 v[42:45], v[164:167], v[216:219], v[42:45]
	v_mfma_f32_16x16x32_bf16 v[30:33], v[156:159], v[224:227], v[30:33]
	v_mfma_f32_16x16x32_bf16 v[26:29], v[164:167], v[224:227], v[26:29]
	v_mfma_f32_16x16x32_bf16 v[14:17], v[156:159], v[232:235], v[14:17]
	v_mfma_f32_16x16x32_bf16 v[10:13], v[164:167], v[232:235], v[10:13]
	v_mfma_f32_16x16x32_bf16 v[62:65], v[160:163], v[212:215], v[62:65]
	v_mfma_f32_16x16x32_bf16 v[58:61], v[178:181], v[212:215], v[58:61]
	v_mfma_f32_16x16x32_bf16 v[46:49], v[160:163], v[220:223], v[46:49]
	v_mfma_f32_16x16x32_bf16 v[42:45], v[178:181], v[220:223], v[42:45]
	v_mfma_f32_16x16x32_bf16 v[30:33], v[160:163], v[228:231], v[30:33]
	v_mfma_f32_16x16x32_bf16 v[26:29], v[178:181], v[228:231], v[26:29]
	v_mfma_f32_16x16x32_bf16 v[14:17], v[160:163], v[236:239], v[14:17]
	v_mfma_f32_16x16x32_bf16 v[10:13], v[178:181], v[236:239], v[10:13]
	s_setprio 0
	s_setprio 1
	v_mfma_f32_16x16x32_bf16 v[54:57], v[182:185], v[198:201], v[54:57]
	v_mfma_f32_16x16x32_bf16 v[50:53], v[190:193], v[198:201], v[50:53]
	v_mfma_f32_16x16x32_bf16 v[38:41], v[182:185], v[216:219], v[38:41]
	v_mfma_f32_16x16x32_bf16 v[34:37], v[190:193], v[216:219], v[34:37]
	v_mfma_f32_16x16x32_bf16 v[22:25], v[182:185], v[224:227], v[22:25]
	v_mfma_f32_16x16x32_bf16 v[18:21], v[190:193], v[224:227], v[18:21]
	v_mfma_f32_16x16x32_bf16 v[6:9], v[182:185], v[232:235], v[6:9]
	v_mfma_f32_16x16x32_bf16 v[2:5], v[190:193], v[232:235], v[2:5]
	v_mfma_f32_16x16x32_bf16 v[54:57], v[186:189], v[212:215], v[54:57]
	v_mfma_f32_16x16x32_bf16 v[50:53], v[194:197], v[212:215], v[50:53]
	v_mfma_f32_16x16x32_bf16 v[38:41], v[186:189], v[220:223], v[38:41]
	v_mfma_f32_16x16x32_bf16 v[34:37], v[194:197], v[220:223], v[34:37]
	v_mfma_f32_16x16x32_bf16 v[22:25], v[186:189], v[228:231], v[22:25]
	v_mfma_f32_16x16x32_bf16 v[18:21], v[194:197], v[228:231], v[18:21]
	v_mfma_f32_16x16x32_bf16 v[6:9], v[186:189], v[236:239], v[6:9]
	v_mfma_f32_16x16x32_bf16 v[2:5], v[194:197], v[236:239], v[2:5]
	s_setprio 0
	s_barrier
	s_add_i32 s48, s48, 2
	s_add_u32 s46, s46, 0x100
	s_addc_u32 s47, s47, 0
	s_add_u32 s28, s28, 0x100
	s_addc_u32 s29, s29, 0
	s_cmp_gt_u32 s48, 29
	s_cbranch_scc0 .LBB0_261
	s_and_b64 vcc, exec, s[14:15]
	s_cbranch_vccz .LBB0_264
	s_barrier

; #define PG8_STAGE(bufoff, gbase, voff) do { _Pragma("unroll") for (int _i = 0; _i < 2; ++_i) \
;         __builtin_amdgcn_global_load_lds((const unsigned*)((const char*)(gbase) + (voff)[_i]), (LAS unsigned*)(lds + (bufoff) + ldsw + _i * 8192), 16, 0, 0); } while (0)
; #define PG8_LDA(dst, b, h) do { _Pragma("unroll") for (int m = 0; m < 4; ++m) _Pragma("unroll") for (int k = 0; k < 2; ++k) dst[m][k] = *(const LAS bf16x8*)(lds + PG8_SA(b, h) + aoff + m * 2048 + k * 1024); } while (0)
; #define PG8_LDB(dst, b, h) do { _Pragma("unroll") for (int n = 0; n < 2; ++n) _Pragma("unroll") for (int k = 0; k < 2; ++k) dst[n][k] = *(const LAS bf16x8*)(lds + PG8_SB(b, h) + boff + n * 2048 + k * 1024); } while (0)
; #define PG8_WAIT_V(n) asm volatile("s_waitcnt vmcnt(" #n ")" ::: "memory")
; #define PG8_WAIT_L(n) asm volatile("s_waitcnt lgkmcnt(" #n ")" ::: "memory")
; #define PG8_BAR __builtin_amdgcn_s_barrier()
; #define PG8_SCHED __builtin_amdgcn_sched_barrier(0)
; template <class Epi>
; __device__ __forceinline__ void gemm_phase(LAS unsigned char* lds, const Gemm g, const StaticOrder& S, const Epi& E, const int tid) {
;     ...
;         for (int t = 0; t < ntt; t += 2) {
;             const bool last = (t == ntt - 2);
;             const bool s1 = Epi::TWO && (t >= nt), s2 = Epi::TWO && (t + 2 >= nt);
;             const char* a1 = (s1 ? cA2 + (size_t)(t - nt + 1) * kstep : cA + (size_t)(t + 1) * kstep);
;             const char* a2 = last ? nA : (s2 ? cA2 + (size_t)(t + 2 - nt) * kstep : cA + (size_t)(t + 2) * kstep);
;             const char* b2 = last ? nB : (s2 ? cB2 + (size_t)(t + 2 - nt) * kstep : cB + (size_t)(t + 2) * kstep);
;             const char* a3 = a2 + kstep; const char* b3 = b2 + kstep;
;             if constexpr (Epi::TWO) { if (t == nt) E.mid(acc, cur, wr, wc, fr, fq); }
;             if constexpr (SP2) {
;             PG8_LDB(B0, 0, 0); PG8_LDB(B1, 0, 1); PG8_SCHED; PG8_LDA(At, 0, 0); PG8_STAGE(PG8_SA(1, 1), a1 + hstep, voffA);
;             PG8_WAIT_V(8); PG8_WAIT_L(0); PG8_BAR; PG8_MMA(0, 0, At, B0); PG8_MMA(0, 1, At, B1); PG8_BAR; PG8_SCHED;
;             PG8_LDA(At, 0, 1); PG8_STAGE(PG8_SB(0, 0), b2, voffB); PG8_STAGE(PG8_SB(0, 1), b2 + bhs, voffB); PG8_STAGE(PG8_SA(0, 0), a2, voffA);
;             PG8_WAIT_V(8); PG8_WAIT_L(0); PG8_BAR; PG8_MMA(1, 0, At, B0); PG8_MMA(1, 1, At, B1); PG8_BAR; PG8_SCHED;
.LBB0_314:
	s_add_u32 s40, s6, 0xfff80080
	s_addc_u32 s41, s7, -1
	s_add_i32 s56, 0, 0x10000
	s_cmp_eq_u32 s55, 28
	s_cselect_b32 s43, s27, s41
	s_cselect_b32 s42, s39, s40
	s_cselect_b32 s41, s25, s54
	s_cselect_b32 s40, s52, s53
	s_add_i32 s58, 0, 0x14000
	v_add_u32_e32 v46, s56, v212
	v_add_u32_e32 v70, s58, v212
	ds_read_b128 v[34:37], v46
	ds_read_b128 v[38:41], v46 offset:1024
	ds_read_b128 v[42:45], v46 offset:2048
	ds_read_b128 v[46:49], v46 offset:3072
	ds_read_b128 v[58:61], v70
	ds_read_b128 v[62:65], v70 offset:1024
	ds_read_b128 v[66:69], v70 offset:2048
	ds_read_b128 v[70:73], v70 offset:3072
	v_lshl_add_u64 v[172:173], s[6:7], 0, v[188:189]
	s_add_i32 m0, s44, 0xc000
	ds_read_b128 v[162:165], v220
	global_load_lds_dwordx4 v[172:173], off
	ds_read_b128 v[166:169], v220 offset:1024
	ds_read_b128 v[190:193], v220 offset:2048
	v_lshl_add_u64 v[172:173], s[6:7], 0, v[186:187]
	s_add_i32 m0, s44, 0xe000
	s_nop 0
	global_load_lds_dwordx4 v[172:173], off
	ds_read_b128 v[194:197], v220 offset:3072
	ds_read_b128 v[198:201], v220 offset:4096
	ds_read_b128 v[222:225], v220 offset:5120
	ds_read_b128 v[226:229], v220 offset:6144
	ds_read_b128 v[230:233], v220 offset:7168
	s_waitcnt vmcnt(8)
	s_waitcnt lgkmcnt(0)
	s_barrier
	s_setprio 1
	s_waitcnt lgkmcnt(0)
	v_mfma_f32_16x16x32_bf16 v[158:161], v[34:37], v[162:165], v[158:161]
	v_mfma_f32_16x16x32_bf16 v[154:157], v[42:45], v[162:165], v[154:157]
	v_mfma_f32_16x16x32_bf16 v[142:145], v[34:37], v[190:193], v[142:145]
	v_mfma_f32_16x16x32_bf16 v[138:141], v[42:45], v[190:193], v[138:141]
	v_mfma_f32_16x16x32_bf16 v[126:129], v[34:37], v[198:201], v[126:129]
	v_mfma_f32_16x16x32_bf16 v[122:125], v[42:45], v[198:201], v[122:125]
	v_mfma_f32_16x16x32_bf16 v[110:113], v[34:37], v[226:229], v[110:113]
	v_mfma_f32_16x16x32_bf16 v[106:109], v[42:45], v[226:229], v[106:109]
	v_mfma_f32_16x16x32_bf16 v[158:161], v[38:41], v[166:169], v[158:161]
	v_mfma_f32_16x16x32_bf16 v[154:157], v[46:49], v[166:169], v[154:157]
	v_mfma_f32_16x16x32_bf16 v[142:145], v[38:41], v[194:197], v[142:145]
	v_mfma_f32_16x16x32_bf16 v[138:141], v[46:49], v[194:197], v[138:141]
	v_mfma_f32_16x16x32_bf16 v[126:129], v[38:41], v[222:225], v[126:129]
	v_mfma_f32_16x16x32_bf16 v[122:125], v[46:49], v[222:225], v[122:125]
	v_mfma_f32_16x16x32_bf16 v[110:113], v[38:41], v[230:233], v[110:113]
	v_mfma_f32_16x16x32_bf16 v[106:109], v[46:49], v[230:233], v[106:109]
	s_setprio 0
	s_setprio 1
	v_mfma_f32_16x16x32_bf16 v[150:153], v[58:61], v[162:165], v[150:153]
	v_mfma_f32_16x16x32_bf16 v[146:149], v[66:69], v[162:165], v[146:149]
	v_mfma_f32_16x16x32_bf16 v[134:137], v[58:61], v[190:193], v[134:137]
	v_mfma_f32_16x16x32_bf16 v[130:133], v[66:69], v[190:193], v[130:133]
	v_mfma_f32_16x16x32_bf16 v[118:121], v[58:61], v[198:201], v[118:121]
	v_mfma_f32_16x16x32_bf16 v[114:117], v[66:69], v[198:201], v[114:117]
	v_mfma_f32_16x16x32_bf16 v[102:105], v[58:61], v[226:229], v[102:105]
	v_mfma_f32_16x16x32_bf16 v[98:101], v[66:69], v[226:229], v[98:101]
	v_mfma_f32_16x16x32_bf16 v[150:153], v[62:65], v[166:169], v[150:153]
	v_mfma_f32_16x16x32_bf16 v[146:149], v[70:73], v[166:169], v[146:149]
	v_mfma_f32_16x16x32_bf16 v[134:137], v[62:65], v[194:197], v[134:137]
	v_mfma_f32_16x16x32_bf16 v[130:133], v[70:73], v[194:197], v[130:133]
	v_mfma_f32_16x16x32_bf16 v[118:121], v[62:65], v[222:225], v[118:121]
	v_mfma_f32_16x16x32_bf16 v[114:117], v[70:73], v[222:225], v[114:117]
	v_mfma_f32_16x16x32_bf16 v[102:105], v[62:65], v[230:233], v[102:105]
	v_mfma_f32_16x16x32_bf16 v[98:101], v[70:73], v[230:233], v[98:101]
	s_setprio 0
	s_barrier
	s_add_i32 s56, s56, s33
	v_lshl_add_u64 v[172:173], s[40:41], 0, v[0:1]
	s_mov_b32 m0, s56
	ds_read_b128 v[162:165], v220 offset:16384
	global_load_lds_dwordx4 v[172:173], off
	ds_read_b128 v[166:169], v220 offset:17408
	ds_read_b128 v[190:193], v220 offset:18432
	s_add_i32 m0, s56, 0x2000
	s_add_u32 s56, s40, 0x8000
	v_lshl_add_u64 v[174:175], s[40:41], 0, v[182:183]
	s_addc_u32 s57, s41, 0
	s_add_i32 s58, s58, s33
	global_load_lds_dwordx4 v[174:175], off
	ds_read_b128 v[194:197], v220 offset:19456
	ds_read_b128 v[198:201], v220 offset:20480
	v_lshl_add_u64 v[176:177], s[56:57], 0, v[0:1]
	s_mov_b32 m0, s58
	v_lshl_add_u64 v[238:239], s[42:43], 0, v[180:181]
	global_load_lds_dwordx4 v[176:177], off
	ds_read_b128 v[222:225], v220 offset:21504
	ds_read_b128 v[226:229], v220 offset:22528
	v_lshl_add_u64 v[176:177], s[56:57], 0, v[182:183]
	s_add_i32 m0, s58, 0x2000
	s_nop 0
	global_load_lds_dwordx4 v[176:177], off
	ds_read_b128 v[230:233], v220 offset:23552
	v_lshl_add_u64 v[176:177], s[42:43], 0, v[178:179]
	s_mov_b32 m0, s44
	s_nop 0
	global_load_lds_dwordx4 v[176:177], off
	s_mov_b32 m0, s45
	s_nop 0
	global_load_lds_dwordx4 v[238:239], off
	s_nop 0
	s_waitcnt vmcnt(8)
	s_waitcnt lgkmcnt(0)
	s_barrier
; #define PG8_STAGE(bufoff, gbase, voff) do { _Pragma("unroll") for (int _i = 0; _i < 2; ++_i) \
;         __builtin_amdgcn_global_load_lds((const unsigned*)((const char*)(gbase) + (voff)[_i]), (LAS unsigned*)(lds + (bufoff) + ldsw + _i * 8192), 16, 0, 0); } while (0)
; #define PG8_LDA(dst, b, h) do { _Pragma("unroll") for (int m = 0; m < 4; ++m) _Pragma("unroll") for (int k = 0; k < 2; ++k) dst[m][k] = *(const LAS bf16x8*)(lds + PG8_SA(b, h) + aoff + m * 2048 + k * 1024); } while (0)
; #define PG8_LDB(dst, b, h) do { _Pragma("unroll") for (int n = 0; n < 2; ++n) _Pragma("unroll") for (int k = 0; k < 2; ++k) dst[n][k] = *(const LAS bf16x8*)(lds + PG8_SB(b, h) + boff + n * 2048 + k * 1024); } while (0)
; #define PG8_MMA(ai, bj, At, Bt) do { __builtin_amdgcn_s_setprio(1); _Pragma("unroll") for (int m = 0; m < 4; ++m) _Pragma("unroll") for (int n = 0; n < 2; ++n) _Pragma("unroll") for (int k = 0; k < 2; ++k) \
;         acc[ai][bj][m][n] = __builtin_amdgcn_mfma_f32_16x16x32_bf16(Bt[n][k], At[m][k], acc[ai][bj][m][n], 0, 0, 0); __builtin_amdgcn_s_setprio(0); } while (0)
; #define PG8_WAIT_V(n) asm volatile("s_waitcnt vmcnt(" #n ")" ::: "memory")
; #define PG8_WAIT_L(n) asm volatile("s_waitcnt lgkmcnt(" #n ")" ::: "memory")
; #define PG8_BAR __builtin_amdgcn_s_barrier()
; #define PG8_SCHED __builtin_amdgcn_sched_barrier(0)
; template <class Epi>
; __device__ __forceinline__ void gemm_phase(LAS unsigned char* lds, const Gemm g, const StaticOrder& S, const Epi& E, const int tid) {
;     ...
;             PG8_LDA(At, 0, 1); PG8_STAGE(PG8_SB(0, 0), b2, voffB); PG8_STAGE(PG8_SB(0, 1), b2 + bhs, voffB); PG8_STAGE(PG8_SA(0, 0), a2, voffA);
;             PG8_WAIT_V(8); PG8_WAIT_L(0); PG8_BAR; PG8_MMA(1, 0, At, B0); PG8_MMA(1, 1, At, B1); PG8_BAR; PG8_SCHED;
;             PG8_LDB(B0, 1, 0); PG8_LDB(B1, 1, 1); PG8_SCHED; PG8_LDA(At, 1, 0); PG8_STAGE(PG8_SA(0, 1), a2 + hstep, voffA);
;             PG8_WAIT_V(8); PG8_WAIT_L(0); PG8_BAR; PG8_MMA(0, 0, At, B0); PG8_MMA(0, 1, At, B1); PG8_BAR; PG8_SCHED;
	s_setprio 1
	s_waitcnt lgkmcnt(0)
	v_mfma_f32_16x16x32_bf16 v[94:97], v[34:37], v[162:165], v[94:97]
	v_mfma_f32_16x16x32_bf16 v[90:93], v[42:45], v[162:165], v[90:93]
	v_mfma_f32_16x16x32_bf16 v[78:81], v[34:37], v[190:193], v[78:81]
	v_mfma_f32_16x16x32_bf16 v[74:77], v[42:45], v[190:193], v[74:77]
	v_mfma_f32_16x16x32_bf16 v[30:33], v[34:37], v[198:201], v[30:33]
	v_mfma_f32_16x16x32_bf16 v[26:29], v[42:45], v[198:201], v[26:29]
	v_mfma_f32_16x16x32_bf16 v[14:17], v[34:37], v[226:229], v[14:17]
	v_mfma_f32_16x16x32_bf16 v[10:13], v[42:45], v[226:229], v[10:13]
	v_mfma_f32_16x16x32_bf16 v[94:97], v[38:41], v[166:169], v[94:97]
	v_mfma_f32_16x16x32_bf16 v[90:93], v[46:49], v[166:169], v[90:93]
	v_mfma_f32_16x16x32_bf16 v[78:81], v[38:41], v[194:197], v[78:81]
	v_mfma_f32_16x16x32_bf16 v[74:77], v[46:49], v[194:197], v[74:77]
	v_mfma_f32_16x16x32_bf16 v[30:33], v[38:41], v[222:225], v[30:33]
	v_mfma_f32_16x16x32_bf16 v[26:29], v[46:49], v[222:225], v[26:29]
	v_mfma_f32_16x16x32_bf16 v[14:17], v[38:41], v[230:233], v[14:17]
	v_mfma_f32_16x16x32_bf16 v[10:13], v[46:49], v[230:233], v[10:13]
	s_setprio 0
	s_setprio 1
	v_mfma_f32_16x16x32_bf16 v[22:25], v[58:61], v[198:201], v[22:25]
	v_mfma_f32_16x16x32_bf16 v[18:21], v[66:69], v[198:201], v[18:21]
	v_mfma_f32_16x16x32_bf16 v[6:9], v[58:61], v[226:229], v[6:9]
	v_mfma_f32_16x16x32_bf16 v[2:5], v[66:69], v[226:229], v[2:5]
	v_mfma_f32_16x16x32_bf16 v[34:37], v[58:61], v[162:165], v[86:89]
	v_mfma_f32_16x16x32_bf16 v[38:41], v[66:69], v[162:165], v[82:85]
	v_mfma_f32_16x16x32_bf16 v[42:45], v[58:61], v[190:193], v[54:57]
	v_mfma_f32_16x16x32_bf16 v[46:49], v[66:69], v[190:193], v[50:53]
	v_mfma_f32_16x16x32_bf16 v[22:25], v[62:65], v[222:225], v[22:25]
	v_mfma_f32_16x16x32_bf16 v[18:21], v[70:73], v[222:225], v[18:21]
	v_mfma_f32_16x16x32_bf16 v[6:9], v[62:65], v[230:233], v[6:9]
	v_mfma_f32_16x16x32_bf16 v[2:5], v[70:73], v[230:233], v[2:5]
	v_mfma_f32_16x16x32_bf16 v[34:37], v[62:65], v[166:169], v[34:37]
	v_mfma_f32_16x16x32_bf16 v[38:41], v[70:73], v[166:169], v[38:41]
	v_mfma_f32_16x16x32_bf16 v[42:45], v[62:65], v[194:197], v[42:45]
	v_mfma_f32_16x16x32_bf16 v[46:49], v[70:73], v[194:197], v[46:49]
	s_setprio 0
	s_barrier
	s_add_i32 s56, 0, 0x18000
	s_add_i32 s57, 0, 0x1c000
	v_add_u32_e32 v62, s56, v212
	v_add_u32_e32 v82, s57, v212
	ds_read_b128 v[50:53], v62
	ds_read_b128 v[54:57], v62 offset:1024
	ds_read_b128 v[58:61], v62 offset:2048
	ds_read_b128 v[62:65], v62 offset:3072
	ds_read_b128 v[66:69], v82
	ds_read_b128 v[70:73], v82 offset:1024
	ds_read_b128 v[162:165], v82 offset:2048
	ds_read_b128 v[166:169], v82 offset:3072
	s_add_u32 s42, s42, 0x80000
	s_addc_u32 s43, s43, 0
	s_mov_b32 m0, s46
	v_lshl_add_u64 v[234:235], s[42:43], 0, v[178:179]
	ds_read_b128 v[82:85], v220 offset:32768
	global_load_lds_dwordx4 v[234:235], off
	ds_read_b128 v[86:89], v220 offset:33792
	ds_read_b128 v[190:193], v220 offset:34816
	v_lshl_add_u64 v[234:235], s[42:43], 0, v[180:181]
	s_mov_b32 m0, s47
	s_nop 0
	global_load_lds_dwordx4 v[234:235], off
	ds_read_b128 v[194:197], v220 offset:35840
	ds_read_b128 v[198:201], v220 offset:36864
	ds_read_b128 v[222:225], v220 offset:37888
	ds_read_b128 v[226:229], v220 offset:38912
	ds_read_b128 v[230:233], v220 offset:39936
	s_nop 0
	s_waitcnt vmcnt(8)
	s_waitcnt lgkmcnt(0)
	s_barrier
	s_setprio 1
	s_waitcnt lgkmcnt(0)
	v_mfma_f32_16x16x32_bf16 v[158:161], v[50:53], v[82:85], v[158:161]
	v_mfma_f32_16x16x32_bf16 v[154:157], v[58:61], v[82:85], v[154:157]
	v_mfma_f32_16x16x32_bf16 v[142:145], v[50:53], v[190:193], v[142:145]
	v_mfma_f32_16x16x32_bf16 v[138:141], v[58:61], v[190:193], v[138:141]
	v_mfma_f32_16x16x32_bf16 v[126:129], v[50:53], v[198:201], v[126:129]
	v_mfma_f32_16x16x32_bf16 v[122:125], v[58:61], v[198:201], v[122:125]
	v_mfma_f32_16x16x32_bf16 v[110:113], v[50:53], v[226:229], v[110:113]
	v_mfma_f32_16x16x32_bf16 v[106:109], v[58:61], v[226:229], v[106:109]
	v_mfma_f32_16x16x32_bf16 v[158:161], v[54:57], v[86:89], v[158:161]
	v_mfma_f32_16x16x32_bf16 v[154:157], v[62:65], v[86:89], v[154:157]
	v_mfma_f32_16x16x32_bf16 v[142:145], v[54:57], v[194:197], v[142:145]
	v_mfma_f32_16x16x32_bf16 v[138:141], v[62:65], v[194:197], v[138:141]
	v_mfma_f32_16x16x32_bf16 v[126:129], v[54:57], v[222:225], v[126:129]
	v_mfma_f32_16x16x32_bf16 v[122:125], v[62:65], v[222:225], v[122:125]
	v_mfma_f32_16x16x32_bf16 v[110:113], v[54:57], v[230:233], v[110:113]
	v_mfma_f32_16x16x32_bf16 v[106:109], v[62:65], v[230:233], v[106:109]
	s_setprio 0
	s_setprio 1
	v_mfma_f32_16x16x32_bf16 v[150:153], v[66:69], v[82:85], v[150:153]
	v_mfma_f32_16x16x32_bf16 v[82:85], v[162:165], v[82:85], v[146:149]
	v_mfma_f32_16x16x32_bf16 v[146:149], v[166:169], v[86:89], v[82:85]
	v_mfma_f32_16x16x32_bf16 v[82:85], v[66:69], v[190:193], v[134:137]
	v_mfma_f32_16x16x32_bf16 v[134:137], v[70:73], v[194:197], v[82:85]
	v_mfma_f32_16x16x32_bf16 v[82:85], v[162:165], v[190:193], v[130:133]
	v_mfma_f32_16x16x32_bf16 v[130:133], v[166:169], v[194:197], v[82:85]
	v_mfma_f32_16x16x32_bf16 v[82:85], v[66:69], v[198:201], v[118:121]
	v_mfma_f32_16x16x32_bf16 v[118:121], v[70:73], v[222:225], v[82:85]
	v_mfma_f32_16x16x32_bf16 v[82:85], v[162:165], v[198:201], v[114:117]
	v_mfma_f32_16x16x32_bf16 v[114:117], v[166:169], v[222:225], v[82:85]
	v_mfma_f32_16x16x32_bf16 v[82:85], v[66:69], v[226:229], v[102:105]
	v_mfma_f32_16x16x32_bf16 v[102:105], v[70:73], v[230:233], v[82:85]
	v_mfma_f32_16x16x32_bf16 v[82:85], v[162:165], v[226:229], v[98:101]
	v_mfma_f32_16x16x32_bf16 v[150:153], v[70:73], v[86:89], v[150:153]
	v_mfma_f32_16x16x32_bf16 v[98:101], v[166:169], v[230:233], v[82:85]
	s_setprio 0
	s_barrier
; #define PG8_STAGE(bufoff, gbase, voff) do { _Pragma("unroll") for (int _i = 0; _i < 2; ++_i) \
;         __builtin_amdgcn_global_load_lds((const unsigned*)((const char*)(gbase) + (voff)[_i]), (LAS unsigned*)(lds + (bufoff) + ldsw + _i * 8192), 16, 0, 0); } while (0)
; #define PG8_LDA(dst, b, h) do { _Pragma("unroll") for (int m = 0; m < 4; ++m) _Pragma("unroll") for (int k = 0; k < 2; ++k) dst[m][k] = *(const LAS bf16x8*)(lds + PG8_SA(b, h) + aoff + m * 2048 + k * 1024); } while (0)
; #define PG8_MMA(ai, bj, At, Bt) do { __builtin_amdgcn_s_setprio(1); _Pragma("unroll") for (int m = 0; m < 4; ++m) _Pragma("unroll") for (int n = 0; n < 2; ++n) _Pragma("unroll") for (int k = 0; k < 2; ++k) \
;         acc[ai][bj][m][n] = __builtin_amdgcn_mfma_f32_16x16x32_bf16(Bt[n][k], At[m][k], acc[ai][bj][m][n], 0, 0, 0); __builtin_amdgcn_s_setprio(0); } while (0)
; #define PG8_WAIT_V(n) asm volatile("s_waitcnt vmcnt(" #n ")" ::: "memory")
; #define PG8_WAIT_L(n) asm volatile("s_waitcnt lgkmcnt(" #n ")" ::: "memory")
; #define PG8_BAR __builtin_amdgcn_s_barrier()
; #define PG8_SCHED __builtin_amdgcn_sched_barrier(0)
; template <class Epi>
; __device__ __forceinline__ void gemm_phase(LAS unsigned char* lds, const Gemm g, const StaticOrder& S, const Epi& E, const int tid) {
;     ...
;             PG8_WAIT_V(8); PG8_WAIT_L(0); PG8_BAR; PG8_MMA(0, 0, At, B0); PG8_MMA(0, 1, At, B1); PG8_BAR; PG8_SCHED;
;             PG8_LDA(At, 1, 1); PG8_STAGE(PG8_SB(1, 0), b3, voffB); PG8_STAGE(PG8_SB(1, 1), b3 + bhs, voffB); PG8_STAGE(PG8_SA(1, 0), a3, voffA);
;             PG8_WAIT_V(8); PG8_WAIT_L(0); PG8_BAR; PG8_MMA(1, 0, At, B0); PG8_MMA(1, 1, At, B1); PG8_BAR; PG8_SCHED;
	s_add_i32 s42, s56, s33
	v_lshl_add_u64 v[86:87], v[172:173], 0, s[70:71]
	s_mov_b32 m0, s42
	s_nop 0
	ds_read_b128 v[82:85], v220 offset:49152
	global_load_lds_dwordx4 v[86:87], off
	ds_read_b128 v[190:193], v220 offset:50176
	ds_read_b128 v[194:197], v220 offset:51200
	s_add_i32 m0, s42, 0x2000
	s_add_u32 s40, s40, 0x8080
	v_lshl_add_u64 v[86:87], v[174:175], 0, s[70:71]
	s_addc_u32 s41, s41, 0
	s_add_i32 s42, s57, s33
	global_load_lds_dwordx4 v[86:87], off
	ds_read_b128 v[198:201], v220 offset:52224
	ds_read_b128 v[222:225], v220 offset:53248
	v_lshl_add_u64 v[86:87], s[40:41], 0, v[0:1]
	s_mov_b32 m0, s42
	s_nop 0
	global_load_lds_dwordx4 v[86:87], off
	ds_read_b128 v[226:229], v220 offset:54272
	ds_read_b128 v[230:233], v220 offset:55296
	v_lshl_add_u64 v[86:87], s[40:41], 0, v[182:183]
	s_add_i32 m0, s42, 0x2000
	s_nop 0
	global_load_lds_dwordx4 v[86:87], off
	ds_read_b128 v[234:237], v220 offset:56320
	v_lshl_add_u64 v[86:87], v[176:177], 0, s[70:71]
	s_mov_b32 m0, s48
	s_nop 0
	global_load_lds_dwordx4 v[86:87], off
	v_lshl_add_u64 v[86:87], v[238:239], 0, s[70:71]
	s_mov_b32 m0, s49
	s_nop 0
	global_load_lds_dwordx4 v[86:87], off
	s_nop 0
	s_waitcnt vmcnt(8)
	s_waitcnt lgkmcnt(0)
	s_barrier
	s_setprio 1
	s_waitcnt lgkmcnt(0)
	v_mfma_f32_16x16x32_bf16 v[86:89], v[50:53], v[82:85], v[94:97]
	v_mfma_f32_16x16x32_bf16 v[94:97], v[54:57], v[190:193], v[86:89]
	v_mfma_f32_16x16x32_bf16 v[86:89], v[58:61], v[82:85], v[90:93]
	v_mfma_f32_16x16x32_bf16 v[78:81], v[50:53], v[194:197], v[78:81]
	v_mfma_f32_16x16x32_bf16 v[74:77], v[58:61], v[194:197], v[74:77]
	v_mfma_f32_16x16x32_bf16 v[30:33], v[50:53], v[222:225], v[30:33]
	v_mfma_f32_16x16x32_bf16 v[26:29], v[58:61], v[222:225], v[26:29]
	v_mfma_f32_16x16x32_bf16 v[14:17], v[50:53], v[230:233], v[14:17]
	v_mfma_f32_16x16x32_bf16 v[10:13], v[58:61], v[230:233], v[10:13]
	v_mfma_f32_16x16x32_bf16 v[90:93], v[62:65], v[190:193], v[86:89]
	v_mfma_f32_16x16x32_bf16 v[78:81], v[54:57], v[198:201], v[78:81]
	v_mfma_f32_16x16x32_bf16 v[74:77], v[62:65], v[198:201], v[74:77]
	v_mfma_f32_16x16x32_bf16 v[30:33], v[54:57], v[226:229], v[30:33]
	v_mfma_f32_16x16x32_bf16 v[26:29], v[62:65], v[226:229], v[26:29]
	v_mfma_f32_16x16x32_bf16 v[14:17], v[54:57], v[234:237], v[14:17]
	v_mfma_f32_16x16x32_bf16 v[10:13], v[62:65], v[234:237], v[10:13]
	s_setprio 0
	s_setprio 1
	v_mfma_f32_16x16x32_bf16 v[34:37], v[66:69], v[82:85], v[34:37]
	v_mfma_f32_16x16x32_bf16 v[86:89], v[70:73], v[190:193], v[34:37]
	v_mfma_f32_16x16x32_bf16 v[34:37], v[162:165], v[82:85], v[38:41]
	v_mfma_f32_16x16x32_bf16 v[82:85], v[166:169], v[190:193], v[34:37]
	v_mfma_f32_16x16x32_bf16 v[34:37], v[66:69], v[194:197], v[42:45]
	v_mfma_f32_16x16x32_bf16 v[54:57], v[70:73], v[198:201], v[34:37]
	v_mfma_f32_16x16x32_bf16 v[34:37], v[162:165], v[194:197], v[46:49]
	v_mfma_f32_16x16x32_bf16 v[22:25], v[66:69], v[222:225], v[22:25]
	v_mfma_f32_16x16x32_bf16 v[18:21], v[162:165], v[222:225], v[18:21]
	v_mfma_f32_16x16x32_bf16 v[6:9], v[66:69], v[230:233], v[6:9]
	v_mfma_f32_16x16x32_bf16 v[2:5], v[162:165], v[230:233], v[2:5]
	v_mfma_f32_16x16x32_bf16 v[50:53], v[166:169], v[198:201], v[34:37]
	v_mfma_f32_16x16x32_bf16 v[22:25], v[70:73], v[226:229], v[22:25]
	v_mfma_f32_16x16x32_bf16 v[18:21], v[166:169], v[226:229], v[18:21]
	v_mfma_f32_16x16x32_bf16 v[6:9], v[70:73], v[234:237], v[6:9]
	v_mfma_f32_16x16x32_bf16 v[2:5], v[166:169], v[234:237], v[2:5]
	s_setprio 0
	s_barrier
	s_add_i32 s55, s55, 2
	s_add_u32 s53, s53, 0x100
	s_addc_u32 s54, s54, 0
	s_add_u32 s6, s6, 0x100
	s_addc_u32 s7, s7, 0
	s_cmp_gt_u32 s55, 29
	s_cbranch_scc0 .LBB0_314
	s_and_b64 vcc, exec, s[22:23]
	s_cbranch_vccz .LBB0_317
	s_barrier

; #define PG8_STAGE(bufoff, gbase, voff) do { _Pragma("unroll") for (int _i = 0; _i < 2; ++_i) \
;         __builtin_amdgcn_global_load_lds((const unsigned*)((const char*)(gbase) + (voff)[_i]), (LAS unsigned*)(lds + (bufoff) + ldsw + _i * 8192), 16, 0, 0); } while (0)
; #define PG8_LDA(dst, b, h) do { _Pragma("unroll") for (int m = 0; m < 4; ++m) _Pragma("unroll") for (int k = 0; k < 2; ++k) dst[m][k] = *(const LAS bf16x8*)(lds + PG8_SA(b, h) + aoff + m * 2048 + k * 1024); } while (0)
; #define PG8_LDB(dst, b, h) do { _Pragma("unroll") for (int n = 0; n < 2; ++n) _Pragma("unroll") for (int k = 0; k < 2; ++k) dst[n][k] = *(const LAS bf16x8*)(lds + PG8_SB(b, h) + boff + n * 2048 + k * 1024); } while (0)
; #define PG8_MMA(ai, bj, At, Bt) do { __builtin_amdgcn_s_setprio(1); _Pragma("unroll") for (int m = 0; m < 4; ++m) _Pragma("unroll") for (int n = 0; n < 2; ++n) _Pragma("unroll") for (int k = 0; k < 2; ++k) \
;         acc[ai][bj][m][n] = __builtin_amdgcn_mfma_f32_16x16x32_bf16(Bt[n][k], At[m][k], acc[ai][bj][m][n], 0, 0, 0); __builtin_amdgcn_s_setprio(0); } while (0)
; #define PG8_WAIT_V(n) asm volatile("s_waitcnt vmcnt(" #n ")" ::: "memory")
; #define PG8_WAIT_L(n) asm volatile("s_waitcnt lgkmcnt(" #n ")" ::: "memory")
; #define PG8_BAR __builtin_amdgcn_s_barrier()
; #define PG8_SCHED __builtin_amdgcn_sched_barrier(0)
; template <class Epi>
; __device__ __forceinline__ void gemm_phase(LAS unsigned char* lds, const Gemm g, const StaticOrder& S, const Epi& E, const int tid) {
;     ...
;             PG8_LDB(B0, 0, 0); PG8_LDB(B1, 0, 1); PG8_SCHED; PG8_LDA(At, 0, 0); PG8_STAGE(PG8_SA(1, 1), a1 + hstep, voffA);
;             PG8_WAIT_V(8); PG8_WAIT_L(0); PG8_BAR; PG8_MMA(0, 0, At, B0); PG8_MMA(0, 1, At, B1); PG8_BAR; PG8_SCHED;
;             PG8_LDA(At, 0, 1); PG8_STAGE(PG8_SB(0, 0), b2, voffB); PG8_STAGE(PG8_SB(0, 1), b2 + bhs, voffB); PG8_STAGE(PG8_SA(0, 0), a2, voffA);
;             PG8_WAIT_V(8); PG8_WAIT_L(0); PG8_BAR; PG8_MMA(1, 0, At, B0); PG8_MMA(1, 1, At, B1); PG8_BAR; PG8_SCHED;
.LBB0_454:
	s_add_i32 s13, 0, 0x10000
	v_add_u32_e32 v0, s13, v153
	s_add_i32 s36, 0, 0x14000
	ds_read_b128 v[132:135], v0
	ds_read_b128 v[136:139], v0 offset:1024
	ds_read_b128 v[156:159], v0 offset:2048
	ds_read_b128 v[160:163], v0 offset:3072
	v_add_u32_e32 v0, s36, v153
	ds_read_b128 v[164:167], v0
	ds_read_b128 v[178:181], v0 offset:1024
	ds_read_b128 v[182:185], v0 offset:2048
	ds_read_b128 v[186:189], v0 offset:3072
	s_add_u32 s34, s34, 0x40000
	s_addc_u32 s35, s35, 0
	v_lshl_add_u64 v[2:3], s[34:35], 0, v[140:141]
	s_add_i32 m0, s43, 0xc000
	ds_read_b128 v[190:193], v155
	global_load_lds_dwordx4 v[2:3], off
	ds_read_b128 v[194:197], v155 offset:1024
	ds_read_b128 v[198:201], v155 offset:2048
	v_lshl_add_u64 v[2:3], s[34:35], 0, v[144:145]
	s_add_i32 m0, s43, 0xe000
	s_nop 0
	global_load_lds_dwordx4 v[2:3], off
	ds_read_b128 v[212:215], v155 offset:3072
	ds_read_b128 v[216:219], v155 offset:4096
	ds_read_b128 v[220:223], v155 offset:5120
	ds_read_b128 v[224:227], v155 offset:6144
	ds_read_b128 v[228:231], v155 offset:7168
	s_nop 0
	s_waitcnt vmcnt(8)
	s_waitcnt lgkmcnt(0)
	s_barrier
	s_setprio 1
	s_waitcnt lgkmcnt(0)
	v_mfma_f32_16x16x32_bf16 v[128:131], v[132:135], v[190:193], v[128:131]
	v_mfma_f32_16x16x32_bf16 v[124:127], v[156:159], v[190:193], v[124:127]
	v_mfma_f32_16x16x32_bf16 v[112:115], v[132:135], v[198:201], v[112:115]
	v_mfma_f32_16x16x32_bf16 v[108:111], v[156:159], v[198:201], v[108:111]
	v_mfma_f32_16x16x32_bf16 v[96:99], v[132:135], v[216:219], v[96:99]
	v_mfma_f32_16x16x32_bf16 v[92:95], v[156:159], v[216:219], v[92:95]
	v_mfma_f32_16x16x32_bf16 v[80:83], v[132:135], v[224:227], v[80:83]
	v_mfma_f32_16x16x32_bf16 v[76:79], v[156:159], v[224:227], v[76:79]
	v_mfma_f32_16x16x32_bf16 v[128:131], v[136:139], v[194:197], v[128:131]
	v_mfma_f32_16x16x32_bf16 v[124:127], v[160:163], v[194:197], v[124:127]
	v_mfma_f32_16x16x32_bf16 v[112:115], v[136:139], v[212:215], v[112:115]
	v_mfma_f32_16x16x32_bf16 v[108:111], v[160:163], v[212:215], v[108:111]
	v_mfma_f32_16x16x32_bf16 v[96:99], v[136:139], v[220:223], v[96:99]
	v_mfma_f32_16x16x32_bf16 v[92:95], v[160:163], v[220:223], v[92:95]
	v_mfma_f32_16x16x32_bf16 v[80:83], v[136:139], v[228:231], v[80:83]
	v_mfma_f32_16x16x32_bf16 v[76:79], v[160:163], v[228:231], v[76:79]
	s_setprio 0
	s_setprio 1
	v_mfma_f32_16x16x32_bf16 v[120:123], v[164:167], v[190:193], v[120:123]
	v_mfma_f32_16x16x32_bf16 v[116:119], v[182:185], v[190:193], v[116:119]
	v_mfma_f32_16x16x32_bf16 v[104:107], v[164:167], v[198:201], v[104:107]
	v_mfma_f32_16x16x32_bf16 v[100:103], v[182:185], v[198:201], v[100:103]
	v_mfma_f32_16x16x32_bf16 v[88:91], v[164:167], v[216:219], v[88:91]
	v_mfma_f32_16x16x32_bf16 v[84:87], v[182:185], v[216:219], v[84:87]
	v_mfma_f32_16x16x32_bf16 v[72:75], v[164:167], v[224:227], v[72:75]
	v_mfma_f32_16x16x32_bf16 v[68:71], v[182:185], v[224:227], v[68:71]
	v_mfma_f32_16x16x32_bf16 v[120:123], v[178:181], v[194:197], v[120:123]
	v_mfma_f32_16x16x32_bf16 v[116:119], v[186:189], v[194:197], v[116:119]
	v_mfma_f32_16x16x32_bf16 v[104:107], v[178:181], v[212:215], v[104:107]
	v_mfma_f32_16x16x32_bf16 v[100:103], v[186:189], v[212:215], v[100:103]
	v_mfma_f32_16x16x32_bf16 v[88:91], v[178:181], v[220:223], v[88:91]
	v_mfma_f32_16x16x32_bf16 v[84:87], v[186:189], v[220:223], v[84:87]
	v_mfma_f32_16x16x32_bf16 v[72:75], v[178:181], v[228:231], v[72:75]
	v_mfma_f32_16x16x32_bf16 v[68:71], v[186:189], v[228:231], v[68:71]
	s_setprio 0
	s_barrier
	s_add_i32 s13, s13, s42
	v_lshl_add_u64 v[168:169], s[28:29], 0, v[142:143]
	s_mov_b32 m0, s13
	ds_read_b128 v[190:193], v155 offset:16384
	global_load_lds_dwordx4 v[168:169], off
	ds_read_b128 v[194:197], v155 offset:17408
	ds_read_b128 v[198:201], v155 offset:18432
	s_add_i32 m0, s13, 0x2000
	s_add_u32 s34, s28, 0x4000
	v_lshl_add_u64 v[172:173], s[28:29], 0, v[146:147]
	s_addc_u32 s35, s29, 0
	s_add_i32 s13, s36, s42
	global_load_lds_dwordx4 v[172:173], off
	ds_read_b128 v[212:215], v155 offset:19456
	ds_read_b128 v[216:219], v155 offset:20480
	v_lshl_add_u64 v[2:3], s[34:35], 0, v[142:143]
	s_mov_b32 m0, s13
	v_lshl_add_u64 v[174:175], s[30:31], 0, v[140:141]
	global_load_lds_dwordx4 v[2:3], off
	ds_read_b128 v[220:223], v155 offset:21504
	ds_read_b128 v[224:227], v155 offset:22528
	v_lshl_add_u64 v[2:3], s[34:35], 0, v[146:147]
	s_add_i32 m0, s13, 0x2000
	v_lshl_add_u64 v[176:177], s[30:31], 0, v[144:145]
	global_load_lds_dwordx4 v[2:3], off
	ds_read_b128 v[228:231], v155 offset:23552
	s_mov_b32 m0, s43
	s_nop 0
	global_load_lds_dwordx4 v[174:175], off
	s_mov_b32 m0, s44
	s_nop 0
	global_load_lds_dwordx4 v[176:177], off
	s_waitcnt vmcnt(8)
	s_waitcnt lgkmcnt(0)
	s_barrier
; #define PG8_STAGE(bufoff, gbase, voff) do { _Pragma("unroll") for (int _i = 0; _i < 2; ++_i) \
;         __builtin_amdgcn_global_load_lds((const unsigned*)((const char*)(gbase) + (voff)[_i]), (LAS unsigned*)(lds + (bufoff) + ldsw + _i * 8192), 16, 0, 0); } while (0)
; #define PG8_LDA(dst, b, h) do { _Pragma("unroll") for (int m = 0; m < 4; ++m) _Pragma("unroll") for (int k = 0; k < 2; ++k) dst[m][k] = *(const LAS bf16x8*)(lds + PG8_SA(b, h) + aoff + m * 2048 + k * 1024); } while (0)
; #define PG8_LDB(dst, b, h) do { _Pragma("unroll") for (int n = 0; n < 2; ++n) _Pragma("unroll") for (int k = 0; k < 2; ++k) dst[n][k] = *(const LAS bf16x8*)(lds + PG8_SB(b, h) + boff + n * 2048 + k * 1024); } while (0)
; #define PG8_MMA(ai, bj, At, Bt) do { __builtin_amdgcn_s_setprio(1); _Pragma("unroll") for (int m = 0; m < 4; ++m) _Pragma("unroll") for (int n = 0; n < 2; ++n) _Pragma("unroll") for (int k = 0; k < 2; ++k) \
;         acc[ai][bj][m][n] = __builtin_amdgcn_mfma_f32_16x16x32_bf16(Bt[n][k], At[m][k], acc[ai][bj][m][n], 0, 0, 0); __builtin_amdgcn_s_setprio(0); } while (0)
; #define PG8_WAIT_V(n) asm volatile("s_waitcnt vmcnt(" #n ")" ::: "memory")
; #define PG8_WAIT_L(n) asm volatile("s_waitcnt lgkmcnt(" #n ")" ::: "memory")
; #define PG8_BAR __builtin_amdgcn_s_barrier()
; #define PG8_SCHED __builtin_amdgcn_sched_barrier(0)
; template <class Epi>
; __device__ __forceinline__ void gemm_phase(LAS unsigned char* lds, const Gemm g, const StaticOrder& S, const Epi& E, const int tid) {
;     ...
;             PG8_LDA(At, 0, 1); PG8_STAGE(PG8_SB(0, 0), b2, voffB); PG8_STAGE(PG8_SB(0, 1), b2 + bhs, voffB); PG8_STAGE(PG8_SA(0, 0), a2, voffA);
;             PG8_WAIT_V(8); PG8_WAIT_L(0); PG8_BAR; PG8_MMA(1, 0, At, B0); PG8_MMA(1, 1, At, B1); PG8_BAR; PG8_SCHED;
;             PG8_LDB(B0, 1, 0); PG8_LDB(B1, 1, 1); PG8_SCHED; PG8_LDA(At, 1, 0); PG8_STAGE(PG8_SA(0, 1), a2 + hstep, voffA);
;             PG8_WAIT_V(8); PG8_WAIT_L(0); PG8_BAR; PG8_MMA(0, 0, At, B0); PG8_MMA(0, 1, At, B1); PG8_BAR; PG8_SCHED;
	s_setprio 1
	s_waitcnt lgkmcnt(0)
	v_mfma_f32_16x16x32_bf16 v[64:67], v[132:135], v[190:193], v[64:67]
	v_mfma_f32_16x16x32_bf16 v[60:63], v[156:159], v[190:193], v[60:63]
	v_mfma_f32_16x16x32_bf16 v[48:51], v[132:135], v[198:201], v[48:51]
	v_mfma_f32_16x16x32_bf16 v[44:47], v[156:159], v[198:201], v[44:47]
	v_mfma_f32_16x16x32_bf16 v[32:35], v[132:135], v[216:219], v[32:35]
	v_mfma_f32_16x16x32_bf16 v[28:31], v[156:159], v[216:219], v[28:31]
	v_mfma_f32_16x16x32_bf16 v[16:19], v[132:135], v[224:227], v[16:19]
	v_mfma_f32_16x16x32_bf16 v[12:15], v[156:159], v[224:227], v[12:15]
	v_mfma_f32_16x16x32_bf16 v[64:67], v[136:139], v[194:197], v[64:67]
	v_mfma_f32_16x16x32_bf16 v[60:63], v[160:163], v[194:197], v[60:63]
	v_mfma_f32_16x16x32_bf16 v[48:51], v[136:139], v[212:215], v[48:51]
	v_mfma_f32_16x16x32_bf16 v[44:47], v[160:163], v[212:215], v[44:47]
	v_mfma_f32_16x16x32_bf16 v[32:35], v[136:139], v[220:223], v[32:35]
	v_mfma_f32_16x16x32_bf16 v[28:31], v[160:163], v[220:223], v[28:31]
	v_mfma_f32_16x16x32_bf16 v[16:19], v[136:139], v[228:231], v[16:19]
	v_mfma_f32_16x16x32_bf16 v[12:15], v[160:163], v[228:231], v[12:15]
	s_setprio 0
	s_setprio 1
	v_mfma_f32_16x16x32_bf16 v[56:59], v[164:167], v[190:193], v[56:59]
	v_mfma_f32_16x16x32_bf16 v[52:55], v[182:185], v[190:193], v[52:55]
	v_mfma_f32_16x16x32_bf16 v[40:43], v[164:167], v[198:201], v[40:43]
	v_mfma_f32_16x16x32_bf16 v[36:39], v[182:185], v[198:201], v[36:39]
	v_mfma_f32_16x16x32_bf16 v[24:27], v[164:167], v[216:219], v[24:27]
	v_mfma_f32_16x16x32_bf16 v[20:23], v[182:185], v[216:219], v[20:23]
	v_mfma_f32_16x16x32_bf16 v[8:11], v[164:167], v[224:227], v[8:11]
	v_mfma_f32_16x16x32_bf16 v[2:5], v[182:185], v[224:227], v[4:7]
	v_mfma_f32_16x16x32_bf16 v[56:59], v[178:181], v[194:197], v[56:59]
	v_mfma_f32_16x16x32_bf16 v[52:55], v[186:189], v[194:197], v[52:55]
	v_mfma_f32_16x16x32_bf16 v[40:43], v[178:181], v[212:215], v[40:43]
	v_mfma_f32_16x16x32_bf16 v[36:39], v[186:189], v[212:215], v[36:39]
	v_mfma_f32_16x16x32_bf16 v[24:27], v[178:181], v[220:223], v[24:27]
	v_mfma_f32_16x16x32_bf16 v[20:23], v[186:189], v[220:223], v[20:23]
	v_mfma_f32_16x16x32_bf16 v[8:11], v[178:181], v[228:231], v[8:11]
	v_mfma_f32_16x16x32_bf16 v[2:5], v[186:189], v[228:231], v[2:5]
	s_setprio 0
	s_barrier
	s_add_i32 s13, 0, 0x18000
	v_add_u32_e32 v0, s13, v153
	s_add_i32 s34, 0, 0x1c000
	ds_read_b128 v[132:135], v0
	ds_read_b128 v[136:139], v0 offset:1024
	ds_read_b128 v[156:159], v0 offset:2048
	ds_read_b128 v[160:163], v0 offset:3072
	v_add_u32_e32 v0, s34, v153
	ds_read_b128 v[164:167], v0
	ds_read_b128 v[178:181], v0 offset:1024
	ds_read_b128 v[182:185], v0 offset:2048
	ds_read_b128 v[186:189], v0 offset:3072
	s_add_u32 s30, s30, 0x40000
	s_addc_u32 s31, s31, 0
	s_mov_b32 m0, s45
	v_lshl_add_u64 v[6:7], s[30:31], 0, v[140:141]
	ds_read_b128 v[190:193], v155 offset:32768
	global_load_lds_dwordx4 v[6:7], off
	ds_read_b128 v[194:197], v155 offset:33792
	ds_read_b128 v[198:201], v155 offset:34816
	v_lshl_add_u64 v[6:7], s[30:31], 0, v[144:145]
	s_mov_b32 m0, s46
	s_nop 0
	global_load_lds_dwordx4 v[6:7], off
	ds_read_b128 v[212:215], v155 offset:35840
	ds_read_b128 v[216:219], v155 offset:36864
	ds_read_b128 v[220:223], v155 offset:37888
	ds_read_b128 v[224:227], v155 offset:38912
	ds_read_b128 v[228:231], v155 offset:39936
	s_nop 0
	s_waitcnt vmcnt(8)
	s_waitcnt lgkmcnt(0)
	s_barrier
	s_setprio 1
	s_waitcnt lgkmcnt(0)
	v_mfma_f32_16x16x32_bf16 v[128:131], v[132:135], v[190:193], v[128:131]
	v_mfma_f32_16x16x32_bf16 v[124:127], v[156:159], v[190:193], v[124:127]
	v_mfma_f32_16x16x32_bf16 v[112:115], v[132:135], v[198:201], v[112:115]
	v_mfma_f32_16x16x32_bf16 v[108:111], v[156:159], v[198:201], v[108:111]
	v_mfma_f32_16x16x32_bf16 v[96:99], v[132:135], v[216:219], v[96:99]
	v_mfma_f32_16x16x32_bf16 v[92:95], v[156:159], v[216:219], v[92:95]
	v_mfma_f32_16x16x32_bf16 v[80:83], v[132:135], v[224:227], v[80:83]
	v_mfma_f32_16x16x32_bf16 v[76:79], v[156:159], v[224:227], v[76:79]
	v_mfma_f32_16x16x32_bf16 v[128:131], v[136:139], v[194:197], v[128:131]
	v_mfma_f32_16x16x32_bf16 v[124:127], v[160:163], v[194:197], v[124:127]
	v_mfma_f32_16x16x32_bf16 v[112:115], v[136:139], v[212:215], v[112:115]
	v_mfma_f32_16x16x32_bf16 v[108:111], v[160:163], v[212:215], v[108:111]
	v_mfma_f32_16x16x32_bf16 v[96:99], v[136:139], v[220:223], v[96:99]
	v_mfma_f32_16x16x32_bf16 v[92:95], v[160:163], v[220:223], v[92:95]
	v_mfma_f32_16x16x32_bf16 v[80:83], v[136:139], v[228:231], v[80:83]
	v_mfma_f32_16x16x32_bf16 v[76:79], v[160:163], v[228:231], v[76:79]
	s_setprio 0
	s_setprio 1
	v_mfma_f32_16x16x32_bf16 v[120:123], v[164:167], v[190:193], v[120:123]
	v_mfma_f32_16x16x32_bf16 v[116:119], v[182:185], v[190:193], v[116:119]
	v_mfma_f32_16x16x32_bf16 v[104:107], v[164:167], v[198:201], v[104:107]
	v_mfma_f32_16x16x32_bf16 v[100:103], v[182:185], v[198:201], v[100:103]
	v_mfma_f32_16x16x32_bf16 v[88:91], v[164:167], v[216:219], v[88:91]
	v_mfma_f32_16x16x32_bf16 v[84:87], v[182:185], v[216:219], v[84:87]
	v_mfma_f32_16x16x32_bf16 v[72:75], v[164:167], v[224:227], v[72:75]
	v_mfma_f32_16x16x32_bf16 v[68:71], v[182:185], v[224:227], v[68:71]
	v_mfma_f32_16x16x32_bf16 v[120:123], v[178:181], v[194:197], v[120:123]
	v_mfma_f32_16x16x32_bf16 v[116:119], v[186:189], v[194:197], v[116:119]
	v_mfma_f32_16x16x32_bf16 v[104:107], v[178:181], v[212:215], v[104:107]
	v_mfma_f32_16x16x32_bf16 v[100:103], v[186:189], v[212:215], v[100:103]
	v_mfma_f32_16x16x32_bf16 v[88:91], v[178:181], v[220:223], v[88:91]
	v_mfma_f32_16x16x32_bf16 v[84:87], v[186:189], v[220:223], v[84:87]
	v_mfma_f32_16x16x32_bf16 v[72:75], v[178:181], v[228:231], v[72:75]
	v_mfma_f32_16x16x32_bf16 v[68:71], v[186:189], v[228:231], v[68:71]
	s_setprio 0
	s_barrier
; #define PG8_STAGE(bufoff, gbase, voff) do { _Pragma("unroll") for (int _i = 0; _i < 2; ++_i) \
;         __builtin_amdgcn_global_load_lds((const unsigned*)((const char*)(gbase) + (voff)[_i]), (LAS unsigned*)(lds + (bufoff) + ldsw + _i * 8192), 16, 0, 0); } while (0)
; #define PG8_LDA(dst, b, h) do { _Pragma("unroll") for (int m = 0; m < 4; ++m) _Pragma("unroll") for (int k = 0; k < 2; ++k) dst[m][k] = *(const LAS bf16x8*)(lds + PG8_SA(b, h) + aoff + m * 2048 + k * 1024); } while (0)
; #define PG8_MMA(ai, bj, At, Bt) do { __builtin_amdgcn_s_setprio(1); _Pragma("unroll") for (int m = 0; m < 4; ++m) _Pragma("unroll") for (int n = 0; n < 2; ++n) _Pragma("unroll") for (int k = 0; k < 2; ++k) \
;         acc[ai][bj][m][n] = __builtin_amdgcn_mfma_f32_16x16x32_bf16(Bt[n][k], At[m][k], acc[ai][bj][m][n], 0, 0, 0); __builtin_amdgcn_s_setprio(0); } while (0)
; #define PG8_WAIT_V(n) asm volatile("s_waitcnt vmcnt(" #n ")" ::: "memory")
; #define PG8_WAIT_L(n) asm volatile("s_waitcnt lgkmcnt(" #n ")" ::: "memory")
; #define PG8_BAR __builtin_amdgcn_s_barrier()
; #define PG8_SCHED __builtin_amdgcn_sched_barrier(0)
; template <class Epi>
; __device__ __forceinline__ void gemm_phase(LAS unsigned char* lds, const Gemm g, const StaticOrder& S, const Epi& E, const int tid) {
;     ...
;             PG8_LDA(At, 1, 1); PG8_STAGE(PG8_SB(1, 0), b3, voffB); PG8_STAGE(PG8_SB(1, 1), b3 + bhs, voffB); PG8_STAGE(PG8_SA(1, 0), a3, voffA);
;             PG8_WAIT_V(8); PG8_WAIT_L(0); PG8_BAR; PG8_MMA(1, 0, At, B0); PG8_MMA(1, 1, At, B1); PG8_BAR; PG8_SCHED;
	s_add_i32 s13, s13, s42
	v_lshl_add_u64 v[6:7], v[168:169], 0, s[70:71]
	s_mov_b32 m0, s13
	ds_read_b128 v[190:193], v155 offset:49152
	global_load_lds_dwordx4 v[6:7], off
	ds_read_b128 v[194:197], v155 offset:50176
	ds_read_b128 v[198:201], v155 offset:51200
	s_add_i32 m0, s13, 0x2000
	s_add_u32 s28, s28, 0x4080
	v_lshl_add_u64 v[6:7], v[172:173], 0, s[70:71]
	s_addc_u32 s29, s29, 0
	s_add_i32 s13, s34, s42
	global_load_lds_dwordx4 v[6:7], off
	ds_read_b128 v[212:215], v155 offset:52224
	ds_read_b128 v[216:219], v155 offset:53248
	v_lshl_add_u64 v[6:7], s[28:29], 0, v[142:143]
	s_mov_b32 m0, s13
	s_nop 0
	global_load_lds_dwordx4 v[6:7], off
	ds_read_b128 v[220:223], v155 offset:54272
	ds_read_b128 v[224:227], v155 offset:55296
	v_lshl_add_u64 v[6:7], s[28:29], 0, v[146:147]
	s_add_i32 m0, s13, 0x2000
	s_nop 0
	global_load_lds_dwordx4 v[6:7], off
	ds_read_b128 v[228:231], v155 offset:56320
	v_lshl_add_u64 v[6:7], v[174:175], 0, s[70:71]
	s_mov_b32 m0, s47
	s_nop 0
	global_load_lds_dwordx4 v[6:7], off
	v_lshl_add_u64 v[6:7], v[176:177], 0, s[70:71]
	s_mov_b32 m0, s48
	s_nop 0
	global_load_lds_dwordx4 v[6:7], off
	s_waitcnt vmcnt(8)
	s_waitcnt lgkmcnt(0)
	s_barrier
	s_setprio 1
	s_waitcnt lgkmcnt(0)
	v_mfma_f32_16x16x32_bf16 v[64:67], v[132:135], v[190:193], v[64:67]
	v_mfma_f32_16x16x32_bf16 v[60:63], v[156:159], v[190:193], v[60:63]
	v_mfma_f32_16x16x32_bf16 v[48:51], v[132:135], v[198:201], v[48:51]
	v_mfma_f32_16x16x32_bf16 v[44:47], v[156:159], v[198:201], v[44:47]
	v_mfma_f32_16x16x32_bf16 v[32:35], v[132:135], v[216:219], v[32:35]
	v_mfma_f32_16x16x32_bf16 v[28:31], v[156:159], v[216:219], v[28:31]
	v_mfma_f32_16x16x32_bf16 v[16:19], v[132:135], v[224:227], v[16:19]
	v_mfma_f32_16x16x32_bf16 v[12:15], v[156:159], v[224:227], v[12:15]
	v_mfma_f32_16x16x32_bf16 v[64:67], v[136:139], v[194:197], v[64:67]
	v_mfma_f32_16x16x32_bf16 v[60:63], v[160:163], v[194:197], v[60:63]
	v_mfma_f32_16x16x32_bf16 v[48:51], v[136:139], v[212:215], v[48:51]
	v_mfma_f32_16x16x32_bf16 v[44:47], v[160:163], v[212:215], v[44:47]
	v_mfma_f32_16x16x32_bf16 v[32:35], v[136:139], v[220:223], v[32:35]
	v_mfma_f32_16x16x32_bf16 v[28:31], v[160:163], v[220:223], v[28:31]
	v_mfma_f32_16x16x32_bf16 v[16:19], v[136:139], v[228:231], v[16:19]
	v_mfma_f32_16x16x32_bf16 v[12:15], v[160:163], v[228:231], v[12:15]
	s_setprio 0
	s_setprio 1
	v_mfma_f32_16x16x32_bf16 v[56:59], v[164:167], v[190:193], v[56:59]
	v_mfma_f32_16x16x32_bf16 v[52:55], v[182:185], v[190:193], v[52:55]
	v_mfma_f32_16x16x32_bf16 v[40:43], v[164:167], v[198:201], v[40:43]
	v_mfma_f32_16x16x32_bf16 v[36:39], v[182:185], v[198:201], v[36:39]
	v_mfma_f32_16x16x32_bf16 v[24:27], v[164:167], v[216:219], v[24:27]
	v_mfma_f32_16x16x32_bf16 v[20:23], v[182:185], v[216:219], v[20:23]
	v_mfma_f32_16x16x32_bf16 v[6:9], v[164:167], v[224:227], v[8:11]
	v_mfma_f32_16x16x32_bf16 v[2:5], v[182:185], v[224:227], v[2:5]
	v_mfma_f32_16x16x32_bf16 v[56:59], v[178:181], v[194:197], v[56:59]
	v_mfma_f32_16x16x32_bf16 v[52:55], v[186:189], v[194:197], v[52:55]
	v_mfma_f32_16x16x32_bf16 v[40:43], v[178:181], v[212:215], v[40:43]
	v_mfma_f32_16x16x32_bf16 v[36:39], v[186:189], v[212:215], v[36:39]
	v_mfma_f32_16x16x32_bf16 v[24:27], v[178:181], v[220:223], v[24:27]
	v_mfma_f32_16x16x32_bf16 v[20:23], v[186:189], v[220:223], v[20:23]
	v_mfma_f32_16x16x32_bf16 v[8:11], v[178:181], v[228:231], v[6:9]
	v_mfma_f32_16x16x32_bf16 v[4:7], v[186:189], v[228:231], v[2:5]
	s_setprio 0
	s_barrier
	s_add_i32 s2, s2, 2
	s_add_u32 s24, s24, 0x100
	s_addc_u32 s25, s25, 0
	s_add_u32 s26, s26, 0x100
	s_addc_u32 s27, s27, 0
	s_cmp_gt_u32 s11, 29
	s_cbranch_scc1 .LBB0_467

; #define PG8_STAGE(bufoff, gbase, voff) do { _Pragma("unroll") for (int _i = 0; _i < 2; ++_i) \
;         __builtin_amdgcn_global_load_lds((const unsigned*)((const char*)(gbase) + (voff)[_i]), (LAS unsigned*)(lds + (bufoff) + ldsw + _i * 8192), 16, 0, 0); } while (0)
; #define PG8_LDA(dst, b, h) do { _Pragma("unroll") for (int m = 0; m < 4; ++m) _Pragma("unroll") for (int k = 0; k < 2; ++k) dst[m][k] = *(const LAS bf16x8*)(lds + PG8_SA(b, h) + aoff + m * 2048 + k * 1024); } while (0)
; #define PG8_LDB(dst, b, h) do { _Pragma("unroll") for (int n = 0; n < 2; ++n) _Pragma("unroll") for (int k = 0; k < 2; ++k) dst[n][k] = *(const LAS bf16x8*)(lds + PG8_SB(b, h) + boff + n * 2048 + k * 1024); } while (0)
; #define PG8_MMA(ai, bj, At, Bt) do { __builtin_amdgcn_s_setprio(1); _Pragma("unroll") for (int m = 0; m < 4; ++m) _Pragma("unroll") for (int n = 0; n < 2; ++n) _Pragma("unroll") for (int k = 0; k < 2; ++k) \
;         acc[ai][bj][m][n] = __builtin_amdgcn_mfma_f32_16x16x32_bf16(Bt[n][k], At[m][k], acc[ai][bj][m][n], 0, 0, 0); __builtin_amdgcn_s_setprio(0); } while (0)
; #define PG8_WAIT_V(n) asm volatile("s_waitcnt vmcnt(" #n ")" ::: "memory")
; #define PG8_WAIT_L(n) asm volatile("s_waitcnt lgkmcnt(" #n ")" ::: "memory")
; #define PG8_BAR __builtin_amdgcn_s_barrier()
; template <class Epi>
; __device__ __forceinline__ void gemm_phase(LAS unsigned char* lds, const Gemm g, const StaticOrder& S, const Epi& E, const int tid) {
;     ...
;             const char* a2 = last ? nA : (s2 ? cA2 + (size_t)(t + 2 - nt) * kstep : cA + (size_t)(t + 2) * kstep);
;             const char* b2 = last ? nB : (s2 ? cB2 + (size_t)(t + 2 - nt) * kstep : cB + (size_t)(t + 2) * kstep);
;             const char* a3 = a2 + kstep; const char* b3 = b2 + kstep;
;             if constexpr (Epi::TWO) { if (t == nt) E.mid(acc, cur, wr, wc, fr, fq); }
;             if constexpr (SP2) {
;             PG8_LDB(B0, 0, 0); PG8_LDB(B1, 0, 1); PG8_SCHED; PG8_LDA(At, 0, 0); PG8_STAGE(PG8_SA(1, 1), a1 + hstep, voffA);
;             PG8_WAIT_V(8); PG8_WAIT_L(0); PG8_BAR; PG8_MMA(0, 0, At, B0); PG8_MMA(0, 1, At, B1); PG8_BAR; PG8_SCHED;
;             PG8_LDA(At, 0, 1); PG8_STAGE(PG8_SB(0, 0), b2, voffB); PG8_STAGE(PG8_SB(0, 1), b2 + bhs, voffB); PG8_STAGE(PG8_SA(0, 0), a2, voffA);
;             PG8_WAIT_V(8); PG8_WAIT_L(0); PG8_BAR; PG8_MMA(1, 0, At, B0); PG8_MMA(1, 1, At, B1); PG8_BAR; PG8_SCHED;
.LBB0_546:
	s_add_u32 s28, s26, 0xfff80080
	s_addc_u32 s29, s27, -1
	s_add_i32 s44, 0, 0x10000
	s_cmp_eq_u32 s39, 28
	s_cselect_b32 s35, s19, s29
	s_cselect_b32 s34, s31, s28
	v_add_u32_e32 v0, s44, v149
	s_cselect_b32 s29, s17, s38
	s_cselect_b32 s28, s33, s37
	s_add_i32 s46, 0, 0x14000
	ds_read_b128 v[150:153], v0
	ds_read_b128 v[154:157], v0 offset:1024
	ds_read_b128 v[158:161], v0 offset:2048
	ds_read_b128 v[186:189], v0 offset:3072
	v_add_u32_e32 v0, s46, v149
	ds_read_b128 v[190:193], v0
	ds_read_b128 v[194:197], v0 offset:1024
	ds_read_b128 v[198:201], v0 offset:2048
	ds_read_b128 v[212:215], v0 offset:3072
	v_lshl_add_u64 v[162:163], s[26:27], 0, v[146:147]
	s_add_i32 m0, s57, 0xc000
	ds_read_b128 v[216:219], v184
	global_load_lds_dwordx4 v[162:163], off
	ds_read_b128 v[220:223], v184 offset:1024
	ds_read_b128 v[224:227], v184 offset:2048
	v_lshl_add_u64 v[162:163], s[26:27], 0, v[144:145]
	s_add_i32 m0, s57, 0xe000
	s_nop 0
	global_load_lds_dwordx4 v[162:163], off
	ds_read_b128 v[228:231], v184 offset:3072
	ds_read_b128 v[232:235], v184 offset:4096
	ds_read_b128 v[236:239], v184 offset:5120
	ds_read_b128 v[240:243], v184 offset:6144
	ds_read_b128 v[244:247], v184 offset:7168
	s_waitcnt vmcnt(8)
	s_waitcnt lgkmcnt(0)
	s_barrier
	s_setprio 1
	s_waitcnt lgkmcnt(0)
	v_mfma_f32_16x16x32_bf16 v[126:129], v[150:153], v[216:219], v[126:129]
	v_mfma_f32_16x16x32_bf16 v[122:125], v[158:161], v[216:219], v[122:125]
	v_mfma_f32_16x16x32_bf16 v[110:113], v[150:153], v[224:227], v[110:113]
	v_mfma_f32_16x16x32_bf16 v[106:109], v[158:161], v[224:227], v[106:109]
	v_mfma_f32_16x16x32_bf16 v[94:97], v[150:153], v[232:235], v[94:97]
	v_mfma_f32_16x16x32_bf16 v[90:93], v[158:161], v[232:235], v[90:93]
	v_mfma_f32_16x16x32_bf16 v[78:81], v[150:153], v[240:243], v[78:81]
	v_mfma_f32_16x16x32_bf16 v[74:77], v[158:161], v[240:243], v[74:77]
	v_mfma_f32_16x16x32_bf16 v[126:129], v[154:157], v[220:223], v[126:129]
	v_mfma_f32_16x16x32_bf16 v[122:125], v[186:189], v[220:223], v[122:125]
	v_mfma_f32_16x16x32_bf16 v[110:113], v[154:157], v[228:231], v[110:113]
	v_mfma_f32_16x16x32_bf16 v[106:109], v[186:189], v[228:231], v[106:109]
	v_mfma_f32_16x16x32_bf16 v[94:97], v[154:157], v[236:239], v[94:97]
	v_mfma_f32_16x16x32_bf16 v[90:93], v[186:189], v[236:239], v[90:93]
	v_mfma_f32_16x16x32_bf16 v[78:81], v[154:157], v[244:247], v[78:81]
	v_mfma_f32_16x16x32_bf16 v[74:77], v[186:189], v[244:247], v[74:77]
	s_setprio 0
	s_setprio 1
	v_mfma_f32_16x16x32_bf16 v[118:121], v[190:193], v[216:219], v[118:121]
	v_mfma_f32_16x16x32_bf16 v[114:117], v[198:201], v[216:219], v[114:117]
	v_mfma_f32_16x16x32_bf16 v[102:105], v[190:193], v[224:227], v[102:105]
	v_mfma_f32_16x16x32_bf16 v[98:101], v[198:201], v[224:227], v[98:101]
	v_mfma_f32_16x16x32_bf16 v[86:89], v[190:193], v[232:235], v[86:89]
	v_mfma_f32_16x16x32_bf16 v[82:85], v[198:201], v[232:235], v[82:85]
	v_mfma_f32_16x16x32_bf16 v[70:73], v[190:193], v[240:243], v[70:73]
	v_mfma_f32_16x16x32_bf16 v[66:69], v[198:201], v[240:243], v[66:69]
	v_mfma_f32_16x16x32_bf16 v[118:121], v[194:197], v[220:223], v[118:121]
	v_mfma_f32_16x16x32_bf16 v[114:117], v[212:215], v[220:223], v[114:117]
	v_mfma_f32_16x16x32_bf16 v[102:105], v[194:197], v[228:231], v[102:105]
	v_mfma_f32_16x16x32_bf16 v[98:101], v[212:215], v[228:231], v[98:101]
	v_mfma_f32_16x16x32_bf16 v[86:89], v[194:197], v[236:239], v[86:89]
	v_mfma_f32_16x16x32_bf16 v[82:85], v[212:215], v[236:239], v[82:85]
	v_mfma_f32_16x16x32_bf16 v[70:73], v[194:197], v[244:247], v[70:73]
	v_mfma_f32_16x16x32_bf16 v[66:69], v[212:215], v[244:247], v[66:69]
	s_setprio 0
	s_barrier
	s_add_i32 s44, s44, s56
	v_lshl_add_u64 v[162:163], s[28:29], 0, v[132:133]
	s_mov_b32 m0, s44
	ds_read_b128 v[216:219], v184 offset:16384
	global_load_lds_dwordx4 v[162:163], off
	ds_read_b128 v[220:223], v184 offset:17408
	ds_read_b128 v[224:227], v184 offset:18432
	s_add_i32 m0, s44, 0x2000
	s_add_u32 s44, s28, 0x8000
	v_lshl_add_u64 v[248:249], s[28:29], 0, v[136:137]
	s_addc_u32 s45, s29, 0
	s_add_i32 s46, s46, s56
	global_load_lds_dwordx4 v[248:249], off
	ds_read_b128 v[228:231], v184 offset:19456
	ds_read_b128 v[232:235], v184 offset:20480
	v_lshl_add_u64 v[172:173], s[44:45], 0, v[132:133]
	s_mov_b32 m0, s46
	v_lshl_add_u64 v[174:175], s[34:35], 0, v[134:135]
	global_load_lds_dwordx4 v[172:173], off
	ds_read_b128 v[236:239], v184 offset:21504
	ds_read_b128 v[240:243], v184 offset:22528
	v_lshl_add_u64 v[172:173], s[44:45], 0, v[136:137]
	s_add_i32 m0, s46, 0x2000
	s_nop 0
	global_load_lds_dwordx4 v[172:173], off
	ds_read_b128 v[244:247], v184 offset:23552
	v_lshl_add_u64 v[172:173], s[34:35], 0, v[130:131]
	s_mov_b32 m0, s57
	s_nop 0
	global_load_lds_dwordx4 v[172:173], off
	s_mov_b32 m0, s58
	s_nop 0
	global_load_lds_dwordx4 v[174:175], off
	s_nop 0
	s_waitcnt vmcnt(8)
	s_waitcnt lgkmcnt(0)
	s_barrier
; #define PG8_STAGE(bufoff, gbase, voff) do { _Pragma("unroll") for (int _i = 0; _i < 2; ++_i) \
;         __builtin_amdgcn_global_load_lds((const unsigned*)((const char*)(gbase) + (voff)[_i]), (LAS unsigned*)(lds + (bufoff) + ldsw + _i * 8192), 16, 0, 0); } while (0)
; #define PG8_LDA(dst, b, h) do { _Pragma("unroll") for (int m = 0; m < 4; ++m) _Pragma("unroll") for (int k = 0; k < 2; ++k) dst[m][k] = *(const LAS bf16x8*)(lds + PG8_SA(b, h) + aoff + m * 2048 + k * 1024); } while (0)
; #define PG8_LDB(dst, b, h) do { _Pragma("unroll") for (int n = 0; n < 2; ++n) _Pragma("unroll") for (int k = 0; k < 2; ++k) dst[n][k] = *(const LAS bf16x8*)(lds + PG8_SB(b, h) + boff + n * 2048 + k * 1024); } while (0)
; #define PG8_MMA(ai, bj, At, Bt) do { __builtin_amdgcn_s_setprio(1); _Pragma("unroll") for (int m = 0; m < 4; ++m) _Pragma("unroll") for (int n = 0; n < 2; ++n) _Pragma("unroll") for (int k = 0; k < 2; ++k) \
;         acc[ai][bj][m][n] = __builtin_amdgcn_mfma_f32_16x16x32_bf16(Bt[n][k], At[m][k], acc[ai][bj][m][n], 0, 0, 0); __builtin_amdgcn_s_setprio(0); } while (0)
; #define PG8_WAIT_V(n) asm volatile("s_waitcnt vmcnt(" #n ")" ::: "memory")
; #define PG8_WAIT_L(n) asm volatile("s_waitcnt lgkmcnt(" #n ")" ::: "memory")
; #define PG8_BAR __builtin_amdgcn_s_barrier()
; #define PG8_SCHED __builtin_amdgcn_sched_barrier(0)
; template <class Epi>
; __device__ __forceinline__ void gemm_phase(LAS unsigned char* lds, const Gemm g, const StaticOrder& S, const Epi& E, const int tid) {
;     ...
;             PG8_WAIT_V(8); PG8_WAIT_L(0); PG8_BAR; PG8_MMA(1, 0, At, B0); PG8_MMA(1, 1, At, B1); PG8_BAR; PG8_SCHED;
;             PG8_LDB(B0, 1, 0); PG8_LDB(B1, 1, 1); PG8_SCHED; PG8_LDA(At, 1, 0); PG8_STAGE(PG8_SA(0, 1), a2 + hstep, voffA);
;             PG8_WAIT_V(8); PG8_WAIT_L(0); PG8_BAR; PG8_MMA(0, 0, At, B0); PG8_MMA(0, 1, At, B1); PG8_BAR; PG8_SCHED;
	s_setprio 1
	s_waitcnt lgkmcnt(0)
	v_mfma_f32_16x16x32_bf16 v[62:65], v[150:153], v[216:219], v[62:65]
	v_mfma_f32_16x16x32_bf16 v[58:61], v[158:161], v[216:219], v[58:61]
	v_mfma_f32_16x16x32_bf16 v[46:49], v[150:153], v[224:227], v[46:49]
	v_mfma_f32_16x16x32_bf16 v[42:45], v[158:161], v[224:227], v[42:45]
	v_mfma_f32_16x16x32_bf16 v[30:33], v[150:153], v[232:235], v[30:33]
	v_mfma_f32_16x16x32_bf16 v[26:29], v[158:161], v[232:235], v[26:29]
	v_mfma_f32_16x16x32_bf16 v[14:17], v[150:153], v[240:243], v[14:17]
	v_mfma_f32_16x16x32_bf16 v[10:13], v[158:161], v[240:243], v[10:13]
	v_mfma_f32_16x16x32_bf16 v[62:65], v[154:157], v[220:223], v[62:65]
	v_mfma_f32_16x16x32_bf16 v[58:61], v[186:189], v[220:223], v[58:61]
	v_mfma_f32_16x16x32_bf16 v[46:49], v[154:157], v[228:231], v[46:49]
	v_mfma_f32_16x16x32_bf16 v[42:45], v[186:189], v[228:231], v[42:45]
	v_mfma_f32_16x16x32_bf16 v[30:33], v[154:157], v[236:239], v[30:33]
	v_mfma_f32_16x16x32_bf16 v[26:29], v[186:189], v[236:239], v[26:29]
	v_mfma_f32_16x16x32_bf16 v[14:17], v[154:157], v[244:247], v[14:17]
	v_mfma_f32_16x16x32_bf16 v[10:13], v[186:189], v[244:247], v[10:13]
	s_setprio 0
	s_setprio 1
	v_mfma_f32_16x16x32_bf16 v[54:57], v[190:193], v[216:219], v[54:57]
	v_mfma_f32_16x16x32_bf16 v[50:53], v[198:201], v[216:219], v[50:53]
	v_mfma_f32_16x16x32_bf16 v[38:41], v[190:193], v[224:227], v[38:41]
	v_mfma_f32_16x16x32_bf16 v[34:37], v[198:201], v[224:227], v[34:37]
	v_mfma_f32_16x16x32_bf16 v[22:25], v[190:193], v[232:235], v[22:25]
	v_mfma_f32_16x16x32_bf16 v[18:21], v[198:201], v[232:235], v[18:21]
	v_mfma_f32_16x16x32_bf16 v[6:9], v[190:193], v[240:243], v[6:9]
	v_mfma_f32_16x16x32_bf16 v[2:5], v[198:201], v[240:243], v[2:5]
	v_mfma_f32_16x16x32_bf16 v[54:57], v[194:197], v[220:223], v[54:57]
	v_mfma_f32_16x16x32_bf16 v[50:53], v[212:215], v[220:223], v[50:53]
	v_mfma_f32_16x16x32_bf16 v[38:41], v[194:197], v[228:231], v[38:41]
	v_mfma_f32_16x16x32_bf16 v[34:37], v[212:215], v[228:231], v[34:37]
	v_mfma_f32_16x16x32_bf16 v[22:25], v[194:197], v[236:239], v[22:25]
	v_mfma_f32_16x16x32_bf16 v[18:21], v[212:215], v[236:239], v[18:21]
	v_mfma_f32_16x16x32_bf16 v[6:9], v[194:197], v[244:247], v[6:9]
	v_mfma_f32_16x16x32_bf16 v[2:5], v[212:215], v[244:247], v[2:5]
	s_setprio 0
	s_barrier
	s_add_i32 s44, 0, 0x18000
	v_add_u32_e32 v0, s44, v149
	s_add_i32 s45, 0, 0x1c000
	ds_read_b128 v[150:153], v0
	ds_read_b128 v[154:157], v0 offset:1024
	ds_read_b128 v[158:161], v0 offset:2048
	ds_read_b128 v[186:189], v0 offset:3072
	v_add_u32_e32 v0, s45, v149
	ds_read_b128 v[190:193], v0
	ds_read_b128 v[194:197], v0 offset:1024
	ds_read_b128 v[198:201], v0 offset:2048
	ds_read_b128 v[212:215], v0 offset:3072
	s_add_u32 s34, s34, 0x80000
	s_addc_u32 s35, s35, 0
	s_mov_b32 m0, s59
	v_lshl_add_u64 v[176:177], s[34:35], 0, v[130:131]
	ds_read_b128 v[216:219], v184 offset:32768
	global_load_lds_dwordx4 v[176:177], off
	ds_read_b128 v[220:223], v184 offset:33792
	ds_read_b128 v[224:227], v184 offset:34816
	v_lshl_add_u64 v[176:177], s[34:35], 0, v[134:135]
	s_mov_b32 m0, s60
	s_nop 0
	global_load_lds_dwordx4 v[176:177], off
	ds_read_b128 v[228:231], v184 offset:35840
	ds_read_b128 v[232:235], v184 offset:36864
	ds_read_b128 v[236:239], v184 offset:37888
	ds_read_b128 v[240:243], v184 offset:38912
	ds_read_b128 v[244:247], v184 offset:39936
	s_nop 0
	s_waitcnt vmcnt(8)
	s_waitcnt lgkmcnt(0)
	s_barrier
	s_setprio 1
	s_waitcnt lgkmcnt(0)
	v_mfma_f32_16x16x32_bf16 v[126:129], v[150:153], v[216:219], v[126:129]
	v_mfma_f32_16x16x32_bf16 v[122:125], v[158:161], v[216:219], v[122:125]
	v_mfma_f32_16x16x32_bf16 v[110:113], v[150:153], v[224:227], v[110:113]
	v_mfma_f32_16x16x32_bf16 v[106:109], v[158:161], v[224:227], v[106:109]
	v_mfma_f32_16x16x32_bf16 v[94:97], v[150:153], v[232:235], v[94:97]
	v_mfma_f32_16x16x32_bf16 v[90:93], v[158:161], v[232:235], v[90:93]
	v_mfma_f32_16x16x32_bf16 v[78:81], v[150:153], v[240:243], v[78:81]
	v_mfma_f32_16x16x32_bf16 v[74:77], v[158:161], v[240:243], v[74:77]
	v_mfma_f32_16x16x32_bf16 v[126:129], v[154:157], v[220:223], v[126:129]
	v_mfma_f32_16x16x32_bf16 v[122:125], v[186:189], v[220:223], v[122:125]
	v_mfma_f32_16x16x32_bf16 v[110:113], v[154:157], v[228:231], v[110:113]
	v_mfma_f32_16x16x32_bf16 v[106:109], v[186:189], v[228:231], v[106:109]
	v_mfma_f32_16x16x32_bf16 v[94:97], v[154:157], v[236:239], v[94:97]
	v_mfma_f32_16x16x32_bf16 v[90:93], v[186:189], v[236:239], v[90:93]
	v_mfma_f32_16x16x32_bf16 v[78:81], v[154:157], v[244:247], v[78:81]
	v_mfma_f32_16x16x32_bf16 v[74:77], v[186:189], v[244:247], v[74:77]
	s_setprio 0
	s_setprio 1
	v_mfma_f32_16x16x32_bf16 v[118:121], v[190:193], v[216:219], v[118:121]
	v_mfma_f32_16x16x32_bf16 v[114:117], v[198:201], v[216:219], v[114:117]
	v_mfma_f32_16x16x32_bf16 v[102:105], v[190:193], v[224:227], v[102:105]
	v_mfma_f32_16x16x32_bf16 v[98:101], v[198:201], v[224:227], v[98:101]
	v_mfma_f32_16x16x32_bf16 v[86:89], v[190:193], v[232:235], v[86:89]
	v_mfma_f32_16x16x32_bf16 v[82:85], v[198:201], v[232:235], v[82:85]
	v_mfma_f32_16x16x32_bf16 v[70:73], v[190:193], v[240:243], v[70:73]
	v_mfma_f32_16x16x32_bf16 v[66:69], v[198:201], v[240:243], v[66:69]
	v_mfma_f32_16x16x32_bf16 v[118:121], v[194:197], v[220:223], v[118:121]
	v_mfma_f32_16x16x32_bf16 v[114:117], v[212:215], v[220:223], v[114:117]
	v_mfma_f32_16x16x32_bf16 v[102:105], v[194:197], v[228:231], v[102:105]
	v_mfma_f32_16x16x32_bf16 v[98:101], v[212:215], v[228:231], v[98:101]
	v_mfma_f32_16x16x32_bf16 v[86:89], v[194:197], v[236:239], v[86:89]
	v_mfma_f32_16x16x32_bf16 v[82:85], v[212:215], v[236:239], v[82:85]
	v_mfma_f32_16x16x32_bf16 v[70:73], v[194:197], v[244:247], v[70:73]
	v_mfma_f32_16x16x32_bf16 v[66:69], v[212:215], v[244:247], v[66:69]
	s_setprio 0
	s_barrier
; #define PG8_STAGE(bufoff, gbase, voff) do { _Pragma("unroll") for (int _i = 0; _i < 2; ++_i) \
;         __builtin_amdgcn_global_load_lds((const unsigned*)((const char*)(gbase) + (voff)[_i]), (LAS unsigned*)(lds + (bufoff) + ldsw + _i * 8192), 16, 0, 0); } while (0)
; #define PG8_LDA(dst, b, h) do { _Pragma("unroll") for (int m = 0; m < 4; ++m) _Pragma("unroll") for (int k = 0; k < 2; ++k) dst[m][k] = *(const LAS bf16x8*)(lds + PG8_SA(b, h) + aoff + m * 2048 + k * 1024); } while (0)
; #define PG8_MMA(ai, bj, At, Bt) do { __builtin_amdgcn_s_setprio(1); _Pragma("unroll") for (int m = 0; m < 4; ++m) _Pragma("unroll") for (int n = 0; n < 2; ++n) _Pragma("unroll") for (int k = 0; k < 2; ++k) \
;         acc[ai][bj][m][n] = __builtin_amdgcn_mfma_f32_16x16x32_bf16(Bt[n][k], At[m][k], acc[ai][bj][m][n], 0, 0, 0); __builtin_amdgcn_s_setprio(0); } while (0)
; #define PG8_WAIT_V(n) asm volatile("s_waitcnt vmcnt(" #n ")" ::: "memory")
; #define PG8_WAIT_L(n) asm volatile("s_waitcnt lgkmcnt(" #n ")" ::: "memory")
; #define PG8_BAR __builtin_amdgcn_s_barrier()
; #define PG8_SCHED __builtin_amdgcn_sched_barrier(0)
; template <class Epi>
; __device__ __forceinline__ void gemm_phase(LAS unsigned char* lds, const Gemm g, const StaticOrder& S, const Epi& E, const int tid) {
;     ...
;             PG8_LDA(At, 1, 1); PG8_STAGE(PG8_SB(1, 0), b3, voffB); PG8_STAGE(PG8_SB(1, 1), b3 + bhs, voffB); PG8_STAGE(PG8_SA(1, 0), a3, voffA);
;             PG8_WAIT_V(8); PG8_WAIT_L(0); PG8_BAR; PG8_MMA(1, 0, At, B0); PG8_MMA(1, 1, At, B1); PG8_BAR; PG8_SCHED;
;     ...
;         if (ALIGN_EPI) { if (wr == 0) PG8_BAR; }
	s_add_i32 s34, s44, s56
	v_lshl_add_u64 v[162:163], v[162:163], 0, s[70:71]
	s_mov_b32 m0, s34
	ds_read_b128 v[216:219], v184 offset:49152
	global_load_lds_dwordx4 v[162:163], off
	ds_read_b128 v[220:223], v184 offset:50176
	ds_read_b128 v[224:227], v184 offset:51200
	s_add_i32 m0, s34, 0x2000
	s_add_u32 s28, s28, 0x8080
	v_lshl_add_u64 v[162:163], v[248:249], 0, s[70:71]
	s_addc_u32 s29, s29, 0
	s_add_i32 s34, s45, s56
	global_load_lds_dwordx4 v[162:163], off
	ds_read_b128 v[228:231], v184 offset:52224
	ds_read_b128 v[232:235], v184 offset:53248
	v_lshl_add_u64 v[162:163], s[28:29], 0, v[132:133]
	s_mov_b32 m0, s34
	s_nop 0
	global_load_lds_dwordx4 v[162:163], off
	ds_read_b128 v[236:239], v184 offset:54272
	ds_read_b128 v[240:243], v184 offset:55296
	v_lshl_add_u64 v[162:163], s[28:29], 0, v[136:137]
	s_add_i32 m0, s34, 0x2000
	s_nop 0
	global_load_lds_dwordx4 v[162:163], off
	ds_read_b128 v[244:247], v184 offset:56320
	v_lshl_add_u64 v[162:163], v[172:173], 0, s[70:71]
	s_mov_b32 m0, s61
	s_nop 0
	global_load_lds_dwordx4 v[162:163], off
	v_lshl_add_u64 v[162:163], v[174:175], 0, s[70:71]
	s_mov_b32 m0, s62
	s_nop 0
	global_load_lds_dwordx4 v[162:163], off
	s_waitcnt vmcnt(8)
	s_waitcnt lgkmcnt(0)
	s_barrier
	s_setprio 1
	s_waitcnt lgkmcnt(0)
	v_mfma_f32_16x16x32_bf16 v[62:65], v[150:153], v[216:219], v[62:65]
	v_mfma_f32_16x16x32_bf16 v[58:61], v[158:161], v[216:219], v[58:61]
	v_mfma_f32_16x16x32_bf16 v[46:49], v[150:153], v[224:227], v[46:49]
	v_mfma_f32_16x16x32_bf16 v[42:45], v[158:161], v[224:227], v[42:45]
	v_mfma_f32_16x16x32_bf16 v[30:33], v[150:153], v[232:235], v[30:33]
	v_mfma_f32_16x16x32_bf16 v[26:29], v[158:161], v[232:235], v[26:29]
	v_mfma_f32_16x16x32_bf16 v[14:17], v[150:153], v[240:243], v[14:17]
	v_mfma_f32_16x16x32_bf16 v[10:13], v[158:161], v[240:243], v[10:13]
	v_mfma_f32_16x16x32_bf16 v[62:65], v[154:157], v[220:223], v[62:65]
	v_mfma_f32_16x16x32_bf16 v[58:61], v[186:189], v[220:223], v[58:61]
	v_mfma_f32_16x16x32_bf16 v[46:49], v[154:157], v[228:231], v[46:49]
	v_mfma_f32_16x16x32_bf16 v[42:45], v[186:189], v[228:231], v[42:45]
	v_mfma_f32_16x16x32_bf16 v[30:33], v[154:157], v[236:239], v[30:33]
	v_mfma_f32_16x16x32_bf16 v[26:29], v[186:189], v[236:239], v[26:29]
	v_mfma_f32_16x16x32_bf16 v[14:17], v[154:157], v[244:247], v[14:17]
	v_mfma_f32_16x16x32_bf16 v[10:13], v[186:189], v[244:247], v[10:13]
	s_setprio 0
	s_setprio 1
	v_mfma_f32_16x16x32_bf16 v[54:57], v[190:193], v[216:219], v[54:57]
	v_mfma_f32_16x16x32_bf16 v[50:53], v[198:201], v[216:219], v[50:53]
	v_mfma_f32_16x16x32_bf16 v[38:41], v[190:193], v[224:227], v[38:41]
	v_mfma_f32_16x16x32_bf16 v[34:37], v[198:201], v[224:227], v[34:37]
	v_mfma_f32_16x16x32_bf16 v[22:25], v[190:193], v[232:235], v[22:25]
	v_mfma_f32_16x16x32_bf16 v[18:21], v[198:201], v[232:235], v[18:21]
	v_mfma_f32_16x16x32_bf16 v[6:9], v[190:193], v[240:243], v[6:9]
	v_mfma_f32_16x16x32_bf16 v[2:5], v[198:201], v[240:243], v[2:5]
	v_mfma_f32_16x16x32_bf16 v[54:57], v[194:197], v[220:223], v[54:57]
	v_mfma_f32_16x16x32_bf16 v[50:53], v[212:215], v[220:223], v[50:53]
	v_mfma_f32_16x16x32_bf16 v[38:41], v[194:197], v[228:231], v[38:41]
	v_mfma_f32_16x16x32_bf16 v[34:37], v[212:215], v[228:231], v[34:37]
	v_mfma_f32_16x16x32_bf16 v[22:25], v[194:197], v[236:239], v[22:25]
	v_mfma_f32_16x16x32_bf16 v[18:21], v[212:215], v[236:239], v[18:21]
	v_mfma_f32_16x16x32_bf16 v[6:9], v[194:197], v[244:247], v[6:9]
	v_mfma_f32_16x16x32_bf16 v[2:5], v[212:215], v[244:247], v[2:5]
	s_setprio 0
	s_barrier
	s_add_i32 s39, s39, 2
	s_add_u32 s37, s37, 0x100
	s_addc_u32 s38, s38, 0
	s_add_u32 s26, s26, 0x100
	s_addc_u32 s27, s27, 0
	s_cmp_gt_u32 s39, 29
	s_cbranch_scc0 .LBB0_546
	s_and_b64 vcc, exec, s[14:15]
	s_cbranch_vccz .LBB0_549
	s_barrier

; #define PG8_STAGE(bufoff, gbase, voff) do { _Pragma("unroll") for (int _i = 0; _i < 2; ++_i) \
;         __builtin_amdgcn_global_load_lds((const unsigned*)((const char*)(gbase) + (voff)[_i]), (LAS unsigned*)(lds + (bufoff) + ldsw + _i * 8192), 16, 0, 0); } while (0)
; #define PG8_LDA(dst, b, h) do { _Pragma("unroll") for (int m = 0; m < 4; ++m) _Pragma("unroll") for (int k = 0; k < 2; ++k) dst[m][k] = *(const LAS bf16x8*)(lds + PG8_SA(b, h) + aoff + m * 2048 + k * 1024); } while (0)
; #define PG8_LDB(dst, b, h) do { _Pragma("unroll") for (int n = 0; n < 2; ++n) _Pragma("unroll") for (int k = 0; k < 2; ++k) dst[n][k] = *(const LAS bf16x8*)(lds + PG8_SB(b, h) + boff + n * 2048 + k * 1024); } while (0)
; #define PG8_MMA(ai, bj, At, Bt) do { __builtin_amdgcn_s_setprio(1); _Pragma("unroll") for (int m = 0; m < 4; ++m) _Pragma("unroll") for (int n = 0; n < 2; ++n) _Pragma("unroll") for (int k = 0; k < 2; ++k) \
;         acc[ai][bj][m][n] = __builtin_amdgcn_mfma_f32_16x16x32_bf16(Bt[n][k], At[m][k], acc[ai][bj][m][n], 0, 0, 0); __builtin_amdgcn_s_setprio(0); } while (0)
; #define PG8_WAIT_V(n) asm volatile("s_waitcnt vmcnt(" #n ")" ::: "memory")
; #define PG8_WAIT_L(n) asm volatile("s_waitcnt lgkmcnt(" #n ")" ::: "memory")
; #define PG8_BAR __builtin_amdgcn_s_barrier()
; template <class Epi>
; __device__ __forceinline__ void gemm_phase(LAS unsigned char* lds, const Gemm g, const StaticOrder& S, const Epi& E, const int tid) {
;     ...
;             const char* a2 = last ? nA : (s2 ? cA2 + (size_t)(t + 2 - nt) * kstep : cA + (size_t)(t + 2) * kstep);
;             const char* b2 = last ? nB : (s2 ? cB2 + (size_t)(t + 2 - nt) * kstep : cB + (size_t)(t + 2) * kstep);
;             const char* a3 = a2 + kstep; const char* b3 = b2 + kstep;
;             if constexpr (Epi::TWO) { if (t == nt) E.mid(acc, cur, wr, wc, fr, fq); }
;             if constexpr (SP2) {
;             PG8_LDB(B0, 0, 0); PG8_LDB(B1, 0, 1); PG8_SCHED; PG8_LDA(At, 0, 0); PG8_STAGE(PG8_SA(1, 1), a1 + hstep, voffA);
;             PG8_WAIT_V(8); PG8_WAIT_L(0); PG8_BAR; PG8_MMA(0, 0, At, B0); PG8_MMA(0, 1, At, B1); PG8_BAR; PG8_SCHED;
;             PG8_LDA(At, 0, 1); PG8_STAGE(PG8_SB(0, 0), b2, voffB); PG8_STAGE(PG8_SB(0, 1), b2 + bhs, voffB); PG8_STAGE(PG8_SA(0, 0), a2, voffA);
;             PG8_WAIT_V(8); PG8_WAIT_L(0); PG8_BAR; PG8_MMA(1, 0, At, B0); PG8_MMA(1, 1, At, B1); PG8_BAR; PG8_SCHED;
.LBB0_844:
	s_add_u32 s28, s26, 0xfff80080
	s_addc_u32 s29, s27, -1
	s_add_i32 s48, 0, 0x10000
	s_cmp_eq_u32 s47, 28
	s_cselect_b32 s31, s15, s29
	s_cselect_b32 s30, s43, s28
	v_add_u32_e32 v145, s48, v142
	s_cselect_b32 s29, s13, s46
	s_cselect_b32 s28, s44, s45
	s_add_i32 s50, 0, 0x14000
	ds_read_b128 v[146:149], v145
	ds_read_b128 v[150:153], v145 offset:1024
	ds_read_b128 v[154:157], v145 offset:2048
	ds_read_b128 v[158:161], v145 offset:3072
	v_add_u32_e32 v145, s50, v142
	ds_read_b128 v[162:165], v145
	ds_read_b128 v[166:169], v145 offset:1024
	ds_read_b128 v[178:181], v145 offset:2048
	ds_read_b128 v[182:185], v145 offset:3072
	v_lshl_add_u64 v[172:173], s[26:27], 0, v[138:139]
	s_add_i32 m0, s23, 0xc000
	ds_read_b128 v[186:189], v144
	global_load_lds_dwordx4 v[172:173], off
	ds_read_b128 v[190:193], v144 offset:1024
	ds_read_b128 v[194:197], v144 offset:2048
	v_lshl_add_u64 v[172:173], s[26:27], 0, v[136:137]
	s_add_i32 m0, s23, 0xe000
	s_nop 0
	global_load_lds_dwordx4 v[172:173], off
	ds_read_b128 v[198:201], v144 offset:3072
	ds_read_b128 v[212:215], v144 offset:4096
	ds_read_b128 v[216:219], v144 offset:5120
	ds_read_b128 v[220:223], v144 offset:6144
	ds_read_b128 v[224:227], v144 offset:7168
	s_waitcnt vmcnt(8)
	s_waitcnt lgkmcnt(0)
	s_barrier
	s_setprio 1
	s_waitcnt lgkmcnt(0)
	v_mfma_f32_16x16x32_bf16 v[126:129], v[146:149], v[186:189], v[126:129]
	v_mfma_f32_16x16x32_bf16 v[122:125], v[154:157], v[186:189], v[122:125]
	v_mfma_f32_16x16x32_bf16 v[118:121], v[146:149], v[194:197], v[118:121]
	v_mfma_f32_16x16x32_bf16 v[110:113], v[154:157], v[194:197], v[110:113]
	v_mfma_f32_16x16x32_bf16 v[102:105], v[146:149], v[212:215], v[102:105]
	v_mfma_f32_16x16x32_bf16 v[94:97], v[154:157], v[212:215], v[94:97]
	v_mfma_f32_16x16x32_bf16 v[86:89], v[146:149], v[220:223], v[86:89]
	v_mfma_f32_16x16x32_bf16 v[78:81], v[154:157], v[220:223], v[78:81]
	v_mfma_f32_16x16x32_bf16 v[126:129], v[150:153], v[190:193], v[126:129]
	v_mfma_f32_16x16x32_bf16 v[122:125], v[158:161], v[190:193], v[122:125]
	v_mfma_f32_16x16x32_bf16 v[118:121], v[150:153], v[198:201], v[118:121]
	v_mfma_f32_16x16x32_bf16 v[110:113], v[158:161], v[198:201], v[110:113]
	v_mfma_f32_16x16x32_bf16 v[102:105], v[150:153], v[216:219], v[102:105]
	v_mfma_f32_16x16x32_bf16 v[94:97], v[158:161], v[216:219], v[94:97]
	v_mfma_f32_16x16x32_bf16 v[86:89], v[150:153], v[224:227], v[86:89]
	v_mfma_f32_16x16x32_bf16 v[78:81], v[158:161], v[224:227], v[78:81]
	s_setprio 0
	s_setprio 1
	v_mfma_f32_16x16x32_bf16 v[114:117], v[162:165], v[186:189], v[114:117]
	v_mfma_f32_16x16x32_bf16 v[106:109], v[178:181], v[186:189], v[106:109]
	v_mfma_f32_16x16x32_bf16 v[98:101], v[162:165], v[194:197], v[98:101]
	v_mfma_f32_16x16x32_bf16 v[90:93], v[178:181], v[194:197], v[90:93]
	v_mfma_f32_16x16x32_bf16 v[82:85], v[162:165], v[212:215], v[82:85]
	v_mfma_f32_16x16x32_bf16 v[74:77], v[178:181], v[212:215], v[74:77]
	v_mfma_f32_16x16x32_bf16 v[70:73], v[162:165], v[220:223], v[70:73]
	v_mfma_f32_16x16x32_bf16 v[66:69], v[178:181], v[220:223], v[66:69]
	v_mfma_f32_16x16x32_bf16 v[114:117], v[166:169], v[190:193], v[114:117]
	v_mfma_f32_16x16x32_bf16 v[106:109], v[182:185], v[190:193], v[106:109]
	v_mfma_f32_16x16x32_bf16 v[98:101], v[166:169], v[198:201], v[98:101]
	v_mfma_f32_16x16x32_bf16 v[90:93], v[182:185], v[198:201], v[90:93]
	v_mfma_f32_16x16x32_bf16 v[82:85], v[166:169], v[216:219], v[82:85]
	v_mfma_f32_16x16x32_bf16 v[74:77], v[182:185], v[216:219], v[74:77]
	v_mfma_f32_16x16x32_bf16 v[70:73], v[166:169], v[224:227], v[70:73]
	v_mfma_f32_16x16x32_bf16 v[66:69], v[182:185], v[224:227], v[66:69]
	s_setprio 0
	s_barrier
	s_add_i32 s48, s48, s37
	v_lshl_add_u64 v[172:173], s[28:29], 0, v[0:1]
	s_mov_b32 m0, s48
	ds_read_b128 v[186:189], v144 offset:16384
	global_load_lds_dwordx4 v[172:173], off
	ds_read_b128 v[190:193], v144 offset:17408
	ds_read_b128 v[194:197], v144 offset:18432
	s_add_i32 m0, s48, 0x2000
	s_add_u32 s48, s28, 0x8000
	v_lshl_add_u64 v[174:175], s[28:29], 0, v[134:135]
	s_addc_u32 s49, s29, 0
	s_add_i32 s50, s50, s37
	global_load_lds_dwordx4 v[174:175], off
	ds_read_b128 v[198:201], v144 offset:19456
	ds_read_b128 v[212:215], v144 offset:20480
	v_lshl_add_u64 v[176:177], s[48:49], 0, v[0:1]
	s_mov_b32 m0, s50
	v_lshl_add_u64 v[228:229], s[30:31], 0, v[132:133]
	global_load_lds_dwordx4 v[176:177], off
	ds_read_b128 v[216:219], v144 offset:21504
	ds_read_b128 v[220:223], v144 offset:22528
	v_lshl_add_u64 v[176:177], s[48:49], 0, v[134:135]
	s_add_i32 m0, s50, 0x2000
	s_nop 0
	global_load_lds_dwordx4 v[176:177], off
	ds_read_b128 v[224:227], v144 offset:23552
	v_lshl_add_u64 v[176:177], s[30:31], 0, v[130:131]
	s_mov_b32 m0, s23
	s_nop 0
	global_load_lds_dwordx4 v[176:177], off
	s_mov_b32 m0, s25
	s_nop 0
	global_load_lds_dwordx4 v[228:229], off
	s_nop 0
	s_waitcnt vmcnt(8)
	s_waitcnt lgkmcnt(0)
	s_barrier
; #define PG8_STAGE(bufoff, gbase, voff) do { _Pragma("unroll") for (int _i = 0; _i < 2; ++_i) \
;         __builtin_amdgcn_global_load_lds((const unsigned*)((const char*)(gbase) + (voff)[_i]), (LAS unsigned*)(lds + (bufoff) + ldsw + _i * 8192), 16, 0, 0); } while (0)
; #define PG8_LDA(dst, b, h) do { _Pragma("unroll") for (int m = 0; m < 4; ++m) _Pragma("unroll") for (int k = 0; k < 2; ++k) dst[m][k] = *(const LAS bf16x8*)(lds + PG8_SA(b, h) + aoff + m * 2048 + k * 1024); } while (0)
; #define PG8_LDB(dst, b, h) do { _Pragma("unroll") for (int n = 0; n < 2; ++n) _Pragma("unroll") for (int k = 0; k < 2; ++k) dst[n][k] = *(const LAS bf16x8*)(lds + PG8_SB(b, h) + boff + n * 2048 + k * 1024); } while (0)
; #define PG8_MMA(ai, bj, At, Bt) do { __builtin_amdgcn_s_setprio(1); _Pragma("unroll") for (int m = 0; m < 4; ++m) _Pragma("unroll") for (int n = 0; n < 2; ++n) _Pragma("unroll") for (int k = 0; k < 2; ++k) \
;         acc[ai][bj][m][n] = __builtin_amdgcn_mfma_f32_16x16x32_bf16(Bt[n][k], At[m][k], acc[ai][bj][m][n], 0, 0, 0); __builtin_amdgcn_s_setprio(0); } while (0)
; #define PG8_WAIT_V(n) asm volatile("s_waitcnt vmcnt(" #n ")" ::: "memory")
; #define PG8_WAIT_L(n) asm volatile("s_waitcnt lgkmcnt(" #n ")" ::: "memory")
; #define PG8_BAR __builtin_amdgcn_s_barrier()
; #define PG8_SCHED __builtin_amdgcn_sched_barrier(0)
; template <class Epi>
; __device__ __forceinline__ void gemm_phase(LAS unsigned char* lds, const Gemm g, const StaticOrder& S, const Epi& E, const int tid) {
;     ...
;             PG8_WAIT_V(8); PG8_WAIT_L(0); PG8_BAR; PG8_MMA(1, 0, At, B0); PG8_MMA(1, 1, At, B1); PG8_BAR; PG8_SCHED;
;             PG8_LDB(B0, 1, 0); PG8_LDB(B1, 1, 1); PG8_SCHED; PG8_LDA(At, 1, 0); PG8_STAGE(PG8_SA(0, 1), a2 + hstep, voffA);
;             PG8_WAIT_V(8); PG8_WAIT_L(0); PG8_BAR; PG8_MMA(0, 0, At, B0); PG8_MMA(0, 1, At, B1); PG8_BAR; PG8_SCHED;
	s_setprio 1
	s_waitcnt lgkmcnt(0)
	v_mfma_f32_16x16x32_bf16 v[62:65], v[146:149], v[186:189], v[62:65]
	v_mfma_f32_16x16x32_bf16 v[58:61], v[154:157], v[186:189], v[58:61]
	v_mfma_f32_16x16x32_bf16 v[54:57], v[146:149], v[194:197], v[54:57]
	v_mfma_f32_16x16x32_bf16 v[46:49], v[154:157], v[194:197], v[46:49]
	v_mfma_f32_16x16x32_bf16 v[38:41], v[146:149], v[212:215], v[38:41]
	v_mfma_f32_16x16x32_bf16 v[30:33], v[154:157], v[212:215], v[30:33]
	v_mfma_f32_16x16x32_bf16 v[22:25], v[146:149], v[220:223], v[22:25]
	v_mfma_f32_16x16x32_bf16 v[14:17], v[154:157], v[220:223], v[14:17]
	v_mfma_f32_16x16x32_bf16 v[62:65], v[150:153], v[190:193], v[62:65]
	v_mfma_f32_16x16x32_bf16 v[58:61], v[158:161], v[190:193], v[58:61]
	v_mfma_f32_16x16x32_bf16 v[54:57], v[150:153], v[198:201], v[54:57]
	v_mfma_f32_16x16x32_bf16 v[46:49], v[158:161], v[198:201], v[46:49]
	v_mfma_f32_16x16x32_bf16 v[38:41], v[150:153], v[216:219], v[38:41]
	v_mfma_f32_16x16x32_bf16 v[30:33], v[158:161], v[216:219], v[30:33]
	v_mfma_f32_16x16x32_bf16 v[22:25], v[150:153], v[224:227], v[22:25]
	v_mfma_f32_16x16x32_bf16 v[14:17], v[158:161], v[224:227], v[14:17]
	s_setprio 0
	s_setprio 1
	v_mfma_f32_16x16x32_bf16 v[50:53], v[162:165], v[186:189], v[50:53]
	v_mfma_f32_16x16x32_bf16 v[42:45], v[178:181], v[186:189], v[42:45]
	v_mfma_f32_16x16x32_bf16 v[34:37], v[162:165], v[194:197], v[34:37]
	v_mfma_f32_16x16x32_bf16 v[26:29], v[178:181], v[194:197], v[26:29]
	v_mfma_f32_16x16x32_bf16 v[18:21], v[162:165], v[212:215], v[18:21]
	v_mfma_f32_16x16x32_bf16 v[10:13], v[178:181], v[212:215], v[10:13]
	v_mfma_f32_16x16x32_bf16 v[6:9], v[162:165], v[220:223], v[6:9]
	v_mfma_f32_16x16x32_bf16 v[2:5], v[178:181], v[220:223], v[2:5]
	v_mfma_f32_16x16x32_bf16 v[50:53], v[166:169], v[190:193], v[50:53]
	v_mfma_f32_16x16x32_bf16 v[42:45], v[182:185], v[190:193], v[42:45]
	v_mfma_f32_16x16x32_bf16 v[34:37], v[166:169], v[198:201], v[34:37]
	v_mfma_f32_16x16x32_bf16 v[26:29], v[182:185], v[198:201], v[26:29]
	v_mfma_f32_16x16x32_bf16 v[18:21], v[166:169], v[216:219], v[18:21]
	v_mfma_f32_16x16x32_bf16 v[10:13], v[182:185], v[216:219], v[10:13]
	v_mfma_f32_16x16x32_bf16 v[6:9], v[166:169], v[224:227], v[6:9]
	v_mfma_f32_16x16x32_bf16 v[2:5], v[182:185], v[224:227], v[2:5]
	s_setprio 0
	s_barrier
	s_add_i32 s48, 0, 0x18000
	v_add_u32_e32 v145, s48, v142
	s_add_i32 s49, 0, 0x1c000
	ds_read_b128 v[146:149], v145
	ds_read_b128 v[150:153], v145 offset:1024
	ds_read_b128 v[154:157], v145 offset:2048
	ds_read_b128 v[158:161], v145 offset:3072
	v_add_u32_e32 v145, s49, v142
	ds_read_b128 v[162:165], v145
	ds_read_b128 v[166:169], v145 offset:1024
	ds_read_b128 v[178:181], v145 offset:2048
	ds_read_b128 v[182:185], v145 offset:3072
	s_add_u32 s30, s30, 0x80000
	s_addc_u32 s31, s31, 0
	s_mov_b32 m0, s38
	v_lshl_add_u64 v[230:231], s[30:31], 0, v[130:131]
	ds_read_b128 v[186:189], v144 offset:32768
	global_load_lds_dwordx4 v[230:231], off
	ds_read_b128 v[190:193], v144 offset:33792
	ds_read_b128 v[194:197], v144 offset:34816
	v_lshl_add_u64 v[230:231], s[30:31], 0, v[132:133]
	s_mov_b32 m0, s39
	s_nop 0
	global_load_lds_dwordx4 v[230:231], off
	ds_read_b128 v[198:201], v144 offset:35840
	ds_read_b128 v[212:215], v144 offset:36864
	ds_read_b128 v[216:219], v144 offset:37888
	ds_read_b128 v[220:223], v144 offset:38912
	ds_read_b128 v[224:227], v144 offset:39936
	s_nop 0
	s_waitcnt vmcnt(8)
	s_waitcnt lgkmcnt(0)
	s_barrier
	s_setprio 1
	s_waitcnt lgkmcnt(0)
	v_mfma_f32_16x16x32_bf16 v[126:129], v[146:149], v[186:189], v[126:129]
	v_mfma_f32_16x16x32_bf16 v[122:125], v[154:157], v[186:189], v[122:125]
	v_mfma_f32_16x16x32_bf16 v[118:121], v[146:149], v[194:197], v[118:121]
	v_mfma_f32_16x16x32_bf16 v[110:113], v[154:157], v[194:197], v[110:113]
	v_mfma_f32_16x16x32_bf16 v[102:105], v[146:149], v[212:215], v[102:105]
	v_mfma_f32_16x16x32_bf16 v[94:97], v[154:157], v[212:215], v[94:97]
	v_mfma_f32_16x16x32_bf16 v[86:89], v[146:149], v[220:223], v[86:89]
	v_mfma_f32_16x16x32_bf16 v[78:81], v[154:157], v[220:223], v[78:81]
	v_mfma_f32_16x16x32_bf16 v[126:129], v[150:153], v[190:193], v[126:129]
	v_mfma_f32_16x16x32_bf16 v[122:125], v[158:161], v[190:193], v[122:125]
	v_mfma_f32_16x16x32_bf16 v[118:121], v[150:153], v[198:201], v[118:121]
	v_mfma_f32_16x16x32_bf16 v[110:113], v[158:161], v[198:201], v[110:113]
	v_mfma_f32_16x16x32_bf16 v[102:105], v[150:153], v[216:219], v[102:105]
	v_mfma_f32_16x16x32_bf16 v[94:97], v[158:161], v[216:219], v[94:97]
	v_mfma_f32_16x16x32_bf16 v[86:89], v[150:153], v[224:227], v[86:89]
	v_mfma_f32_16x16x32_bf16 v[78:81], v[158:161], v[224:227], v[78:81]
	s_setprio 0
	s_setprio 1
	v_mfma_f32_16x16x32_bf16 v[114:117], v[162:165], v[186:189], v[114:117]
	v_mfma_f32_16x16x32_bf16 v[106:109], v[178:181], v[186:189], v[106:109]
	v_mfma_f32_16x16x32_bf16 v[98:101], v[162:165], v[194:197], v[98:101]
	v_mfma_f32_16x16x32_bf16 v[90:93], v[178:181], v[194:197], v[90:93]
	v_mfma_f32_16x16x32_bf16 v[82:85], v[162:165], v[212:215], v[82:85]
	v_mfma_f32_16x16x32_bf16 v[74:77], v[178:181], v[212:215], v[74:77]
	v_mfma_f32_16x16x32_bf16 v[70:73], v[162:165], v[220:223], v[70:73]
	v_mfma_f32_16x16x32_bf16 v[66:69], v[178:181], v[220:223], v[66:69]
	v_mfma_f32_16x16x32_bf16 v[114:117], v[166:169], v[190:193], v[114:117]
	v_mfma_f32_16x16x32_bf16 v[106:109], v[182:185], v[190:193], v[106:109]
	v_mfma_f32_16x16x32_bf16 v[98:101], v[166:169], v[198:201], v[98:101]
	v_mfma_f32_16x16x32_bf16 v[90:93], v[182:185], v[198:201], v[90:93]
	v_mfma_f32_16x16x32_bf16 v[82:85], v[166:169], v[216:219], v[82:85]
	v_mfma_f32_16x16x32_bf16 v[74:77], v[182:185], v[216:219], v[74:77]
	v_mfma_f32_16x16x32_bf16 v[70:73], v[166:169], v[224:227], v[70:73]
	v_mfma_f32_16x16x32_bf16 v[66:69], v[182:185], v[224:227], v[66:69]
	s_setprio 0
	s_barrier
; #define PG8_STAGE(bufoff, gbase, voff) do { _Pragma("unroll") for (int _i = 0; _i < 2; ++_i) \
;         __builtin_amdgcn_global_load_lds((const unsigned*)((const char*)(gbase) + (voff)[_i]), (LAS unsigned*)(lds + (bufoff) + ldsw + _i * 8192), 16, 0, 0); } while (0)
; #define PG8_LDA(dst, b, h) do { _Pragma("unroll") for (int m = 0; m < 4; ++m) _Pragma("unroll") for (int k = 0; k < 2; ++k) dst[m][k] = *(const LAS bf16x8*)(lds + PG8_SA(b, h) + aoff + m * 2048 + k * 1024); } while (0)
; #define PG8_MMA(ai, bj, At, Bt) do { __builtin_amdgcn_s_setprio(1); _Pragma("unroll") for (int m = 0; m < 4; ++m) _Pragma("unroll") for (int n = 0; n < 2; ++n) _Pragma("unroll") for (int k = 0; k < 2; ++k) \
;         acc[ai][bj][m][n] = __builtin_amdgcn_mfma_f32_16x16x32_bf16(Bt[n][k], At[m][k], acc[ai][bj][m][n], 0, 0, 0); __builtin_amdgcn_s_setprio(0); } while (0)
; #define PG8_WAIT_V(n) asm volatile("s_waitcnt vmcnt(" #n ")" ::: "memory")
; #define PG8_WAIT_L(n) asm volatile("s_waitcnt lgkmcnt(" #n ")" ::: "memory")
; #define PG8_BAR __builtin_amdgcn_s_barrier()
; #define PG8_SCHED __builtin_amdgcn_sched_barrier(0)
; template <class Epi>
; __device__ __forceinline__ void gemm_phase(LAS unsigned char* lds, const Gemm g, const StaticOrder& S, const Epi& E, const int tid) {
;     ...
;             PG8_LDA(At, 1, 1); PG8_STAGE(PG8_SB(1, 0), b3, voffB); PG8_STAGE(PG8_SB(1, 1), b3 + bhs, voffB); PG8_STAGE(PG8_SA(1, 0), a3, voffA);
;             PG8_WAIT_V(8); PG8_WAIT_L(0); PG8_BAR; PG8_MMA(1, 0, At, B0); PG8_MMA(1, 1, At, B1); PG8_BAR; PG8_SCHED;
;     ...
;         if (ALIGN_EPI) { if (wr == 0) PG8_BAR; }
	s_add_i32 s30, s48, s37
	v_lshl_add_u64 v[172:173], v[172:173], 0, s[70:71]
	s_mov_b32 m0, s30
	ds_read_b128 v[186:189], v144 offset:49152
	global_load_lds_dwordx4 v[172:173], off
	ds_read_b128 v[190:193], v144 offset:50176
	ds_read_b128 v[194:197], v144 offset:51200
	s_add_i32 m0, s30, 0x2000
	s_add_u32 s28, s28, 0x8080
	v_lshl_add_u64 v[172:173], v[174:175], 0, s[70:71]
	s_addc_u32 s29, s29, 0
	s_add_i32 s30, s49, s37
	global_load_lds_dwordx4 v[172:173], off
	ds_read_b128 v[198:201], v144 offset:52224
	ds_read_b128 v[212:215], v144 offset:53248
	v_lshl_add_u64 v[172:173], s[28:29], 0, v[0:1]
	s_mov_b32 m0, s30
	s_nop 0
	global_load_lds_dwordx4 v[172:173], off
	ds_read_b128 v[216:219], v144 offset:54272
	ds_read_b128 v[220:223], v144 offset:55296
	v_lshl_add_u64 v[172:173], s[28:29], 0, v[134:135]
	s_add_i32 m0, s30, 0x2000
	s_nop 0
	global_load_lds_dwordx4 v[172:173], off
	ds_read_b128 v[224:227], v144 offset:56320
	v_lshl_add_u64 v[172:173], v[176:177], 0, s[70:71]
	s_mov_b32 m0, s40
	s_nop 0
	global_load_lds_dwordx4 v[172:173], off
	v_lshl_add_u64 v[172:173], v[228:229], 0, s[70:71]
	s_mov_b32 m0, s41
	s_nop 0
	global_load_lds_dwordx4 v[172:173], off
	s_waitcnt vmcnt(8)
	s_waitcnt lgkmcnt(0)
	s_barrier
	s_setprio 1
	s_waitcnt lgkmcnt(0)
	v_mfma_f32_16x16x32_bf16 v[62:65], v[146:149], v[186:189], v[62:65]
	v_mfma_f32_16x16x32_bf16 v[58:61], v[154:157], v[186:189], v[58:61]
	v_mfma_f32_16x16x32_bf16 v[54:57], v[146:149], v[194:197], v[54:57]
	v_mfma_f32_16x16x32_bf16 v[46:49], v[154:157], v[194:197], v[46:49]
	v_mfma_f32_16x16x32_bf16 v[38:41], v[146:149], v[212:215], v[38:41]
	v_mfma_f32_16x16x32_bf16 v[30:33], v[154:157], v[212:215], v[30:33]
	v_mfma_f32_16x16x32_bf16 v[22:25], v[146:149], v[220:223], v[22:25]
	v_mfma_f32_16x16x32_bf16 v[14:17], v[154:157], v[220:223], v[14:17]
	v_mfma_f32_16x16x32_bf16 v[62:65], v[150:153], v[190:193], v[62:65]
	v_mfma_f32_16x16x32_bf16 v[58:61], v[158:161], v[190:193], v[58:61]
	v_mfma_f32_16x16x32_bf16 v[54:57], v[150:153], v[198:201], v[54:57]
	v_mfma_f32_16x16x32_bf16 v[46:49], v[158:161], v[198:201], v[46:49]
	v_mfma_f32_16x16x32_bf16 v[38:41], v[150:153], v[216:219], v[38:41]
	v_mfma_f32_16x16x32_bf16 v[30:33], v[158:161], v[216:219], v[30:33]
	v_mfma_f32_16x16x32_bf16 v[22:25], v[150:153], v[224:227], v[22:25]
	v_mfma_f32_16x16x32_bf16 v[14:17], v[158:161], v[224:227], v[14:17]
	s_setprio 0
	s_setprio 1
	v_mfma_f32_16x16x32_bf16 v[50:53], v[162:165], v[186:189], v[50:53]
	v_mfma_f32_16x16x32_bf16 v[42:45], v[178:181], v[186:189], v[42:45]
	v_mfma_f32_16x16x32_bf16 v[34:37], v[162:165], v[194:197], v[34:37]
	v_mfma_f32_16x16x32_bf16 v[26:29], v[178:181], v[194:197], v[26:29]
	v_mfma_f32_16x16x32_bf16 v[18:21], v[162:165], v[212:215], v[18:21]
	v_mfma_f32_16x16x32_bf16 v[10:13], v[178:181], v[212:215], v[10:13]
	v_mfma_f32_16x16x32_bf16 v[6:9], v[162:165], v[220:223], v[6:9]
	v_mfma_f32_16x16x32_bf16 v[2:5], v[178:181], v[220:223], v[2:5]
	v_mfma_f32_16x16x32_bf16 v[50:53], v[166:169], v[190:193], v[50:53]
	v_mfma_f32_16x16x32_bf16 v[42:45], v[182:185], v[190:193], v[42:45]
	v_mfma_f32_16x16x32_bf16 v[34:37], v[166:169], v[198:201], v[34:37]
	v_mfma_f32_16x16x32_bf16 v[26:29], v[182:185], v[198:201], v[26:29]
	v_mfma_f32_16x16x32_bf16 v[18:21], v[166:169], v[216:219], v[18:21]
	v_mfma_f32_16x16x32_bf16 v[10:13], v[182:185], v[216:219], v[10:13]
	v_mfma_f32_16x16x32_bf16 v[6:9], v[166:169], v[224:227], v[6:9]
	v_mfma_f32_16x16x32_bf16 v[2:5], v[182:185], v[224:227], v[2:5]
	s_setprio 0
	s_barrier
	s_add_i32 s47, s47, 2
	s_add_u32 s45, s45, 0x100
	s_addc_u32 s46, s46, 0
	s_add_u32 s26, s26, 0x100
	s_addc_u32 s27, s27, 0
	s_cmp_gt_u32 s47, 29
	s_cbranch_scc0 .LBB0_844
	s_and_b64 vcc, exec, s[10:11]
	s_cbranch_vccz .LBB0_847
	s_barrier

; #define PG8_STAGE(bufoff, gbase, voff) do { _Pragma("unroll") for (int _i = 0; _i < 2; ++_i) \
;         __builtin_amdgcn_global_load_lds((const unsigned*)((const char*)(gbase) + (voff)[_i]), (LAS unsigned*)(lds + (bufoff) + ldsw + _i * 8192), 16, 0, 0); } while (0)
; #define PG8_LDA(dst, b, h) do { _Pragma("unroll") for (int m = 0; m < 4; ++m) _Pragma("unroll") for (int k = 0; k < 2; ++k) dst[m][k] = *(const LAS bf16x8*)(lds + PG8_SA(b, h) + aoff + m * 2048 + k * 1024); } while (0)
; #define PG8_LDB(dst, b, h) do { _Pragma("unroll") for (int n = 0; n < 2; ++n) _Pragma("unroll") for (int k = 0; k < 2; ++k) dst[n][k] = *(const LAS bf16x8*)(lds + PG8_SB(b, h) + boff + n * 2048 + k * 1024); } while (0)
; #define PG8_MMA(ai, bj, At, Bt) do { __builtin_amdgcn_s_setprio(1); _Pragma("unroll") for (int m = 0; m < 4; ++m) _Pragma("unroll") for (int n = 0; n < 2; ++n) _Pragma("unroll") for (int k = 0; k < 2; ++k) \
;         acc[ai][bj][m][n] = __builtin_amdgcn_mfma_f32_16x16x32_bf16(Bt[n][k], At[m][k], acc[ai][bj][m][n], 0, 0, 0); __builtin_amdgcn_s_setprio(0); } while (0)
; #define PG8_WAIT_V(n) asm volatile("s_waitcnt vmcnt(" #n ")" ::: "memory")
; #define PG8_WAIT_L(n) asm volatile("s_waitcnt lgkmcnt(" #n ")" ::: "memory")
; #define PG8_BAR __builtin_amdgcn_s_barrier()
; template <class Epi>
; __device__ __forceinline__ void gemm_phase(LAS unsigned char* lds, const Gemm g, const StaticOrder& S, const Epi& E, const int tid) {
;     ...
;             const char* a2 = last ? nA : (s2 ? cA2 + (size_t)(t + 2 - nt) * kstep : cA + (size_t)(t + 2) * kstep);
;             const char* b2 = last ? nB : (s2 ? cB2 + (size_t)(t + 2 - nt) * kstep : cB + (size_t)(t + 2) * kstep);
;             const char* a3 = a2 + kstep; const char* b3 = b2 + kstep;
;             if constexpr (Epi::TWO) { if (t == nt) E.mid(acc, cur, wr, wc, fr, fq); }
;             if constexpr (SP2) {
;             PG8_LDB(B0, 0, 0); PG8_LDB(B1, 0, 1); PG8_SCHED; PG8_LDA(At, 0, 0); PG8_STAGE(PG8_SA(1, 1), a1 + hstep, voffA);
;             PG8_WAIT_V(8); PG8_WAIT_L(0); PG8_BAR; PG8_MMA(0, 0, At, B0); PG8_MMA(0, 1, At, B1); PG8_BAR; PG8_SCHED;
;             PG8_LDA(At, 0, 1); PG8_STAGE(PG8_SB(0, 0), b2, voffB); PG8_STAGE(PG8_SB(0, 1), b2 + bhs, voffB); PG8_STAGE(PG8_SA(0, 0), a2, voffA);
;             PG8_WAIT_V(8); PG8_WAIT_L(0); PG8_BAR; PG8_MMA(1, 0, At, B0); PG8_MMA(1, 1, At, B1); PG8_BAR; PG8_SCHED;
.LBB0_861:
	s_add_u32 s30, s28, 0xfff80080
	s_addc_u32 s31, s29, -1
	s_add_i32 s51, 0, 0x10000
	s_cmp_eq_u32 s50, 28
	s_cselect_b32 s35, s17, s31
	s_cselect_b32 s34, s46, s30
	v_add_u32_e32 v145, s51, v142
	s_cselect_b32 s31, s15, s49
	s_cselect_b32 s30, s47, s48
	s_add_i32 s54, 0, 0x14000
	ds_read_b128 v[146:149], v145
	ds_read_b128 v[150:153], v145 offset:1024
	ds_read_b128 v[154:157], v145 offset:2048
	ds_read_b128 v[158:161], v145 offset:3072
	v_add_u32_e32 v145, s54, v142
	ds_read_b128 v[162:165], v145
	ds_read_b128 v[166:169], v145 offset:1024
	ds_read_b128 v[178:181], v145 offset:2048
	ds_read_b128 v[182:185], v145 offset:3072
	v_lshl_add_u64 v[172:173], s[28:29], 0, v[138:139]
	s_add_i32 m0, s25, 0xc000
	ds_read_b128 v[186:189], v144
	global_load_lds_dwordx4 v[172:173], off
	ds_read_b128 v[190:193], v144 offset:1024
	ds_read_b128 v[194:197], v144 offset:2048
	v_lshl_add_u64 v[172:173], s[28:29], 0, v[136:137]
	s_add_i32 m0, s25, 0xe000
	s_nop 0
	global_load_lds_dwordx4 v[172:173], off
	ds_read_b128 v[198:201], v144 offset:3072
	ds_read_b128 v[212:215], v144 offset:4096
	ds_read_b128 v[216:219], v144 offset:5120
	ds_read_b128 v[220:223], v144 offset:6144
	ds_read_b128 v[224:227], v144 offset:7168
	s_waitcnt vmcnt(8)
	s_waitcnt lgkmcnt(0)
	s_barrier
	s_setprio 1
	s_waitcnt lgkmcnt(0)
	v_mfma_f32_16x16x32_bf16 v[126:129], v[146:149], v[186:189], v[126:129]
	v_mfma_f32_16x16x32_bf16 v[122:125], v[154:157], v[186:189], v[122:125]
	v_mfma_f32_16x16x32_bf16 v[118:121], v[146:149], v[194:197], v[118:121]
	v_mfma_f32_16x16x32_bf16 v[110:113], v[154:157], v[194:197], v[110:113]
	v_mfma_f32_16x16x32_bf16 v[102:105], v[146:149], v[212:215], v[102:105]
	v_mfma_f32_16x16x32_bf16 v[94:97], v[154:157], v[212:215], v[94:97]
	v_mfma_f32_16x16x32_bf16 v[86:89], v[146:149], v[220:223], v[86:89]
	v_mfma_f32_16x16x32_bf16 v[78:81], v[154:157], v[220:223], v[78:81]
	v_mfma_f32_16x16x32_bf16 v[126:129], v[150:153], v[190:193], v[126:129]
	v_mfma_f32_16x16x32_bf16 v[122:125], v[158:161], v[190:193], v[122:125]
	v_mfma_f32_16x16x32_bf16 v[118:121], v[150:153], v[198:201], v[118:121]
	v_mfma_f32_16x16x32_bf16 v[110:113], v[158:161], v[198:201], v[110:113]
	v_mfma_f32_16x16x32_bf16 v[102:105], v[150:153], v[216:219], v[102:105]
	v_mfma_f32_16x16x32_bf16 v[94:97], v[158:161], v[216:219], v[94:97]
	v_mfma_f32_16x16x32_bf16 v[86:89], v[150:153], v[224:227], v[86:89]
	v_mfma_f32_16x16x32_bf16 v[78:81], v[158:161], v[224:227], v[78:81]
	s_setprio 0
	s_setprio 1
	v_mfma_f32_16x16x32_bf16 v[114:117], v[162:165], v[186:189], v[114:117]
	v_mfma_f32_16x16x32_bf16 v[106:109], v[178:181], v[186:189], v[106:109]
	v_mfma_f32_16x16x32_bf16 v[98:101], v[162:165], v[194:197], v[98:101]
	v_mfma_f32_16x16x32_bf16 v[90:93], v[178:181], v[194:197], v[90:93]
	v_mfma_f32_16x16x32_bf16 v[82:85], v[162:165], v[212:215], v[82:85]
	v_mfma_f32_16x16x32_bf16 v[74:77], v[178:181], v[212:215], v[74:77]
	v_mfma_f32_16x16x32_bf16 v[70:73], v[162:165], v[220:223], v[70:73]
	v_mfma_f32_16x16x32_bf16 v[66:69], v[178:181], v[220:223], v[66:69]
	v_mfma_f32_16x16x32_bf16 v[114:117], v[166:169], v[190:193], v[114:117]
	v_mfma_f32_16x16x32_bf16 v[106:109], v[182:185], v[190:193], v[106:109]
	v_mfma_f32_16x16x32_bf16 v[98:101], v[166:169], v[198:201], v[98:101]
	v_mfma_f32_16x16x32_bf16 v[90:93], v[182:185], v[198:201], v[90:93]
	v_mfma_f32_16x16x32_bf16 v[82:85], v[166:169], v[216:219], v[82:85]
	v_mfma_f32_16x16x32_bf16 v[74:77], v[182:185], v[216:219], v[74:77]
	v_mfma_f32_16x16x32_bf16 v[70:73], v[166:169], v[224:227], v[70:73]
	v_mfma_f32_16x16x32_bf16 v[66:69], v[182:185], v[224:227], v[66:69]
	s_setprio 0
	s_barrier
	s_add_i32 s51, s51, s40
	v_lshl_add_u64 v[172:173], s[30:31], 0, v[0:1]
	s_mov_b32 m0, s51
	ds_read_b128 v[186:189], v144 offset:16384
	global_load_lds_dwordx4 v[172:173], off
	ds_read_b128 v[190:193], v144 offset:17408
	ds_read_b128 v[194:197], v144 offset:18432
	s_add_i32 m0, s51, 0x2000
	s_add_u32 s52, s30, 0x8000
	v_lshl_add_u64 v[174:175], s[30:31], 0, v[134:135]
	s_addc_u32 s53, s31, 0
	s_add_i32 s51, s54, s40
	global_load_lds_dwordx4 v[174:175], off
	ds_read_b128 v[198:201], v144 offset:19456
	ds_read_b128 v[212:215], v144 offset:20480
	v_lshl_add_u64 v[176:177], s[52:53], 0, v[0:1]
	s_mov_b32 m0, s51
	v_lshl_add_u64 v[228:229], s[34:35], 0, v[132:133]
	global_load_lds_dwordx4 v[176:177], off
	ds_read_b128 v[216:219], v144 offset:21504
	ds_read_b128 v[220:223], v144 offset:22528
	v_lshl_add_u64 v[176:177], s[52:53], 0, v[134:135]
	s_add_i32 m0, s51, 0x2000
	s_nop 0
	global_load_lds_dwordx4 v[176:177], off
	ds_read_b128 v[224:227], v144 offset:23552
	v_lshl_add_u64 v[176:177], s[34:35], 0, v[130:131]
	s_mov_b32 m0, s25
	s_nop 0
	global_load_lds_dwordx4 v[176:177], off
	s_mov_b32 m0, s27
	s_nop 0
	global_load_lds_dwordx4 v[228:229], off
	s_nop 0
	s_waitcnt vmcnt(8)
	s_waitcnt lgkmcnt(0)
	s_barrier
; #define PG8_STAGE(bufoff, gbase, voff) do { _Pragma("unroll") for (int _i = 0; _i < 2; ++_i) \
;         __builtin_amdgcn_global_load_lds((const unsigned*)((const char*)(gbase) + (voff)[_i]), (LAS unsigned*)(lds + (bufoff) + ldsw + _i * 8192), 16, 0, 0); } while (0)
; #define PG8_LDA(dst, b, h) do { _Pragma("unroll") for (int m = 0; m < 4; ++m) _Pragma("unroll") for (int k = 0; k < 2; ++k) dst[m][k] = *(const LAS bf16x8*)(lds + PG8_SA(b, h) + aoff + m * 2048 + k * 1024); } while (0)
; #define PG8_LDB(dst, b, h) do { _Pragma("unroll") for (int n = 0; n < 2; ++n) _Pragma("unroll") for (int k = 0; k < 2; ++k) dst[n][k] = *(const LAS bf16x8*)(lds + PG8_SB(b, h) + boff + n * 2048 + k * 1024); } while (0)
; #define PG8_MMA(ai, bj, At, Bt) do { __builtin_amdgcn_s_setprio(1); _Pragma("unroll") for (int m = 0; m < 4; ++m) _Pragma("unroll") for (int n = 0; n < 2; ++n) _Pragma("unroll") for (int k = 0; k < 2; ++k) \
;         acc[ai][bj][m][n] = __builtin_amdgcn_mfma_f32_16x16x32_bf16(Bt[n][k], At[m][k], acc[ai][bj][m][n], 0, 0, 0); __builtin_amdgcn_s_setprio(0); } while (0)
; #define PG8_WAIT_V(n) asm volatile("s_waitcnt vmcnt(" #n ")" ::: "memory")
; #define PG8_WAIT_L(n) asm volatile("s_waitcnt lgkmcnt(" #n ")" ::: "memory")
; #define PG8_BAR __builtin_amdgcn_s_barrier()
; #define PG8_SCHED __builtin_amdgcn_sched_barrier(0)
; template <class Epi>
; __device__ __forceinline__ void gemm_phase(LAS unsigned char* lds, const Gemm g, const StaticOrder& S, const Epi& E, const int tid) {
;     ...
;             PG8_WAIT_V(8); PG8_WAIT_L(0); PG8_BAR; PG8_MMA(1, 0, At, B0); PG8_MMA(1, 1, At, B1); PG8_BAR; PG8_SCHED;
;             PG8_LDB(B0, 1, 0); PG8_LDB(B1, 1, 1); PG8_SCHED; PG8_LDA(At, 1, 0); PG8_STAGE(PG8_SA(0, 1), a2 + hstep, voffA);
;             PG8_WAIT_V(8); PG8_WAIT_L(0); PG8_BAR; PG8_MMA(0, 0, At, B0); PG8_MMA(0, 1, At, B1); PG8_BAR; PG8_SCHED;
	s_setprio 1
	s_waitcnt lgkmcnt(0)
	v_mfma_f32_16x16x32_bf16 v[62:65], v[146:149], v[186:189], v[62:65]
	v_mfma_f32_16x16x32_bf16 v[58:61], v[154:157], v[186:189], v[58:61]
	v_mfma_f32_16x16x32_bf16 v[54:57], v[146:149], v[194:197], v[54:57]
	v_mfma_f32_16x16x32_bf16 v[46:49], v[154:157], v[194:197], v[46:49]
	v_mfma_f32_16x16x32_bf16 v[38:41], v[146:149], v[212:215], v[38:41]
	v_mfma_f32_16x16x32_bf16 v[30:33], v[154:157], v[212:215], v[30:33]
	v_mfma_f32_16x16x32_bf16 v[22:25], v[146:149], v[220:223], v[22:25]
	v_mfma_f32_16x16x32_bf16 v[14:17], v[154:157], v[220:223], v[14:17]
	v_mfma_f32_16x16x32_bf16 v[62:65], v[150:153], v[190:193], v[62:65]
	v_mfma_f32_16x16x32_bf16 v[58:61], v[158:161], v[190:193], v[58:61]
	v_mfma_f32_16x16x32_bf16 v[54:57], v[150:153], v[198:201], v[54:57]
	v_mfma_f32_16x16x32_bf16 v[46:49], v[158:161], v[198:201], v[46:49]
	v_mfma_f32_16x16x32_bf16 v[38:41], v[150:153], v[216:219], v[38:41]
	v_mfma_f32_16x16x32_bf16 v[30:33], v[158:161], v[216:219], v[30:33]
	v_mfma_f32_16x16x32_bf16 v[22:25], v[150:153], v[224:227], v[22:25]
	v_mfma_f32_16x16x32_bf16 v[14:17], v[158:161], v[224:227], v[14:17]
	s_setprio 0
	s_setprio 1
	v_mfma_f32_16x16x32_bf16 v[50:53], v[162:165], v[186:189], v[50:53]
	v_mfma_f32_16x16x32_bf16 v[42:45], v[178:181], v[186:189], v[42:45]
	v_mfma_f32_16x16x32_bf16 v[34:37], v[162:165], v[194:197], v[34:37]
	v_mfma_f32_16x16x32_bf16 v[26:29], v[178:181], v[194:197], v[26:29]
	v_mfma_f32_16x16x32_bf16 v[18:21], v[162:165], v[212:215], v[18:21]
	v_mfma_f32_16x16x32_bf16 v[10:13], v[178:181], v[212:215], v[10:13]
	v_mfma_f32_16x16x32_bf16 v[6:9], v[162:165], v[220:223], v[6:9]
	v_mfma_f32_16x16x32_bf16 v[2:5], v[178:181], v[220:223], v[2:5]
	v_mfma_f32_16x16x32_bf16 v[50:53], v[166:169], v[190:193], v[50:53]
	v_mfma_f32_16x16x32_bf16 v[42:45], v[182:185], v[190:193], v[42:45]
	v_mfma_f32_16x16x32_bf16 v[34:37], v[166:169], v[198:201], v[34:37]
	v_mfma_f32_16x16x32_bf16 v[26:29], v[182:185], v[198:201], v[26:29]
	v_mfma_f32_16x16x32_bf16 v[18:21], v[166:169], v[216:219], v[18:21]
	v_mfma_f32_16x16x32_bf16 v[10:13], v[182:185], v[216:219], v[10:13]
	v_mfma_f32_16x16x32_bf16 v[6:9], v[166:169], v[224:227], v[6:9]
	v_mfma_f32_16x16x32_bf16 v[2:5], v[182:185], v[224:227], v[2:5]
	s_setprio 0
	s_barrier
	s_add_i32 s51, 0, 0x18000
	v_add_u32_e32 v145, s51, v142
	s_add_i32 s52, 0, 0x1c000
	ds_read_b128 v[146:149], v145
	ds_read_b128 v[150:153], v145 offset:1024
	ds_read_b128 v[154:157], v145 offset:2048
	ds_read_b128 v[158:161], v145 offset:3072
	v_add_u32_e32 v145, s52, v142
	ds_read_b128 v[162:165], v145
	ds_read_b128 v[166:169], v145 offset:1024
	ds_read_b128 v[178:181], v145 offset:2048
	ds_read_b128 v[182:185], v145 offset:3072
	s_add_u32 s34, s34, 0x80000
	s_addc_u32 s35, s35, 0
	s_mov_b32 m0, s41
	v_lshl_add_u64 v[230:231], s[34:35], 0, v[130:131]
	ds_read_b128 v[186:189], v144 offset:32768
	global_load_lds_dwordx4 v[230:231], off
	ds_read_b128 v[190:193], v144 offset:33792
	ds_read_b128 v[194:197], v144 offset:34816
	v_lshl_add_u64 v[230:231], s[34:35], 0, v[132:133]
	s_mov_b32 m0, s42
	s_nop 0
	global_load_lds_dwordx4 v[230:231], off
	ds_read_b128 v[198:201], v144 offset:35840
	ds_read_b128 v[212:215], v144 offset:36864
	ds_read_b128 v[216:219], v144 offset:37888
	ds_read_b128 v[220:223], v144 offset:38912
	ds_read_b128 v[224:227], v144 offset:39936
	s_nop 0
	s_waitcnt vmcnt(8)
	s_waitcnt lgkmcnt(0)
	s_barrier
	s_setprio 1
	s_waitcnt lgkmcnt(0)
	v_mfma_f32_16x16x32_bf16 v[126:129], v[146:149], v[186:189], v[126:129]
	v_mfma_f32_16x16x32_bf16 v[122:125], v[154:157], v[186:189], v[122:125]
	v_mfma_f32_16x16x32_bf16 v[118:121], v[146:149], v[194:197], v[118:121]
	v_mfma_f32_16x16x32_bf16 v[110:113], v[154:157], v[194:197], v[110:113]
	v_mfma_f32_16x16x32_bf16 v[102:105], v[146:149], v[212:215], v[102:105]
	v_mfma_f32_16x16x32_bf16 v[94:97], v[154:157], v[212:215], v[94:97]
	v_mfma_f32_16x16x32_bf16 v[86:89], v[146:149], v[220:223], v[86:89]
	v_mfma_f32_16x16x32_bf16 v[78:81], v[154:157], v[220:223], v[78:81]
	v_mfma_f32_16x16x32_bf16 v[126:129], v[150:153], v[190:193], v[126:129]
	v_mfma_f32_16x16x32_bf16 v[122:125], v[158:161], v[190:193], v[122:125]
	v_mfma_f32_16x16x32_bf16 v[118:121], v[150:153], v[198:201], v[118:121]
	v_mfma_f32_16x16x32_bf16 v[110:113], v[158:161], v[198:201], v[110:113]
	v_mfma_f32_16x16x32_bf16 v[102:105], v[150:153], v[216:219], v[102:105]
	v_mfma_f32_16x16x32_bf16 v[94:97], v[158:161], v[216:219], v[94:97]
	v_mfma_f32_16x16x32_bf16 v[86:89], v[150:153], v[224:227], v[86:89]
	v_mfma_f32_16x16x32_bf16 v[78:81], v[158:161], v[224:227], v[78:81]
	s_setprio 0
	s_setprio 1
	v_mfma_f32_16x16x32_bf16 v[114:117], v[162:165], v[186:189], v[114:117]
	v_mfma_f32_16x16x32_bf16 v[106:109], v[178:181], v[186:189], v[106:109]
	v_mfma_f32_16x16x32_bf16 v[98:101], v[162:165], v[194:197], v[98:101]
	v_mfma_f32_16x16x32_bf16 v[90:93], v[178:181], v[194:197], v[90:93]
	v_mfma_f32_16x16x32_bf16 v[82:85], v[162:165], v[212:215], v[82:85]
	v_mfma_f32_16x16x32_bf16 v[74:77], v[178:181], v[212:215], v[74:77]
	v_mfma_f32_16x16x32_bf16 v[70:73], v[162:165], v[220:223], v[70:73]
	v_mfma_f32_16x16x32_bf16 v[66:69], v[178:181], v[220:223], v[66:69]
	v_mfma_f32_16x16x32_bf16 v[114:117], v[166:169], v[190:193], v[114:117]
	v_mfma_f32_16x16x32_bf16 v[106:109], v[182:185], v[190:193], v[106:109]
	v_mfma_f32_16x16x32_bf16 v[98:101], v[166:169], v[198:201], v[98:101]
	v_mfma_f32_16x16x32_bf16 v[90:93], v[182:185], v[198:201], v[90:93]
	v_mfma_f32_16x16x32_bf16 v[82:85], v[166:169], v[216:219], v[82:85]
	v_mfma_f32_16x16x32_bf16 v[74:77], v[182:185], v[216:219], v[74:77]
	v_mfma_f32_16x16x32_bf16 v[70:73], v[166:169], v[224:227], v[70:73]
	v_mfma_f32_16x16x32_bf16 v[66:69], v[182:185], v[224:227], v[66:69]
	s_setprio 0
	s_barrier
; #define PG8_STAGE(bufoff, gbase, voff) do { _Pragma("unroll") for (int _i = 0; _i < 2; ++_i) \
;         __builtin_amdgcn_global_load_lds((const unsigned*)((const char*)(gbase) + (voff)[_i]), (LAS unsigned*)(lds + (bufoff) + ldsw + _i * 8192), 16, 0, 0); } while (0)
; #define PG8_LDA(dst, b, h) do { _Pragma("unroll") for (int m = 0; m < 4; ++m) _Pragma("unroll") for (int k = 0; k < 2; ++k) dst[m][k] = *(const LAS bf16x8*)(lds + PG8_SA(b, h) + aoff + m * 2048 + k * 1024); } while (0)
; #define PG8_MMA(ai, bj, At, Bt) do { __builtin_amdgcn_s_setprio(1); _Pragma("unroll") for (int m = 0; m < 4; ++m) _Pragma("unroll") for (int n = 0; n < 2; ++n) _Pragma("unroll") for (int k = 0; k < 2; ++k) \
;         acc[ai][bj][m][n] = __builtin_amdgcn_mfma_f32_16x16x32_bf16(Bt[n][k], At[m][k], acc[ai][bj][m][n], 0, 0, 0); __builtin_amdgcn_s_setprio(0); } while (0)
; #define PG8_WAIT_V(n) asm volatile("s_waitcnt vmcnt(" #n ")" ::: "memory")
; #define PG8_WAIT_L(n) asm volatile("s_waitcnt lgkmcnt(" #n ")" ::: "memory")
; #define PG8_BAR __builtin_amdgcn_s_barrier()
; #define PG8_SCHED __builtin_amdgcn_sched_barrier(0)
; template <class Epi>
; __device__ __forceinline__ void gemm_phase(LAS unsigned char* lds, const Gemm g, const StaticOrder& S, const Epi& E, const int tid) {
;     ...
;             PG8_LDA(At, 1, 1); PG8_STAGE(PG8_SB(1, 0), b3, voffB); PG8_STAGE(PG8_SB(1, 1), b3 + bhs, voffB); PG8_STAGE(PG8_SA(1, 0), a3, voffA);
;             PG8_WAIT_V(8); PG8_WAIT_L(0); PG8_BAR; PG8_MMA(1, 0, At, B0); PG8_MMA(1, 1, At, B1); PG8_BAR; PG8_SCHED;
;     ...
;         if (ALIGN_EPI) { if (wr == 0) PG8_BAR; }
	s_add_i32 s34, s51, s40
	v_lshl_add_u64 v[172:173], v[172:173], 0, s[70:71]
	s_mov_b32 m0, s34
	ds_read_b128 v[186:189], v144 offset:49152
	global_load_lds_dwordx4 v[172:173], off
	ds_read_b128 v[190:193], v144 offset:50176
	ds_read_b128 v[194:197], v144 offset:51200
	s_add_i32 m0, s34, 0x2000
	s_add_u32 s30, s30, 0x8080
	v_lshl_add_u64 v[172:173], v[174:175], 0, s[70:71]
	s_addc_u32 s31, s31, 0
	s_add_i32 s34, s52, s40
	global_load_lds_dwordx4 v[172:173], off
	ds_read_b128 v[198:201], v144 offset:52224
	ds_read_b128 v[212:215], v144 offset:53248
	v_lshl_add_u64 v[172:173], s[30:31], 0, v[0:1]
	s_mov_b32 m0, s34
	s_nop 0
	global_load_lds_dwordx4 v[172:173], off
	ds_read_b128 v[216:219], v144 offset:54272
	ds_read_b128 v[220:223], v144 offset:55296
	v_lshl_add_u64 v[172:173], s[30:31], 0, v[134:135]
	s_add_i32 m0, s34, 0x2000
	s_nop 0
	global_load_lds_dwordx4 v[172:173], off
	ds_read_b128 v[224:227], v144 offset:56320
	v_lshl_add_u64 v[172:173], v[176:177], 0, s[70:71]
	s_mov_b32 m0, s43
	s_nop 0
	global_load_lds_dwordx4 v[172:173], off
	v_lshl_add_u64 v[172:173], v[228:229], 0, s[70:71]
	s_mov_b32 m0, s44
	s_nop 0
	global_load_lds_dwordx4 v[172:173], off
	s_waitcnt vmcnt(8)
	s_waitcnt lgkmcnt(0)
	s_barrier
	s_setprio 1
	s_waitcnt lgkmcnt(0)
	v_mfma_f32_16x16x32_bf16 v[62:65], v[146:149], v[186:189], v[62:65]
	v_mfma_f32_16x16x32_bf16 v[58:61], v[154:157], v[186:189], v[58:61]
	v_mfma_f32_16x16x32_bf16 v[54:57], v[146:149], v[194:197], v[54:57]
	v_mfma_f32_16x16x32_bf16 v[46:49], v[154:157], v[194:197], v[46:49]
	v_mfma_f32_16x16x32_bf16 v[38:41], v[146:149], v[212:215], v[38:41]
	v_mfma_f32_16x16x32_bf16 v[30:33], v[154:157], v[212:215], v[30:33]
	v_mfma_f32_16x16x32_bf16 v[22:25], v[146:149], v[220:223], v[22:25]
	v_mfma_f32_16x16x32_bf16 v[14:17], v[154:157], v[220:223], v[14:17]
	v_mfma_f32_16x16x32_bf16 v[62:65], v[150:153], v[190:193], v[62:65]
	v_mfma_f32_16x16x32_bf16 v[58:61], v[158:161], v[190:193], v[58:61]
	v_mfma_f32_16x16x32_bf16 v[54:57], v[150:153], v[198:201], v[54:57]
	v_mfma_f32_16x16x32_bf16 v[46:49], v[158:161], v[198:201], v[46:49]
	v_mfma_f32_16x16x32_bf16 v[38:41], v[150:153], v[216:219], v[38:41]
	v_mfma_f32_16x16x32_bf16 v[30:33], v[158:161], v[216:219], v[30:33]
	v_mfma_f32_16x16x32_bf16 v[22:25], v[150:153], v[224:227], v[22:25]
	v_mfma_f32_16x16x32_bf16 v[14:17], v[158:161], v[224:227], v[14:17]
	s_setprio 0
	s_setprio 1
	v_mfma_f32_16x16x32_bf16 v[50:53], v[162:165], v[186:189], v[50:53]
	v_mfma_f32_16x16x32_bf16 v[42:45], v[178:181], v[186:189], v[42:45]
	v_mfma_f32_16x16x32_bf16 v[34:37], v[162:165], v[194:197], v[34:37]
	v_mfma_f32_16x16x32_bf16 v[26:29], v[178:181], v[194:197], v[26:29]
	v_mfma_f32_16x16x32_bf16 v[18:21], v[162:165], v[212:215], v[18:21]
	v_mfma_f32_16x16x32_bf16 v[10:13], v[178:181], v[212:215], v[10:13]
	v_mfma_f32_16x16x32_bf16 v[6:9], v[162:165], v[220:223], v[6:9]
	v_mfma_f32_16x16x32_bf16 v[2:5], v[178:181], v[220:223], v[2:5]
	v_mfma_f32_16x16x32_bf16 v[50:53], v[166:169], v[190:193], v[50:53]
	v_mfma_f32_16x16x32_bf16 v[42:45], v[182:185], v[190:193], v[42:45]
	v_mfma_f32_16x16x32_bf16 v[34:37], v[166:169], v[198:201], v[34:37]
	v_mfma_f32_16x16x32_bf16 v[26:29], v[182:185], v[198:201], v[26:29]
	v_mfma_f32_16x16x32_bf16 v[18:21], v[166:169], v[216:219], v[18:21]
	v_mfma_f32_16x16x32_bf16 v[10:13], v[182:185], v[216:219], v[10:13]
	v_mfma_f32_16x16x32_bf16 v[6:9], v[166:169], v[224:227], v[6:9]
	v_mfma_f32_16x16x32_bf16 v[2:5], v[182:185], v[224:227], v[2:5]
	s_setprio 0
	s_barrier
	s_add_i32 s50, s50, 2
	s_add_u32 s48, s48, 0x100
	s_addc_u32 s49, s49, 0
	s_add_u32 s28, s28, 0x100
	s_addc_u32 s29, s29, 0
	s_cmp_gt_u32 s50, 29
	s_cbranch_scc0 .LBB0_861
	s_and_b64 vcc, exec, s[12:13]
	s_cbranch_vccz .LBB0_864
	s_barrier
